# v58 plus merge-GEMM epilogues: the sigmoid gate loads (one or two at a time, each fully waited) are issued ten ahead into spare registers and copied at the original wait points
# speedup vs baseline: 1.0053x; 1.0007x over previous
; __device__ __forceinline__ unsigned cvt_pk_bf16(float lo, float hi) { unsigned r; asm volatile("v_cvt_pk_bf16_f32 %0, %1, %2" : "=v"(r) : "v"(lo), "v"(hi)); return r; }
; __device__ __forceinline__ float fast_sigmoid(float x) { return __builtin_amdgcn_rcpf(1.f + __expf(-x)); }
;     __device__ __forceinline__ void operator()(f32x4 (&acc)[2][2][4][2], const Unit& u, int wr, int wc, int fr, int fq) const {
;     ...
;             for (int st = 0; st < 16; ++st) { const int ai = st >> 3, m = (st >> 1) & 3, bj = st & 1;
;                 const size_t r = (size_t)(row0 + ai * HALF + m * 16); const int c = col0 + bj * HALF;
;                 const u32x4 ga = *(const u32x4*)(za + r * ldz + c);
;                 float o[8];
; #pragma unroll
;                 for (int j = 0; j < 4; ++j) { const unsigned wa = ga[j];
;                     const float a0 = fminf(fmaxf(__uint_as_float(wa << 16), -30.f), 30.f), a1 = fminf(fmaxf(__uint_as_float(wa & 0xffff0000u), -30.f), 30.f);
;                     o[2 * j] = acc[ai][bj][m][j >> 1][(j & 1) * 2] * fast_sigmoid(a0); o[2 * j + 1] = acc[ai][bj][m][j >> 1][(j & 1) * 2 + 1] * fast_sigmoid(a1); }
;                 u32x4 w; w.x = cvt_pk_bf16(o[0], o[1]); w.y = cvt_pk_bf16(o[2], o[3]); w.z = cvt_pk_bf16(o[4], o[5]); w.w = cvt_pk_bf16(o[6], o[7]);
;                 *(u32x4*)(MG + r * ldm + c) = w;
;                 if ((st & 3) == 3) asm volatile("" ::: "memory"); }
.LBB0_2099:
	s_ashr_i32 s31, s30, 31
	s_lshl_b64 s[26:27], s[30:31], 12
	v_lshl_add_u32 v4, s36, 8, v1
	v_lshl_or_b32 v134, s21, 8, v176
	s_add_u32 s36, s59, s26
	s_addc_u32 s37, s60, s27
	v_ashrrev_i32_e32 v135, 31, v134
	s_cmp_lt_i32 s30, 2
	v_ashrrev_i32_e32 v5, 31, v4
	s_mov_b64 s[40:41], -1
	v_lshlrev_b64 v[154:155], 1, v[134:135]
	v_or_b32_e32 v174, 16, v4
	v_or_b32_e32 v158, 32, v4
	v_or_b32_e32 v156, 48, v4
	s_cbranch_scc1 .LBB0_2102
	v_mov_b64_e32 v[134:135], s[36:37]
	v_mad_i64_i32 v[246:247], s[26:27], v4, s25, v[134:135]
	v_lshl_add_u64 v[246:247], v[246:247], 0, v[154:155]
	global_load_dwordx4 v[214:217], v[246:247], off
	v_mad_i64_i32 v[248:249], s[26:27], v4, s25, v[134:135]
	v_lshl_add_u64 v[248:249], v[248:249], 0, v[154:155]
	global_load_dwordx4 v[218:221], v[248:249], off offset:256
	v_add_u32_e32 v213, 0x10, v4
	v_mad_i64_i32 v[246:247], s[26:27], v213, s25, v[134:135]
	v_lshl_add_u64 v[246:247], v[246:247], 0, v[154:155]
	global_load_dwordx4 v[222:225], v[246:247], off
	v_add_u32_e32 v213, 0x10, v4
	v_mad_i64_i32 v[248:249], s[26:27], v213, s25, v[134:135]
	v_lshl_add_u64 v[248:249], v[248:249], 0, v[154:155]
	global_load_dwordx4 v[226:229], v[248:249], off offset:256
	v_add_u32_e32 v213, 0x20, v4
	v_mad_i64_i32 v[246:247], s[26:27], v213, s25, v[134:135]
	v_lshl_add_u64 v[246:247], v[246:247], 0, v[154:155]
	global_load_dwordx4 v[230:233], v[246:247], off
	v_add_u32_e32 v213, 0x20, v4
	v_mad_i64_i32 v[248:249], s[26:27], v213, s25, v[134:135]
	v_lshl_add_u64 v[248:249], v[248:249], 0, v[154:155]
	global_load_dwordx4 v[234:237], v[248:249], off offset:256
	v_add_u32_e32 v213, 0x30, v4
	v_mad_i64_i32 v[246:247], s[26:27], v213, s25, v[134:135]
	v_lshl_add_u64 v[246:247], v[246:247], 0, v[154:155]
	global_load_dwordx4 v[238:241], v[246:247], off
	v_add_u32_e32 v213, 0x30, v4
	v_mad_i64_i32 v[248:249], s[26:27], v213, s25, v[134:135]
	v_lshl_add_u64 v[248:249], v[248:249], 0, v[154:155]
	global_load_dwordx4 v[242:245], v[248:249], off offset:256
	v_add_u32_e32 v213, 0x80, v4
	v_mad_i64_i32 v[246:247], s[26:27], v213, s25, v[134:135]
	v_lshl_add_u64 v[246:247], v[246:247], 0, v[154:155]
	global_load_dwordx4 v[204:207], v[246:247], off
	v_add_u32_e32 v213, 0x80, v4
	v_mad_i64_i32 v[248:249], s[26:27], v213, s25, v[134:135]
	v_lshl_add_u64 v[248:249], v[248:249], 0, v[154:155]
	global_load_dwordx4 v[208:211], v[248:249], off offset:256
	v_mad_i64_i32 v[136:137], s[26:27], v4, s25, v[134:135]
	v_lshl_add_u64 v[136:137], v[136:137], 0, v[154:155]
	v_ashrrev_i32_e32 v175, 31, v174
	s_waitcnt vmcnt(9)
	v_mov_b64_e32 v[138:139], v[214:215]
	v_mov_b64_e32 v[140:141], v[216:217]
	v_add_u32_e32 v213, 0x90, v4
	v_mad_i64_i32 v[246:247], s[26:27], v213, s25, v[134:135]
	v_lshl_add_u64 v[246:247], v[246:247], 0, v[154:155]
	global_load_dwordx4 v[214:217], v[246:247], off
	v_lshlrev_b32_e32 v2, 16, v138
	v_and_b32_e32 v138, 0xffff0000, v138
	v_lshlrev_b32_e32 v157, 16, v139
	v_and_b32_e32 v139, 0xffff0000, v139
	v_lshlrev_b32_e32 v159, 16, v140
	v_and_b32_e32 v140, 0xffff0000, v140
	v_lshlrev_b32_e32 v160, 16, v141
	v_and_b32_e32 v141, 0xffff0000, v141
	v_max_f32_e32 v138, v138, v138
	v_max_f32_e32 v139, v139, v139
	v_max_f32_e32 v140, v140, v140
	v_max_f32_e32 v160, v160, v160
	v_max_f32_e32 v141, v141, v141
	v_max_f32_e32 v2, v2, v2
	v_med3_f32 v138, v138, s20, v199
	v_max_f32_e32 v157, v157, v157
	v_med3_f32 v139, v139, s20, v199
	v_max_f32_e32 v159, v159, v159
	v_med3_f32 v140, v140, s20, v199
	v_med3_f32 v160, v160, s20, v199
	v_med3_f32 v141, v141, s20, v199
	v_med3_f32 v2, v2, s20, v199
	v_mul_f32_e32 v138, 0xbfb8aa3b, v138
	v_med3_f32 v157, v157, s20, v199
	v_mul_f32_e32 v139, 0xbfb8aa3b, v139
	v_med3_f32 v159, v159, s20, v199
	v_mul_f32_e32 v140, 0xbfb8aa3b, v140
	v_mul_f32_e32 v160, 0xbfb8aa3b, v160
	v_mul_f32_e32 v141, 0xbfb8aa3b, v141
	v_mul_f32_e32 v2, 0xbfb8aa3b, v2
	v_exp_f32_e32 v138, v138
	v_mul_f32_e32 v157, 0xbfb8aa3b, v157
	v_exp_f32_e32 v139, v139
	v_mul_f32_e32 v159, 0xbfb8aa3b, v159
	v_exp_f32_e32 v140, v140
	v_exp_f32_e32 v160, v160
	v_exp_f32_e32 v141, v141
	v_exp_f32_e32 v2, v2
	v_exp_f32_e32 v157, v157
	v_exp_f32_e32 v159, v159
	v_add_f32_e32 v138, 1.0, v138
	v_add_f32_e32 v139, 1.0, v139
	v_add_f32_e32 v140, 1.0, v140
	v_add_f32_e32 v160, 1.0, v160
	v_add_f32_e32 v141, 1.0, v141
	v_add_f32_e32 v2, 1.0, v2
	v_rcp_f32_e32 v138, v138
	v_add_f32_e32 v157, 1.0, v157
	v_rcp_f32_e32 v139, v139
	v_add_f32_e32 v159, 1.0, v159
	v_rcp_f32_e32 v140, v140
	v_rcp_f32_e32 v160, v160
	v_rcp_f32_e32 v141, v141
	v_rcp_f32_e32 v2, v2
	v_rcp_f32_e32 v157, v157
	v_rcp_f32_e32 v159, v159
	v_mul_f32_e32 v138, v131, v138
	v_mul_f32_e32 v139, v133, v139
	v_mul_f32_e32 v140, v127, v140
	v_mul_f32_e32 v160, v128, v160
	v_mul_f32_e32 v141, v129, v141
	v_mul_f32_e32 v2, v130, v2
	v_mul_f32_e32 v157, v132, v157
	v_mul_f32_e32 v159, v126, v159
	v_cvt_pk_bf16_f32 v138, v2, v138
	v_cvt_pk_bf16_f32 v139, v157, v139
	v_cvt_pk_bf16_f32 v140, v159, v140
	v_cvt_pk_bf16_f32 v141, v160, v141
	v_lshlrev_b64 v[160:161], 12, v[4:5]
	v_lshl_add_u64 v[160:161], s[6:7], 0, v[160:161]
	v_lshl_add_u64 v[160:161], v[160:161], 0, v[154:155]
	global_store_dwordx4 v[160:161], v[138:141], off
	s_waitcnt vmcnt(10)
; __device__ __forceinline__ unsigned cvt_pk_bf16(float lo, float hi) { unsigned r; asm volatile("v_cvt_pk_bf16_f32 %0, %1, %2" : "=v"(r) : "v"(lo), "v"(hi)); return r; }
; __device__ __forceinline__ float fast_sigmoid(float x) { return __builtin_amdgcn_rcpf(1.f + __expf(-x)); }
;     __device__ __forceinline__ void operator()(f32x4 (&acc)[2][2][4][2], const Unit& u, int wr, int wc, int fr, int fq) const {
;     ...
;             for (int st = 0; st < 16; ++st) { const int ai = st >> 3, m = (st >> 1) & 3, bj = st & 1;
;                 const size_t r = (size_t)(row0 + ai * HALF + m * 16); const int c = col0 + bj * HALF;
;                 const u32x4 ga = *(const u32x4*)(za + r * ldz + c);
;                 float o[8];
; #pragma unroll
;                 for (int j = 0; j < 4; ++j) { const unsigned wa = ga[j];
;                     const float a0 = fminf(fmaxf(__uint_as_float(wa << 16), -30.f), 30.f), a1 = fminf(fmaxf(__uint_as_float(wa & 0xffff0000u), -30.f), 30.f);
;                     o[2 * j] = acc[ai][bj][m][j >> 1][(j & 1) * 2] * fast_sigmoid(a0); o[2 * j + 1] = acc[ai][bj][m][j >> 1][(j & 1) * 2 + 1] * fast_sigmoid(a1); }
;                 u32x4 w; w.x = cvt_pk_bf16(o[0], o[1]); w.y = cvt_pk_bf16(o[2], o[3]); w.z = cvt_pk_bf16(o[4], o[5]); w.w = cvt_pk_bf16(o[6], o[7]);
;                 *(u32x4*)(MG + r * ldm + c) = w;
;                 if ((st & 3) == 3) asm volatile("" ::: "memory"); }
	v_mov_b64_e32 v[136:137], v[218:219]
	v_mov_b64_e32 v[138:139], v[220:221]
	v_add_u32_e32 v213, 0x90, v4
	v_mad_i64_i32 v[248:249], s[26:27], v213, s25, v[134:135]
	v_lshl_add_u64 v[248:249], v[248:249], 0, v[154:155]
	global_load_dwordx4 v[218:221], v[248:249], off offset:256
	v_lshlrev_b32_e32 v2, 16, v136
	v_and_b32_e32 v5, 0xffff0000, v136
	v_lshlrev_b32_e32 v136, 16, v137
	v_max_f32_e32 v136, v136, v136
	v_med3_f32 v136, v136, s20, v199
	v_mul_f32_e32 v136, 0xbfb8aa3b, v136
	v_exp_f32_e32 v136, v136
	v_and_b32_e32 v137, 0xffff0000, v137
	v_max_f32_e32 v137, v137, v137
	v_med3_f32 v137, v137, s20, v199
	v_add_f32_e32 v136, 1.0, v136
	v_rcp_f32_e32 v136, v136
	v_max_f32_e32 v2, v2, v2
	v_max_f32_e32 v5, v5, v5
	v_med3_f32 v2, v2, s20, v199
	v_mul_f32_e32 v140, v100, v136
	v_mul_f32_e32 v136, 0xbfb8aa3b, v137
	v_exp_f32_e32 v136, v136
	v_med3_f32 v5, v5, s20, v199
	v_mul_f32_e32 v2, 0xbfb8aa3b, v2
	v_mul_f32_e32 v5, 0xbfb8aa3b, v5
	v_add_f32_e32 v136, 1.0, v136
	v_rcp_f32_e32 v136, v136
	v_exp_f32_e32 v2, v2
	v_exp_f32_e32 v5, v5
	v_mul_f32_e32 v137, v101, v136
	v_lshlrev_b32_e32 v136, 16, v138
	v_max_f32_e32 v136, v136, v136
	v_med3_f32 v136, v136, s20, v199
	v_mul_f32_e32 v136, 0xbfb8aa3b, v136
	v_exp_f32_e32 v136, v136
	v_and_b32_e32 v138, 0xffff0000, v138
	v_max_f32_e32 v138, v138, v138
	v_med3_f32 v138, v138, s20, v199
	v_add_f32_e32 v136, 1.0, v136
	v_rcp_f32_e32 v136, v136
	v_add_f32_e32 v2, 1.0, v2
	v_add_f32_e32 v5, 1.0, v5
	v_rcp_f32_e32 v2, v2
	v_mul_f32_e32 v141, v94, v136
	v_mul_f32_e32 v136, 0xbfb8aa3b, v138
	v_exp_f32_e32 v136, v136
	v_rcp_f32_e32 v5, v5
	v_mul_f32_e32 v2, v98, v2
	v_add_f32_e32 v136, 1.0, v136
	v_rcp_f32_e32 v136, v136
	v_mul_f32_e32 v5, v99, v5
	v_mul_f32_e32 v138, v95, v136
	v_lshlrev_b32_e32 v136, 16, v139
	v_max_f32_e32 v136, v136, v136
	v_med3_f32 v136, v136, s20, v199
	v_mul_f32_e32 v136, 0xbfb8aa3b, v136
	v_exp_f32_e32 v136, v136
	v_and_b32_e32 v139, 0xffff0000, v139
	v_max_f32_e32 v139, v139, v139
	v_med3_f32 v139, v139, s20, v199
	v_add_f32_e32 v136, 1.0, v136
	v_rcp_f32_e32 v136, v136
	s_nop 0
	v_mul_f32_e32 v157, v96, v136
	v_mul_f32_e32 v136, 0xbfb8aa3b, v139
	v_exp_f32_e32 v136, v136
	s_nop 0
	v_add_f32_e32 v136, 1.0, v136
	v_rcp_f32_e32 v136, v136
	s_nop 0
	v_mul_f32_e32 v139, v97, v136
	v_cvt_pk_bf16_f32 v136, v2, v5
	v_cvt_pk_bf16_f32 v137, v140, v137
	v_cvt_pk_bf16_f32 v138, v141, v138
	v_cvt_pk_bf16_f32 v139, v157, v139
	global_store_dwordx4 v[160:161], v[136:139], off offset:256
	s_nop 1
	v_mad_i64_i32 v[136:137], s[26:27], v174, s25, v[134:135]
	v_lshl_add_u64 v[136:137], v[136:137], 0, v[154:155]
	s_waitcnt vmcnt(11)
	v_mov_b64_e32 v[138:139], v[222:223]
	v_mov_b64_e32 v[140:141], v[224:225]
	v_add_u32_e32 v213, 0xa0, v4
	v_mad_i64_i32 v[246:247], s[26:27], v213, s25, v[134:135]
	v_lshl_add_u64 v[246:247], v[246:247], 0, v[154:155]
	global_load_dwordx4 v[222:225], v[246:247], off
	v_lshlrev_b32_e32 v2, 16, v138
	v_and_b32_e32 v5, 0xffff0000, v138
	v_lshlrev_b32_e32 v138, 16, v139
	v_max_f32_e32 v138, v138, v138
	v_med3_f32 v138, v138, s20, v199
	v_mul_f32_e32 v138, 0xbfb8aa3b, v138
	v_exp_f32_e32 v138, v138
	v_and_b32_e32 v139, 0xffff0000, v139
	v_max_f32_e32 v139, v139, v139
	v_med3_f32 v139, v139, s20, v199
	v_add_f32_e32 v138, 1.0, v138
	v_rcp_f32_e32 v138, v138
	v_max_f32_e32 v2, v2, v2
	v_max_f32_e32 v5, v5, v5
	v_med3_f32 v2, v2, s20, v199
	v_mul_f32_e32 v157, v124, v138
	v_mul_f32_e32 v138, 0xbfb8aa3b, v139
	v_exp_f32_e32 v138, v138
	v_med3_f32 v5, v5, s20, v199
	v_mul_f32_e32 v2, 0xbfb8aa3b, v2
	v_mul_f32_e32 v5, 0xbfb8aa3b, v5
	v_add_f32_e32 v138, 1.0, v138
	v_rcp_f32_e32 v138, v138
	v_exp_f32_e32 v2, v2
	v_exp_f32_e32 v5, v5
	v_mul_f32_e32 v139, v125, v138
	v_lshlrev_b32_e32 v138, 16, v140
	v_max_f32_e32 v138, v138, v138
	v_med3_f32 v138, v138, s20, v199
	v_mul_f32_e32 v138, 0xbfb8aa3b, v138
	v_exp_f32_e32 v138, v138
	v_and_b32_e32 v140, 0xffff0000, v140
	v_max_f32_e32 v140, v140, v140
	v_med3_f32 v140, v140, s20, v199
	v_add_f32_e32 v138, 1.0, v138
	v_rcp_f32_e32 v138, v138
	v_add_f32_e32 v2, 1.0, v2
	v_add_f32_e32 v5, 1.0, v5
	v_rcp_f32_e32 v2, v2
	v_mul_f32_e32 v159, v118, v138
	v_mul_f32_e32 v138, 0xbfb8aa3b, v140
	v_exp_f32_e32 v138, v138
	v_rcp_f32_e32 v5, v5
	v_mul_f32_e32 v2, v122, v2
	v_add_f32_e32 v138, 1.0, v138
	v_rcp_f32_e32 v138, v138
	v_mul_f32_e32 v5, v123, v5
	v_mul_f32_e32 v140, v119, v138
	v_lshlrev_b32_e32 v138, 16, v141
	v_max_f32_e32 v138, v138, v138
	v_med3_f32 v138, v138, s20, v199
	v_mul_f32_e32 v138, 0xbfb8aa3b, v138
	v_exp_f32_e32 v138, v138
	v_and_b32_e32 v141, 0xffff0000, v141
	v_max_f32_e32 v141, v141, v141
	v_med3_f32 v141, v141, s20, v199
	v_add_f32_e32 v138, 1.0, v138
	v_rcp_f32_e32 v138, v138
	s_nop 0
	v_mul_f32_e32 v160, v120, v138
	v_mul_f32_e32 v138, 0xbfb8aa3b, v141
	v_exp_f32_e32 v138, v138
	s_nop 0
	v_add_f32_e32 v138, 1.0, v138
	v_rcp_f32_e32 v138, v138
	s_nop 0
	v_mul_f32_e32 v141, v121, v138
	v_cvt_pk_bf16_f32 v138, v2, v5
	v_cvt_pk_bf16_f32 v139, v157, v139
	v_cvt_pk_bf16_f32 v140, v159, v140
	v_cvt_pk_bf16_f32 v141, v160, v141
	v_lshlrev_b64 v[160:161], 12, v[174:175]
	v_lshl_add_u64 v[160:161], s[6:7], 0, v[160:161]
	v_lshl_add_u64 v[160:161], v[160:161], 0, v[154:155]
	global_store_dwordx4 v[160:161], v[138:141], off
	v_ashrrev_i32_e32 v159, 31, v158
	s_waitcnt vmcnt(12)
; __device__ __forceinline__ unsigned cvt_pk_bf16(float lo, float hi) { unsigned r; asm volatile("v_cvt_pk_bf16_f32 %0, %1, %2" : "=v"(r) : "v"(lo), "v"(hi)); return r; }
; __device__ __forceinline__ float fast_sigmoid(float x) { return __builtin_amdgcn_rcpf(1.f + __expf(-x)); }
;     __device__ __forceinline__ void operator()(f32x4 (&acc)[2][2][4][2], const Unit& u, int wr, int wc, int fr, int fq) const {
;     ...
;             for (int st = 0; st < 16; ++st) { const int ai = st >> 3, m = (st >> 1) & 3, bj = st & 1;
;                 const size_t r = (size_t)(row0 + ai * HALF + m * 16); const int c = col0 + bj * HALF;
;                 const u32x4 ga = *(const u32x4*)(za + r * ldz + c);
;                 float o[8];
; #pragma unroll
;                 for (int j = 0; j < 4; ++j) { const unsigned wa = ga[j];
;                     const float a0 = fminf(fmaxf(__uint_as_float(wa << 16), -30.f), 30.f), a1 = fminf(fmaxf(__uint_as_float(wa & 0xffff0000u), -30.f), 30.f);
;                     o[2 * j] = acc[ai][bj][m][j >> 1][(j & 1) * 2] * fast_sigmoid(a0); o[2 * j + 1] = acc[ai][bj][m][j >> 1][(j & 1) * 2 + 1] * fast_sigmoid(a1); }
;                 u32x4 w; w.x = cvt_pk_bf16(o[0], o[1]); w.y = cvt_pk_bf16(o[2], o[3]); w.z = cvt_pk_bf16(o[4], o[5]); w.w = cvt_pk_bf16(o[6], o[7]);
;                 *(u32x4*)(MG + r * ldm + c) = w;
;                 if ((st & 3) == 3) asm volatile("" ::: "memory"); }
	v_mov_b64_e32 v[136:137], v[226:227]
	v_mov_b64_e32 v[138:139], v[228:229]
	v_add_u32_e32 v213, 0xa0, v4
	v_mad_i64_i32 v[248:249], s[26:27], v213, s25, v[134:135]
	v_lshl_add_u64 v[248:249], v[248:249], 0, v[154:155]
	global_load_dwordx4 v[226:229], v[248:249], off offset:256
	v_lshlrev_b32_e32 v2, 16, v136
	v_and_b32_e32 v5, 0xffff0000, v136
	v_lshlrev_b32_e32 v136, 16, v137
	v_max_f32_e32 v136, v136, v136
	v_med3_f32 v136, v136, s20, v199
	v_mul_f32_e32 v136, 0xbfb8aa3b, v136
	v_exp_f32_e32 v136, v136
	v_and_b32_e32 v137, 0xffff0000, v137
	v_max_f32_e32 v137, v137, v137
	v_med3_f32 v137, v137, s20, v199
	v_add_f32_e32 v136, 1.0, v136
	v_rcp_f32_e32 v136, v136
	v_max_f32_e32 v2, v2, v2
	v_max_f32_e32 v5, v5, v5
	v_med3_f32 v2, v2, s20, v199
	v_mul_f32_e32 v140, v92, v136
	v_mul_f32_e32 v136, 0xbfb8aa3b, v137
	v_exp_f32_e32 v136, v136
	v_med3_f32 v5, v5, s20, v199
	v_mul_f32_e32 v2, 0xbfb8aa3b, v2
	v_mul_f32_e32 v5, 0xbfb8aa3b, v5
	v_add_f32_e32 v136, 1.0, v136
	v_rcp_f32_e32 v136, v136
	v_exp_f32_e32 v2, v2
	v_exp_f32_e32 v5, v5
	v_mul_f32_e32 v137, v93, v136
	v_lshlrev_b32_e32 v136, 16, v138
	v_max_f32_e32 v136, v136, v136
	v_med3_f32 v136, v136, s20, v199
	v_mul_f32_e32 v136, 0xbfb8aa3b, v136
	v_exp_f32_e32 v136, v136
	v_and_b32_e32 v138, 0xffff0000, v138
	v_max_f32_e32 v138, v138, v138
	v_med3_f32 v138, v138, s20, v199
	v_add_f32_e32 v136, 1.0, v136
	v_rcp_f32_e32 v136, v136
	v_add_f32_e32 v2, 1.0, v2
	v_add_f32_e32 v5, 1.0, v5
	v_rcp_f32_e32 v2, v2
	v_mul_f32_e32 v141, v86, v136
	v_mul_f32_e32 v136, 0xbfb8aa3b, v138
	v_exp_f32_e32 v136, v136
	v_rcp_f32_e32 v5, v5
	v_mul_f32_e32 v2, v90, v2
	v_add_f32_e32 v136, 1.0, v136
	v_rcp_f32_e32 v136, v136
	v_mul_f32_e32 v5, v91, v5
	v_mul_f32_e32 v138, v87, v136
	v_lshlrev_b32_e32 v136, 16, v139
	v_max_f32_e32 v136, v136, v136
	v_med3_f32 v136, v136, s20, v199
	v_mul_f32_e32 v136, 0xbfb8aa3b, v136
	v_exp_f32_e32 v136, v136
	v_and_b32_e32 v139, 0xffff0000, v139
	v_max_f32_e32 v139, v139, v139
	v_med3_f32 v139, v139, s20, v199
	v_add_f32_e32 v136, 1.0, v136
	v_rcp_f32_e32 v136, v136
	s_nop 0
	v_mul_f32_e32 v157, v88, v136
	v_mul_f32_e32 v136, 0xbfb8aa3b, v139
	v_exp_f32_e32 v136, v136
	s_nop 0
	v_add_f32_e32 v136, 1.0, v136
	v_rcp_f32_e32 v136, v136
	s_nop 0
	v_mul_f32_e32 v139, v89, v136
	v_cvt_pk_bf16_f32 v136, v2, v5
	v_cvt_pk_bf16_f32 v137, v140, v137
	v_cvt_pk_bf16_f32 v138, v141, v138
	v_cvt_pk_bf16_f32 v139, v157, v139
	global_store_dwordx4 v[160:161], v[136:139], off offset:256
	s_nop 1
	v_mad_i64_i32 v[136:137], s[26:27], v158, s25, v[134:135]
	v_lshl_add_u64 v[136:137], v[136:137], 0, v[154:155]
	s_waitcnt vmcnt(13)
	v_mov_b64_e32 v[138:139], v[230:231]
	v_mov_b64_e32 v[140:141], v[232:233]
	v_add_u32_e32 v213, 0xb0, v4
	v_mad_i64_i32 v[246:247], s[26:27], v213, s25, v[134:135]
	v_lshl_add_u64 v[246:247], v[246:247], 0, v[154:155]
	global_load_dwordx4 v[230:233], v[246:247], off
	v_lshlrev_b32_e32 v2, 16, v138
	v_and_b32_e32 v5, 0xffff0000, v138
	v_lshlrev_b32_e32 v138, 16, v139
	v_max_f32_e32 v138, v138, v138
	v_med3_f32 v138, v138, s20, v199
	v_mul_f32_e32 v138, 0xbfb8aa3b, v138
	v_exp_f32_e32 v138, v138
	v_and_b32_e32 v139, 0xffff0000, v139
	v_max_f32_e32 v139, v139, v139
	v_med3_f32 v139, v139, s20, v199
	v_add_f32_e32 v138, 1.0, v138
	v_rcp_f32_e32 v138, v138
	v_max_f32_e32 v2, v2, v2
	v_max_f32_e32 v5, v5, v5
	v_med3_f32 v2, v2, s20, v199
	v_mul_f32_e32 v157, v116, v138
	v_mul_f32_e32 v138, 0xbfb8aa3b, v139
	v_exp_f32_e32 v138, v138
	v_med3_f32 v5, v5, s20, v199
	v_mul_f32_e32 v2, 0xbfb8aa3b, v2
	v_mul_f32_e32 v5, 0xbfb8aa3b, v5
	v_add_f32_e32 v138, 1.0, v138
	v_rcp_f32_e32 v138, v138
	v_exp_f32_e32 v2, v2
	v_exp_f32_e32 v5, v5
	v_mul_f32_e32 v139, v117, v138
	v_lshlrev_b32_e32 v138, 16, v140
	v_max_f32_e32 v138, v138, v138
	v_med3_f32 v138, v138, s20, v199
	v_mul_f32_e32 v138, 0xbfb8aa3b, v138
	v_exp_f32_e32 v138, v138
	v_and_b32_e32 v140, 0xffff0000, v140
	v_max_f32_e32 v140, v140, v140
	v_med3_f32 v140, v140, s20, v199
	v_add_f32_e32 v138, 1.0, v138
	v_rcp_f32_e32 v138, v138
	v_add_f32_e32 v2, 1.0, v2
	v_add_f32_e32 v5, 1.0, v5
	v_rcp_f32_e32 v2, v2
	v_mul_f32_e32 v160, v110, v138
	v_mul_f32_e32 v138, 0xbfb8aa3b, v140
	v_exp_f32_e32 v138, v138
	v_rcp_f32_e32 v5, v5
	v_mul_f32_e32 v2, v114, v2
	v_add_f32_e32 v138, 1.0, v138
	v_rcp_f32_e32 v138, v138
	v_mul_f32_e32 v5, v115, v5
	v_mul_f32_e32 v140, v111, v138
	v_lshlrev_b32_e32 v138, 16, v141
	v_max_f32_e32 v138, v138, v138
	v_med3_f32 v138, v138, s20, v199
	v_mul_f32_e32 v138, 0xbfb8aa3b, v138
	v_exp_f32_e32 v138, v138
	v_and_b32_e32 v141, 0xffff0000, v141
	v_max_f32_e32 v141, v141, v141
	v_med3_f32 v141, v141, s20, v199
	v_add_f32_e32 v138, 1.0, v138
	v_rcp_f32_e32 v138, v138
	s_nop 0
	v_mul_f32_e32 v161, v112, v138
	v_mul_f32_e32 v138, 0xbfb8aa3b, v141
	v_exp_f32_e32 v138, v138
	s_nop 0
	v_add_f32_e32 v138, 1.0, v138
	v_rcp_f32_e32 v138, v138
	s_nop 0
	v_mul_f32_e32 v141, v113, v138
	v_cvt_pk_bf16_f32 v138, v2, v5
	v_cvt_pk_bf16_f32 v139, v157, v139
	v_cvt_pk_bf16_f32 v140, v160, v140
	v_cvt_pk_bf16_f32 v141, v161, v141
	v_lshlrev_b64 v[160:161], 12, v[158:159]
	v_lshl_add_u64 v[160:161], s[6:7], 0, v[160:161]
	v_lshl_add_u64 v[160:161], v[160:161], 0, v[154:155]
	global_store_dwordx4 v[160:161], v[138:141], off
	s_waitcnt vmcnt(14)
; __device__ __forceinline__ unsigned cvt_pk_bf16(float lo, float hi) { unsigned r; asm volatile("v_cvt_pk_bf16_f32 %0, %1, %2" : "=v"(r) : "v"(lo), "v"(hi)); return r; }
; __device__ __forceinline__ float fast_sigmoid(float x) { return __builtin_amdgcn_rcpf(1.f + __expf(-x)); }
;     __device__ __forceinline__ void operator()(f32x4 (&acc)[2][2][4][2], const Unit& u, int wr, int wc, int fr, int fq) const {
;     ...
;             for (int st = 0; st < 16; ++st) { const int ai = st >> 3, m = (st >> 1) & 3, bj = st & 1;
;                 const size_t r = (size_t)(row0 + ai * HALF + m * 16); const int c = col0 + bj * HALF;
;                 const u32x4 ga = *(const u32x4*)(za + r * ldz + c);
;                 float o[8];
; #pragma unroll
;                 for (int j = 0; j < 4; ++j) { const unsigned wa = ga[j];
;                     const float a0 = fminf(fmaxf(__uint_as_float(wa << 16), -30.f), 30.f), a1 = fminf(fmaxf(__uint_as_float(wa & 0xffff0000u), -30.f), 30.f);
;                     o[2 * j] = acc[ai][bj][m][j >> 1][(j & 1) * 2] * fast_sigmoid(a0); o[2 * j + 1] = acc[ai][bj][m][j >> 1][(j & 1) * 2 + 1] * fast_sigmoid(a1); }
;                 u32x4 w; w.x = cvt_pk_bf16(o[0], o[1]); w.y = cvt_pk_bf16(o[2], o[3]); w.z = cvt_pk_bf16(o[4], o[5]); w.w = cvt_pk_bf16(o[6], o[7]);
;                 *(u32x4*)(MG + r * ldm + c) = w;
;                 if ((st & 3) == 3) asm volatile("" ::: "memory"); }
	v_mov_b64_e32 v[136:137], v[234:235]
	v_mov_b64_e32 v[138:139], v[236:237]
	v_add_u32_e32 v213, 0xb0, v4
	v_mad_i64_i32 v[248:249], s[26:27], v213, s25, v[134:135]
	v_lshl_add_u64 v[248:249], v[248:249], 0, v[154:155]
	global_load_dwordx4 v[234:237], v[248:249], off offset:256
	v_lshlrev_b32_e32 v2, 16, v136
	v_and_b32_e32 v5, 0xffff0000, v136
	v_lshlrev_b32_e32 v136, 16, v137
	v_max_f32_e32 v136, v136, v136
	v_med3_f32 v136, v136, s20, v199
	v_mul_f32_e32 v136, 0xbfb8aa3b, v136
	v_exp_f32_e32 v136, v136
	v_and_b32_e32 v137, 0xffff0000, v137
	v_max_f32_e32 v137, v137, v137
	v_med3_f32 v137, v137, s20, v199
	v_add_f32_e32 v136, 1.0, v136
	v_rcp_f32_e32 v136, v136
	v_max_f32_e32 v2, v2, v2
	v_max_f32_e32 v5, v5, v5
	v_med3_f32 v2, v2, s20, v199
	v_mul_f32_e32 v140, v84, v136
	v_mul_f32_e32 v136, 0xbfb8aa3b, v137
	v_exp_f32_e32 v136, v136
	v_med3_f32 v5, v5, s20, v199
	v_mul_f32_e32 v2, 0xbfb8aa3b, v2
	v_mul_f32_e32 v5, 0xbfb8aa3b, v5
	v_add_f32_e32 v136, 1.0, v136
	v_rcp_f32_e32 v136, v136
	v_exp_f32_e32 v2, v2
	v_exp_f32_e32 v5, v5
	v_mul_f32_e32 v137, v85, v136
	v_lshlrev_b32_e32 v136, 16, v138
	v_max_f32_e32 v136, v136, v136
	v_med3_f32 v136, v136, s20, v199
	v_mul_f32_e32 v136, 0xbfb8aa3b, v136
	v_exp_f32_e32 v136, v136
	v_and_b32_e32 v138, 0xffff0000, v138
	v_max_f32_e32 v138, v138, v138
	v_med3_f32 v138, v138, s20, v199
	v_add_f32_e32 v136, 1.0, v136
	v_rcp_f32_e32 v136, v136
	v_add_f32_e32 v2, 1.0, v2
	v_add_f32_e32 v5, 1.0, v5
	v_rcp_f32_e32 v2, v2
	v_mul_f32_e32 v141, v78, v136
	v_mul_f32_e32 v136, 0xbfb8aa3b, v138
	v_exp_f32_e32 v136, v136
	v_rcp_f32_e32 v5, v5
	v_mul_f32_e32 v2, v82, v2
	v_add_f32_e32 v136, 1.0, v136
	v_rcp_f32_e32 v136, v136
	v_mul_f32_e32 v5, v83, v5
	v_mul_f32_e32 v138, v79, v136
	v_lshlrev_b32_e32 v136, 16, v139
	v_max_f32_e32 v136, v136, v136
	v_med3_f32 v136, v136, s20, v199
	v_mul_f32_e32 v136, 0xbfb8aa3b, v136
	v_exp_f32_e32 v136, v136
	v_and_b32_e32 v139, 0xffff0000, v139
	v_max_f32_e32 v139, v139, v139
	v_med3_f32 v139, v139, s20, v199
	v_add_f32_e32 v136, 1.0, v136
	v_rcp_f32_e32 v136, v136
	s_nop 0
	v_mul_f32_e32 v157, v80, v136
	v_mul_f32_e32 v136, 0xbfb8aa3b, v139
	v_exp_f32_e32 v136, v136
	s_nop 0
	v_add_f32_e32 v136, 1.0, v136
	v_rcp_f32_e32 v136, v136
	s_nop 0
	v_mul_f32_e32 v139, v81, v136
	v_cvt_pk_bf16_f32 v136, v2, v5
	v_cvt_pk_bf16_f32 v137, v140, v137
	v_cvt_pk_bf16_f32 v138, v141, v138
	v_cvt_pk_bf16_f32 v139, v157, v139
	global_store_dwordx4 v[160:161], v[136:139], off offset:256
	v_ashrrev_i32_e32 v157, 31, v156
	s_nop 0
	v_mad_i64_i32 v[136:137], s[26:27], v156, s25, v[134:135]
	v_lshl_add_u64 v[136:137], v[136:137], 0, v[154:155]
	s_waitcnt vmcnt(15)
	v_mov_b64_e32 v[138:139], v[238:239]
	v_mov_b64_e32 v[140:141], v[240:241]
	v_lshlrev_b32_e32 v2, 16, v138
	v_and_b32_e32 v5, 0xffff0000, v138
	v_lshlrev_b32_e32 v138, 16, v139
	v_max_f32_e32 v138, v138, v138
	v_med3_f32 v138, v138, s20, v199
	v_mul_f32_e32 v138, 0xbfb8aa3b, v138
	v_exp_f32_e32 v138, v138
	v_and_b32_e32 v139, 0xffff0000, v139
	v_max_f32_e32 v139, v139, v139
	v_med3_f32 v139, v139, s20, v199
	v_add_f32_e32 v138, 1.0, v138
	v_rcp_f32_e32 v138, v138
	v_max_f32_e32 v2, v2, v2
	v_max_f32_e32 v5, v5, v5
	v_med3_f32 v2, v2, s20, v199
	v_mul_f32_e32 v159, v108, v138
	v_mul_f32_e32 v138, 0xbfb8aa3b, v139
	v_exp_f32_e32 v138, v138
	v_med3_f32 v5, v5, s20, v199
	v_mul_f32_e32 v2, 0xbfb8aa3b, v2
	v_mul_f32_e32 v5, 0xbfb8aa3b, v5
	v_add_f32_e32 v138, 1.0, v138
	v_rcp_f32_e32 v138, v138
	v_exp_f32_e32 v2, v2
	v_exp_f32_e32 v5, v5
	v_mul_f32_e32 v139, v109, v138
	v_lshlrev_b32_e32 v138, 16, v140
	v_max_f32_e32 v138, v138, v138
	v_med3_f32 v138, v138, s20, v199
	v_mul_f32_e32 v138, 0xbfb8aa3b, v138
	v_exp_f32_e32 v138, v138
	v_and_b32_e32 v140, 0xffff0000, v140
	v_max_f32_e32 v140, v140, v140
	v_med3_f32 v140, v140, s20, v199
	v_add_f32_e32 v138, 1.0, v138
	v_rcp_f32_e32 v138, v138
	v_add_f32_e32 v2, 1.0, v2
	v_add_f32_e32 v5, 1.0, v5
	v_rcp_f32_e32 v2, v2
	v_mul_f32_e32 v160, v102, v138
	v_mul_f32_e32 v138, 0xbfb8aa3b, v140
	v_exp_f32_e32 v138, v138
	v_rcp_f32_e32 v5, v5
	v_mul_f32_e32 v2, v106, v2
	v_add_f32_e32 v138, 1.0, v138
	v_rcp_f32_e32 v138, v138
	v_mul_f32_e32 v5, v107, v5
	v_mul_f32_e32 v140, v103, v138
	v_lshlrev_b32_e32 v138, 16, v141
	v_max_f32_e32 v138, v138, v138
	v_med3_f32 v138, v138, s20, v199
	v_mul_f32_e32 v138, 0xbfb8aa3b, v138
	v_exp_f32_e32 v138, v138
	v_and_b32_e32 v141, 0xffff0000, v141
	v_max_f32_e32 v141, v141, v141
	v_med3_f32 v141, v141, s20, v199
	v_add_f32_e32 v138, 1.0, v138
	v_rcp_f32_e32 v138, v138
	s_nop 0
	v_mul_f32_e32 v161, v104, v138
	v_mul_f32_e32 v138, 0xbfb8aa3b, v141
	v_exp_f32_e32 v138, v138
	s_nop 0
	v_add_f32_e32 v138, 1.0, v138
	v_rcp_f32_e32 v138, v138
	s_nop 0
	v_mul_f32_e32 v141, v105, v138
	v_cvt_pk_bf16_f32 v138, v2, v5
	v_cvt_pk_bf16_f32 v139, v159, v139
	v_cvt_pk_bf16_f32 v140, v160, v140
	v_cvt_pk_bf16_f32 v141, v161, v141
	v_lshlrev_b64 v[160:161], 12, v[156:157]
	v_lshl_add_u64 v[160:161], s[6:7], 0, v[160:161]
	v_lshl_add_u64 v[160:161], v[160:161], 0, v[154:155]
	global_store_dwordx4 v[160:161], v[138:141], off
	s_waitcnt vmcnt(15)
; __device__ __forceinline__ unsigned cvt_pk_bf16(float lo, float hi) { unsigned r; asm volatile("v_cvt_pk_bf16_f32 %0, %1, %2" : "=v"(r) : "v"(lo), "v"(hi)); return r; }
; __device__ __forceinline__ float fast_sigmoid(float x) { return __builtin_amdgcn_rcpf(1.f + __expf(-x)); }
;     __device__ __forceinline__ void operator()(f32x4 (&acc)[2][2][4][2], const Unit& u, int wr, int wc, int fr, int fq) const {
;     ...
;             for (int st = 0; st < 16; ++st) { const int ai = st >> 3, m = (st >> 1) & 3, bj = st & 1;
;                 const size_t r = (size_t)(row0 + ai * HALF + m * 16); const int c = col0 + bj * HALF;
;                 const u32x4 ga = *(const u32x4*)(za + r * ldz + c);
;                 float o[8];
; #pragma unroll
;                 for (int j = 0; j < 4; ++j) { const unsigned wa = ga[j];
;                     const float a0 = fminf(fmaxf(__uint_as_float(wa << 16), -30.f), 30.f), a1 = fminf(fmaxf(__uint_as_float(wa & 0xffff0000u), -30.f), 30.f);
;                     o[2 * j] = acc[ai][bj][m][j >> 1][(j & 1) * 2] * fast_sigmoid(a0); o[2 * j + 1] = acc[ai][bj][m][j >> 1][(j & 1) * 2 + 1] * fast_sigmoid(a1); }
;                 u32x4 w; w.x = cvt_pk_bf16(o[0], o[1]); w.y = cvt_pk_bf16(o[2], o[3]); w.z = cvt_pk_bf16(o[4], o[5]); w.w = cvt_pk_bf16(o[6], o[7]);
;                 *(u32x4*)(MG + r * ldm + c) = w;
;                 if ((st & 3) == 3) asm volatile("" ::: "memory"); }
	v_mov_b64_e32 v[136:137], v[242:243]
	v_mov_b64_e32 v[138:139], v[244:245]
	v_lshlrev_b32_e32 v2, 16, v136
	v_and_b32_e32 v5, 0xffff0000, v136
	v_lshlrev_b32_e32 v136, 16, v137
	v_max_f32_e32 v136, v136, v136
	v_med3_f32 v136, v136, s20, v199
	v_mul_f32_e32 v136, 0xbfb8aa3b, v136
	v_exp_f32_e32 v136, v136
	v_and_b32_e32 v137, 0xffff0000, v137
	v_max_f32_e32 v137, v137, v137
	v_med3_f32 v137, v137, s20, v199
	v_add_f32_e32 v136, 1.0, v136
	v_rcp_f32_e32 v136, v136
	v_max_f32_e32 v2, v2, v2
	v_max_f32_e32 v5, v5, v5
	v_med3_f32 v2, v2, s20, v199
	v_mul_f32_e32 v140, v76, v136
	v_mul_f32_e32 v136, 0xbfb8aa3b, v137
	v_exp_f32_e32 v136, v136
	v_med3_f32 v5, v5, s20, v199
	v_mul_f32_e32 v2, 0xbfb8aa3b, v2
	v_mul_f32_e32 v5, 0xbfb8aa3b, v5
	v_add_f32_e32 v136, 1.0, v136
	v_rcp_f32_e32 v136, v136
	v_exp_f32_e32 v2, v2
	v_exp_f32_e32 v5, v5
	v_mul_f32_e32 v137, v77, v136
	v_lshlrev_b32_e32 v136, 16, v138
	v_max_f32_e32 v136, v136, v136
	v_med3_f32 v136, v136, s20, v199
	v_mul_f32_e32 v136, 0xbfb8aa3b, v136
	v_exp_f32_e32 v136, v136
	v_and_b32_e32 v138, 0xffff0000, v138
	v_max_f32_e32 v138, v138, v138
	v_med3_f32 v138, v138, s20, v199
	v_add_f32_e32 v136, 1.0, v136
	v_rcp_f32_e32 v136, v136
	v_add_f32_e32 v2, 1.0, v2
	v_add_f32_e32 v5, 1.0, v5
	v_rcp_f32_e32 v2, v2
	v_mul_f32_e32 v141, v70, v136
	v_mul_f32_e32 v136, 0xbfb8aa3b, v138
	v_exp_f32_e32 v136, v136
	v_rcp_f32_e32 v5, v5
	v_mul_f32_e32 v2, v74, v2
	v_add_f32_e32 v136, 1.0, v136
	v_rcp_f32_e32 v136, v136
	v_mul_f32_e32 v5, v75, v5
	v_mul_f32_e32 v138, v71, v136
	v_lshlrev_b32_e32 v136, 16, v139
	v_max_f32_e32 v136, v136, v136
	v_med3_f32 v136, v136, s20, v199
	v_mul_f32_e32 v136, 0xbfb8aa3b, v136
	v_exp_f32_e32 v136, v136
	v_and_b32_e32 v139, 0xffff0000, v139
	v_max_f32_e32 v139, v139, v139
	v_med3_f32 v139, v139, s20, v199
	v_add_f32_e32 v136, 1.0, v136
	v_rcp_f32_e32 v136, v136
	s_nop 0
	v_mul_f32_e32 v157, v72, v136
	v_mul_f32_e32 v136, 0xbfb8aa3b, v139
	v_exp_f32_e32 v136, v136
	s_nop 0
	v_add_f32_e32 v136, 1.0, v136
	v_rcp_f32_e32 v136, v136
	s_nop 0
	v_mul_f32_e32 v139, v73, v136
	v_cvt_pk_bf16_f32 v136, v2, v5
	v_cvt_pk_bf16_f32 v137, v140, v137
	v_cvt_pk_bf16_f32 v138, v141, v138
	v_cvt_pk_bf16_f32 v139, v157, v139
	global_store_dwordx4 v[160:161], v[136:139], off offset:256
	s_nop 1
	v_add_u32_e32 v138, 0x80, v4
	v_mad_i64_i32 v[136:137], s[26:27], v138, s25, v[134:135]
	v_lshl_add_u64 v[136:137], v[136:137], 0, v[154:155]
	v_ashrrev_i32_e32 v139, 31, v138
	v_lshlrev_b64 v[138:139], 12, v[138:139]
	v_lshl_add_u64 v[138:139], s[6:7], 0, v[138:139]
	s_waitcnt vmcnt(15)
	v_mov_b64_e32 v[160:161], v[204:205]
	v_mov_b64_e32 v[162:163], v[206:207]
	v_lshlrev_b32_e32 v2, 16, v160
	v_and_b32_e32 v5, 0xffff0000, v160
	v_lshlrev_b32_e32 v160, 16, v163
	v_max_f32_e32 v160, v160, v160
	v_med3_f32 v160, v160, s20, v199
	v_mul_f32_e32 v160, 0xbfb8aa3b, v160
	v_exp_f32_e32 v160, v160
	v_lshlrev_b32_e32 v140, 16, v161
	v_and_b32_e32 v141, 0xffff0000, v161
	v_max_f32_e32 v140, v140, v140
	v_add_f32_e32 v160, 1.0, v160
	v_rcp_f32_e32 v160, v160
	v_max_f32_e32 v141, v141, v141
	v_lshlrev_b32_e32 v157, 16, v162
	v_and_b32_e32 v159, 0xffff0000, v162
	v_and_b32_e32 v161, 0xffff0000, v163
	v_max_f32_e32 v2, v2, v2
	v_max_f32_e32 v5, v5, v5
	v_med3_f32 v140, v140, s20, v199
	v_med3_f32 v141, v141, s20, v199
	v_max_f32_e32 v157, v157, v157
	v_max_f32_e32 v159, v159, v159
	v_max_f32_e32 v161, v161, v161
	v_med3_f32 v2, v2, s20, v199
	v_med3_f32 v5, v5, s20, v199
	v_mul_f32_e32 v140, 0xbfb8aa3b, v140
	v_mul_f32_e32 v141, 0xbfb8aa3b, v141
	v_med3_f32 v157, v157, s20, v199
	v_med3_f32 v159, v159, s20, v199
	v_med3_f32 v161, v161, s20, v199
	v_mul_f32_e32 v2, 0xbfb8aa3b, v2
	v_mul_f32_e32 v5, 0xbfb8aa3b, v5
	v_exp_f32_e32 v140, v140
	v_exp_f32_e32 v141, v141
	v_mul_f32_e32 v157, 0xbfb8aa3b, v157
	v_mul_f32_e32 v159, 0xbfb8aa3b, v159
	v_mul_f32_e32 v163, v64, v160
	v_mul_f32_e32 v160, 0xbfb8aa3b, v161
	v_exp_f32_e32 v2, v2
	v_exp_f32_e32 v5, v5
	v_exp_f32_e32 v157, v157
	v_exp_f32_e32 v159, v159
	v_exp_f32_e32 v160, v160
	v_add_f32_e32 v140, 1.0, v140
	v_add_f32_e32 v141, 1.0, v141
	v_add_f32_e32 v2, 1.0, v2
	v_add_f32_e32 v5, 1.0, v5
	v_rcp_f32_e32 v140, v140
	v_rcp_f32_e32 v141, v141
	v_add_f32_e32 v157, 1.0, v157
	v_add_f32_e32 v159, 1.0, v159
	v_add_f32_e32 v160, 1.0, v160
	v_rcp_f32_e32 v2, v2
	v_rcp_f32_e32 v5, v5
	v_rcp_f32_e32 v157, v157
	v_rcp_f32_e32 v159, v159
	v_rcp_f32_e32 v160, v160
	v_mul_f32_e32 v140, v68, v140
	v_mul_f32_e32 v141, v69, v141
	v_mul_f32_e32 v2, v66, v2
	v_mul_f32_e32 v5, v67, v5
	v_mul_f32_e32 v157, v62, v157
	v_mul_f32_e32 v159, v63, v159
	v_mul_f32_e32 v164, v65, v160
	v_cvt_pk_bf16_f32 v160, v2, v5
	v_cvt_pk_bf16_f32 v161, v140, v141
	v_cvt_pk_bf16_f32 v162, v157, v159
	v_cvt_pk_bf16_f32 v163, v163, v164
	v_lshl_add_u64 v[140:141], v[138:139], 0, v[154:155]
	s_waitcnt vmcnt(14)
; __device__ __forceinline__ unsigned cvt_pk_bf16(float lo, float hi) { unsigned r; asm volatile("v_cvt_pk_bf16_f32 %0, %1, %2" : "=v"(r) : "v"(lo), "v"(hi)); return r; }
; __device__ __forceinline__ float fast_sigmoid(float x) { return __builtin_amdgcn_rcpf(1.f + __expf(-x)); }
;     __device__ __forceinline__ void operator()(f32x4 (&acc)[2][2][4][2], const Unit& u, int wr, int wc, int fr, int fq) const {
;     ...
;             for (int st = 0; st < 16; ++st) { const int ai = st >> 3, m = (st >> 1) & 3, bj = st & 1;
;                 const size_t r = (size_t)(row0 + ai * HALF + m * 16); const int c = col0 + bj * HALF;
;                 const u32x4 ga = *(const u32x4*)(za + r * ldz + c);
;                 float o[8];
; #pragma unroll
;                 for (int j = 0; j < 4; ++j) { const unsigned wa = ga[j];
;                     const float a0 = fminf(fmaxf(__uint_as_float(wa << 16), -30.f), 30.f), a1 = fminf(fmaxf(__uint_as_float(wa & 0xffff0000u), -30.f), 30.f);
;                     o[2 * j] = acc[ai][bj][m][j >> 1][(j & 1) * 2] * fast_sigmoid(a0); o[2 * j + 1] = acc[ai][bj][m][j >> 1][(j & 1) * 2 + 1] * fast_sigmoid(a1); }
;                 u32x4 w; w.x = cvt_pk_bf16(o[0], o[1]); w.y = cvt_pk_bf16(o[2], o[3]); w.z = cvt_pk_bf16(o[4], o[5]); w.w = cvt_pk_bf16(o[6], o[7]);
;                 *(u32x4*)(MG + r * ldm + c) = w;
;                 if ((st & 3) == 3) asm volatile("" ::: "memory"); }
	v_mov_b64_e32 v[136:137], v[208:209]
	v_mov_b64_e32 v[138:139], v[210:211]
	v_lshlrev_b32_e32 v2, 16, v136
	v_and_b32_e32 v5, 0xffff0000, v136
	v_lshlrev_b32_e32 v136, 16, v137
	v_max_f32_e32 v136, v136, v136
	v_med3_f32 v136, v136, s20, v199
	v_mul_f32_e32 v136, 0xbfb8aa3b, v136
	v_exp_f32_e32 v136, v136
	v_and_b32_e32 v137, 0xffff0000, v137
	v_max_f32_e32 v137, v137, v137
	v_med3_f32 v137, v137, s20, v199
	v_add_f32_e32 v136, 1.0, v136
	v_rcp_f32_e32 v136, v136
	v_max_f32_e32 v2, v2, v2
	v_max_f32_e32 v5, v5, v5
	v_med3_f32 v2, v2, s20, v199
	v_mul_f32_e32 v157, v36, v136
	v_mul_f32_e32 v136, 0xbfb8aa3b, v137
	v_exp_f32_e32 v136, v136
	v_med3_f32 v5, v5, s20, v199
	global_store_dwordx4 v[140:141], v[160:163], off
	v_mul_f32_e32 v2, 0xbfb8aa3b, v2
	v_add_f32_e32 v136, 1.0, v136
	v_rcp_f32_e32 v136, v136
	v_mul_f32_e32 v5, 0xbfb8aa3b, v5
	v_exp_f32_e32 v2, v2
	v_exp_f32_e32 v5, v5
	v_mul_f32_e32 v137, v37, v136
	v_lshlrev_b32_e32 v136, 16, v138
	v_max_f32_e32 v136, v136, v136
	v_med3_f32 v136, v136, s20, v199
	v_mul_f32_e32 v136, 0xbfb8aa3b, v136
	v_exp_f32_e32 v136, v136
	v_and_b32_e32 v138, 0xffff0000, v138
	v_max_f32_e32 v138, v138, v138
	v_med3_f32 v138, v138, s20, v199
	v_add_f32_e32 v136, 1.0, v136
	v_rcp_f32_e32 v136, v136
	v_add_f32_e32 v2, 1.0, v2
	v_add_f32_e32 v5, 1.0, v5
	v_rcp_f32_e32 v2, v2
	v_mul_f32_e32 v159, v30, v136
	v_mul_f32_e32 v136, 0xbfb8aa3b, v138
	v_exp_f32_e32 v136, v136
	v_rcp_f32_e32 v5, v5
	v_mul_f32_e32 v2, v34, v2
	v_add_f32_e32 v136, 1.0, v136
	v_rcp_f32_e32 v136, v136
	v_mul_f32_e32 v5, v35, v5
	v_mul_f32_e32 v138, v31, v136
	v_lshlrev_b32_e32 v136, 16, v139
	v_max_f32_e32 v136, v136, v136
	v_med3_f32 v136, v136, s20, v199
	v_mul_f32_e32 v136, 0xbfb8aa3b, v136
	v_exp_f32_e32 v136, v136
	v_and_b32_e32 v139, 0xffff0000, v139
	v_max_f32_e32 v139, v139, v139
	v_med3_f32 v139, v139, s20, v199
	v_add_f32_e32 v136, 1.0, v136
	v_rcp_f32_e32 v136, v136
	s_nop 0
	v_mul_f32_e32 v160, v32, v136
	v_mul_f32_e32 v136, 0xbfb8aa3b, v139
	v_exp_f32_e32 v136, v136
	s_nop 0
	v_add_f32_e32 v136, 1.0, v136
	v_rcp_f32_e32 v136, v136
	s_nop 0
	v_mul_f32_e32 v139, v33, v136
	v_cvt_pk_bf16_f32 v136, v2, v5
	v_cvt_pk_bf16_f32 v137, v157, v137
	v_cvt_pk_bf16_f32 v138, v159, v138
	v_cvt_pk_bf16_f32 v139, v160, v139
	global_store_dwordx4 v[140:141], v[136:139], off offset:256
	s_nop 1
	v_add_u32_e32 v138, 0x90, v4
	v_mad_i64_i32 v[136:137], s[26:27], v138, s25, v[134:135]
	v_lshl_add_u64 v[136:137], v[136:137], 0, v[154:155]
	v_ashrrev_i32_e32 v139, 31, v138
	v_lshlrev_b64 v[138:139], 12, v[138:139]
	v_lshl_add_u64 v[138:139], s[6:7], 0, v[138:139]
	s_waitcnt vmcnt(15)
	v_mov_b64_e32 v[160:161], v[214:215]
	v_mov_b64_e32 v[162:163], v[216:217]
	v_lshlrev_b32_e32 v2, 16, v160
	v_and_b32_e32 v5, 0xffff0000, v160
	v_lshlrev_b32_e32 v160, 16, v163
	v_max_f32_e32 v160, v160, v160
	v_med3_f32 v160, v160, s20, v199
	v_mul_f32_e32 v160, 0xbfb8aa3b, v160
	v_exp_f32_e32 v160, v160
	v_lshlrev_b32_e32 v140, 16, v161
	v_and_b32_e32 v141, 0xffff0000, v161
	v_max_f32_e32 v140, v140, v140
	v_add_f32_e32 v160, 1.0, v160
	v_rcp_f32_e32 v160, v160
	v_max_f32_e32 v141, v141, v141
	v_lshlrev_b32_e32 v157, 16, v162
	v_and_b32_e32 v159, 0xffff0000, v162
	v_and_b32_e32 v161, 0xffff0000, v163
	v_max_f32_e32 v2, v2, v2
	v_max_f32_e32 v5, v5, v5
	v_med3_f32 v140, v140, s20, v199
	v_med3_f32 v141, v141, s20, v199
	v_max_f32_e32 v157, v157, v157
	v_max_f32_e32 v159, v159, v159
	v_max_f32_e32 v161, v161, v161
	v_med3_f32 v2, v2, s20, v199
	v_med3_f32 v5, v5, s20, v199
	v_mul_f32_e32 v140, 0xbfb8aa3b, v140
	v_mul_f32_e32 v141, 0xbfb8aa3b, v141
	v_med3_f32 v157, v157, s20, v199
	v_med3_f32 v159, v159, s20, v199
	v_med3_f32 v161, v161, s20, v199
	v_mul_f32_e32 v2, 0xbfb8aa3b, v2
	v_mul_f32_e32 v5, 0xbfb8aa3b, v5
	v_exp_f32_e32 v140, v140
	v_exp_f32_e32 v141, v141
	v_mul_f32_e32 v157, 0xbfb8aa3b, v157
	v_mul_f32_e32 v159, 0xbfb8aa3b, v159
	v_mul_f32_e32 v163, v56, v160
	v_mul_f32_e32 v160, 0xbfb8aa3b, v161
	v_exp_f32_e32 v2, v2
	v_exp_f32_e32 v5, v5
	v_exp_f32_e32 v157, v157
	v_exp_f32_e32 v159, v159
	v_exp_f32_e32 v160, v160
	v_add_f32_e32 v140, 1.0, v140
	v_add_f32_e32 v141, 1.0, v141
	v_add_f32_e32 v2, 1.0, v2
	v_add_f32_e32 v5, 1.0, v5
	v_rcp_f32_e32 v140, v140
	v_rcp_f32_e32 v141, v141
	v_add_f32_e32 v157, 1.0, v157
	v_add_f32_e32 v159, 1.0, v159
	v_add_f32_e32 v160, 1.0, v160
	v_rcp_f32_e32 v2, v2
	v_rcp_f32_e32 v5, v5
	v_rcp_f32_e32 v157, v157
	v_rcp_f32_e32 v159, v159
	v_rcp_f32_e32 v160, v160
	v_mul_f32_e32 v140, v60, v140
	v_mul_f32_e32 v141, v61, v141
	v_mul_f32_e32 v2, v58, v2
	v_mul_f32_e32 v5, v59, v5
	v_mul_f32_e32 v157, v54, v157
	v_mul_f32_e32 v159, v55, v159
	v_mul_f32_e32 v164, v57, v160
	v_cvt_pk_bf16_f32 v160, v2, v5
	v_cvt_pk_bf16_f32 v161, v140, v141
	v_cvt_pk_bf16_f32 v162, v157, v159
	v_cvt_pk_bf16_f32 v163, v163, v164
	v_lshl_add_u64 v[140:141], v[138:139], 0, v[154:155]
	s_waitcnt vmcnt(13)
; __device__ __forceinline__ unsigned cvt_pk_bf16(float lo, float hi) { unsigned r; asm volatile("v_cvt_pk_bf16_f32 %0, %1, %2" : "=v"(r) : "v"(lo), "v"(hi)); return r; }
; __device__ __forceinline__ float fast_sigmoid(float x) { return __builtin_amdgcn_rcpf(1.f + __expf(-x)); }
;     __device__ __forceinline__ void operator()(f32x4 (&acc)[2][2][4][2], const Unit& u, int wr, int wc, int fr, int fq) const {
;     ...
;             for (int st = 0; st < 16; ++st) { const int ai = st >> 3, m = (st >> 1) & 3, bj = st & 1;
;                 const size_t r = (size_t)(row0 + ai * HALF + m * 16); const int c = col0 + bj * HALF;
;                 const u32x4 ga = *(const u32x4*)(za + r * ldz + c);
;                 float o[8];
; #pragma unroll
;                 for (int j = 0; j < 4; ++j) { const unsigned wa = ga[j];
;                     const float a0 = fminf(fmaxf(__uint_as_float(wa << 16), -30.f), 30.f), a1 = fminf(fmaxf(__uint_as_float(wa & 0xffff0000u), -30.f), 30.f);
;                     o[2 * j] = acc[ai][bj][m][j >> 1][(j & 1) * 2] * fast_sigmoid(a0); o[2 * j + 1] = acc[ai][bj][m][j >> 1][(j & 1) * 2 + 1] * fast_sigmoid(a1); }
;                 u32x4 w; w.x = cvt_pk_bf16(o[0], o[1]); w.y = cvt_pk_bf16(o[2], o[3]); w.z = cvt_pk_bf16(o[4], o[5]); w.w = cvt_pk_bf16(o[6], o[7]);
;                 *(u32x4*)(MG + r * ldm + c) = w;
;                 if ((st & 3) == 3) asm volatile("" ::: "memory"); }
	v_mov_b64_e32 v[136:137], v[218:219]
	v_mov_b64_e32 v[138:139], v[220:221]
	v_lshlrev_b32_e32 v2, 16, v136
	v_and_b32_e32 v5, 0xffff0000, v136
	v_lshlrev_b32_e32 v136, 16, v137
	v_max_f32_e32 v136, v136, v136
	v_med3_f32 v136, v136, s20, v199
	v_mul_f32_e32 v136, 0xbfb8aa3b, v136
	v_exp_f32_e32 v136, v136
	v_and_b32_e32 v137, 0xffff0000, v137
	v_max_f32_e32 v137, v137, v137
	v_med3_f32 v137, v137, s20, v199
	v_add_f32_e32 v136, 1.0, v136
	v_rcp_f32_e32 v136, v136
	v_max_f32_e32 v2, v2, v2
	v_max_f32_e32 v5, v5, v5
	v_med3_f32 v2, v2, s20, v199
	v_mul_f32_e32 v157, v28, v136
	v_mul_f32_e32 v136, 0xbfb8aa3b, v137
	v_exp_f32_e32 v136, v136
	v_med3_f32 v5, v5, s20, v199
	global_store_dwordx4 v[140:141], v[160:163], off
	v_mul_f32_e32 v2, 0xbfb8aa3b, v2
	v_add_f32_e32 v136, 1.0, v136
	v_rcp_f32_e32 v136, v136
	v_mul_f32_e32 v5, 0xbfb8aa3b, v5
	v_exp_f32_e32 v2, v2
	v_exp_f32_e32 v5, v5
	v_mul_f32_e32 v137, v29, v136
	v_lshlrev_b32_e32 v136, 16, v138
	v_max_f32_e32 v136, v136, v136
	v_med3_f32 v136, v136, s20, v199
	v_mul_f32_e32 v136, 0xbfb8aa3b, v136
	v_exp_f32_e32 v136, v136
	v_and_b32_e32 v138, 0xffff0000, v138
	v_max_f32_e32 v138, v138, v138
	v_med3_f32 v138, v138, s20, v199
	v_add_f32_e32 v136, 1.0, v136
	v_rcp_f32_e32 v136, v136
	v_add_f32_e32 v2, 1.0, v2
	v_add_f32_e32 v5, 1.0, v5
	v_rcp_f32_e32 v2, v2
	v_mul_f32_e32 v159, v22, v136
	v_mul_f32_e32 v136, 0xbfb8aa3b, v138
	v_exp_f32_e32 v136, v136
	v_rcp_f32_e32 v5, v5
	v_mul_f32_e32 v2, v26, v2
	v_add_f32_e32 v136, 1.0, v136
	v_rcp_f32_e32 v136, v136
	v_mul_f32_e32 v5, v27, v5
	v_mul_f32_e32 v138, v23, v136
	v_lshlrev_b32_e32 v136, 16, v139
	v_max_f32_e32 v136, v136, v136
	v_med3_f32 v136, v136, s20, v199
	v_mul_f32_e32 v136, 0xbfb8aa3b, v136
	v_exp_f32_e32 v136, v136
	v_and_b32_e32 v139, 0xffff0000, v139
	v_max_f32_e32 v139, v139, v139
	v_med3_f32 v139, v139, s20, v199
	v_add_f32_e32 v136, 1.0, v136
	v_rcp_f32_e32 v136, v136
	s_nop 0
	v_mul_f32_e32 v160, v24, v136
	v_mul_f32_e32 v136, 0xbfb8aa3b, v139
	v_exp_f32_e32 v136, v136
	s_nop 0
	v_add_f32_e32 v136, 1.0, v136
	v_rcp_f32_e32 v136, v136
	s_nop 0
	v_mul_f32_e32 v139, v25, v136
	v_cvt_pk_bf16_f32 v136, v2, v5
	v_cvt_pk_bf16_f32 v137, v157, v137
	v_cvt_pk_bf16_f32 v138, v159, v138
	v_cvt_pk_bf16_f32 v139, v160, v139
	global_store_dwordx4 v[140:141], v[136:139], off offset:256
	s_nop 1
	v_add_u32_e32 v138, 0xa0, v4
	v_mad_i64_i32 v[136:137], s[26:27], v138, s25, v[134:135]
	v_lshl_add_u64 v[136:137], v[136:137], 0, v[154:155]
	v_ashrrev_i32_e32 v139, 31, v138
	v_lshlrev_b64 v[138:139], 12, v[138:139]
	v_lshl_add_u64 v[138:139], s[6:7], 0, v[138:139]
	s_waitcnt vmcnt(13)
	v_mov_b64_e32 v[160:161], v[222:223]
	v_mov_b64_e32 v[162:163], v[224:225]
	v_lshlrev_b32_e32 v2, 16, v160
	v_and_b32_e32 v5, 0xffff0000, v160
	v_lshlrev_b32_e32 v160, 16, v163
	v_max_f32_e32 v160, v160, v160
	v_med3_f32 v160, v160, s20, v199
	v_mul_f32_e32 v160, 0xbfb8aa3b, v160
	v_exp_f32_e32 v160, v160
	v_lshlrev_b32_e32 v140, 16, v161
	v_and_b32_e32 v141, 0xffff0000, v161
	v_max_f32_e32 v140, v140, v140
	v_add_f32_e32 v160, 1.0, v160
	v_rcp_f32_e32 v160, v160
	v_max_f32_e32 v141, v141, v141
	v_lshlrev_b32_e32 v157, 16, v162
	v_and_b32_e32 v159, 0xffff0000, v162
	v_and_b32_e32 v161, 0xffff0000, v163
	v_max_f32_e32 v2, v2, v2
	v_max_f32_e32 v5, v5, v5
	v_med3_f32 v140, v140, s20, v199
	v_med3_f32 v141, v141, s20, v199
	v_max_f32_e32 v157, v157, v157
	v_max_f32_e32 v159, v159, v159
	v_max_f32_e32 v161, v161, v161
	v_med3_f32 v2, v2, s20, v199
	v_med3_f32 v5, v5, s20, v199
	v_mul_f32_e32 v140, 0xbfb8aa3b, v140
	v_mul_f32_e32 v141, 0xbfb8aa3b, v141
	v_med3_f32 v157, v157, s20, v199
	v_med3_f32 v159, v159, s20, v199
	v_med3_f32 v161, v161, s20, v199
	v_mul_f32_e32 v2, 0xbfb8aa3b, v2
	v_mul_f32_e32 v5, 0xbfb8aa3b, v5
	v_exp_f32_e32 v140, v140
	v_exp_f32_e32 v141, v141
	v_mul_f32_e32 v157, 0xbfb8aa3b, v157
	v_mul_f32_e32 v159, 0xbfb8aa3b, v159
	v_mul_f32_e32 v163, v48, v160
	v_mul_f32_e32 v160, 0xbfb8aa3b, v161
	v_exp_f32_e32 v2, v2
	v_exp_f32_e32 v5, v5
	v_exp_f32_e32 v157, v157
	v_exp_f32_e32 v159, v159
	v_exp_f32_e32 v160, v160
	v_add_f32_e32 v140, 1.0, v140
	v_add_f32_e32 v141, 1.0, v141
	v_add_f32_e32 v2, 1.0, v2
	v_add_f32_e32 v5, 1.0, v5
	v_rcp_f32_e32 v140, v140
	v_rcp_f32_e32 v141, v141
	v_add_f32_e32 v157, 1.0, v157
	v_add_f32_e32 v159, 1.0, v159
	v_add_f32_e32 v160, 1.0, v160
	v_rcp_f32_e32 v2, v2
	v_rcp_f32_e32 v5, v5
	v_rcp_f32_e32 v157, v157
	v_rcp_f32_e32 v159, v159
	v_rcp_f32_e32 v160, v160
	v_mul_f32_e32 v140, v52, v140
	v_mul_f32_e32 v141, v53, v141
	v_mul_f32_e32 v2, v50, v2
	v_mul_f32_e32 v5, v51, v5
	v_mul_f32_e32 v157, v46, v157
	v_mul_f32_e32 v159, v47, v159
	v_mul_f32_e32 v164, v49, v160
	v_cvt_pk_bf16_f32 v160, v2, v5
	v_cvt_pk_bf16_f32 v161, v140, v141
	v_cvt_pk_bf16_f32 v162, v157, v159
	v_cvt_pk_bf16_f32 v163, v163, v164
	v_lshl_add_u64 v[140:141], v[138:139], 0, v[154:155]
	s_waitcnt vmcnt(11)
; __device__ __forceinline__ unsigned cvt_pk_bf16(float lo, float hi) { unsigned r; asm volatile("v_cvt_pk_bf16_f32 %0, %1, %2" : "=v"(r) : "v"(lo), "v"(hi)); return r; }
; __device__ __forceinline__ float fast_sigmoid(float x) { return __builtin_amdgcn_rcpf(1.f + __expf(-x)); }
;     __device__ __forceinline__ void operator()(f32x4 (&acc)[2][2][4][2], const Unit& u, int wr, int wc, int fr, int fq) const {
;     ...
;             for (int st = 0; st < 16; ++st) { const int ai = st >> 3, m = (st >> 1) & 3, bj = st & 1;
;                 const size_t r = (size_t)(row0 + ai * HALF + m * 16); const int c = col0 + bj * HALF;
;                 const u32x4 ga = *(const u32x4*)(za + r * ldz + c);
;                 float o[8];
; #pragma unroll
;                 for (int j = 0; j < 4; ++j) { const unsigned wa = ga[j];
;                     const float a0 = fminf(fmaxf(__uint_as_float(wa << 16), -30.f), 30.f), a1 = fminf(fmaxf(__uint_as_float(wa & 0xffff0000u), -30.f), 30.f);
;                     o[2 * j] = acc[ai][bj][m][j >> 1][(j & 1) * 2] * fast_sigmoid(a0); o[2 * j + 1] = acc[ai][bj][m][j >> 1][(j & 1) * 2 + 1] * fast_sigmoid(a1); }
;                 u32x4 w; w.x = cvt_pk_bf16(o[0], o[1]); w.y = cvt_pk_bf16(o[2], o[3]); w.z = cvt_pk_bf16(o[4], o[5]); w.w = cvt_pk_bf16(o[6], o[7]);
;                 *(u32x4*)(MG + r * ldm + c) = w;
;                 if ((st & 3) == 3) asm volatile("" ::: "memory"); }
	v_mov_b64_e32 v[136:137], v[226:227]
	v_mov_b64_e32 v[138:139], v[228:229]
	v_lshlrev_b32_e32 v2, 16, v136
	v_and_b32_e32 v5, 0xffff0000, v136
	v_lshlrev_b32_e32 v136, 16, v137
	v_max_f32_e32 v136, v136, v136
	v_med3_f32 v136, v136, s20, v199
	v_mul_f32_e32 v136, 0xbfb8aa3b, v136
	v_exp_f32_e32 v136, v136
	v_and_b32_e32 v137, 0xffff0000, v137
	v_max_f32_e32 v137, v137, v137
	v_med3_f32 v137, v137, s20, v199
	v_add_f32_e32 v136, 1.0, v136
	v_rcp_f32_e32 v136, v136
	v_max_f32_e32 v2, v2, v2
	v_max_f32_e32 v5, v5, v5
	v_med3_f32 v2, v2, s20, v199
	v_mul_f32_e32 v157, v20, v136
	v_mul_f32_e32 v136, 0xbfb8aa3b, v137
	v_exp_f32_e32 v136, v136
	v_med3_f32 v5, v5, s20, v199
	global_store_dwordx4 v[140:141], v[160:163], off
	v_mul_f32_e32 v2, 0xbfb8aa3b, v2
	v_add_f32_e32 v136, 1.0, v136
	v_rcp_f32_e32 v136, v136
	v_mul_f32_e32 v5, 0xbfb8aa3b, v5
	v_exp_f32_e32 v2, v2
	v_exp_f32_e32 v5, v5
	v_mul_f32_e32 v137, v21, v136
	v_lshlrev_b32_e32 v136, 16, v138
	v_max_f32_e32 v136, v136, v136
	v_med3_f32 v136, v136, s20, v199
	v_mul_f32_e32 v136, 0xbfb8aa3b, v136
	v_exp_f32_e32 v136, v136
	v_and_b32_e32 v138, 0xffff0000, v138
	v_max_f32_e32 v138, v138, v138
	v_med3_f32 v138, v138, s20, v199
	v_add_f32_e32 v136, 1.0, v136
	v_rcp_f32_e32 v136, v136
	v_add_f32_e32 v2, 1.0, v2
	v_add_f32_e32 v5, 1.0, v5
	v_rcp_f32_e32 v2, v2
	v_mul_f32_e32 v159, v14, v136
	v_mul_f32_e32 v136, 0xbfb8aa3b, v138
	v_exp_f32_e32 v136, v136
	v_rcp_f32_e32 v5, v5
	v_mul_f32_e32 v2, v18, v2
	v_add_f32_e32 v136, 1.0, v136
	v_rcp_f32_e32 v136, v136
	v_mul_f32_e32 v5, v19, v5
	v_mul_f32_e32 v138, v15, v136
	v_lshlrev_b32_e32 v136, 16, v139
	v_max_f32_e32 v136, v136, v136
	v_med3_f32 v136, v136, s20, v199
	v_mul_f32_e32 v136, 0xbfb8aa3b, v136
	v_exp_f32_e32 v136, v136
	v_and_b32_e32 v139, 0xffff0000, v139
	v_max_f32_e32 v139, v139, v139
	v_med3_f32 v139, v139, s20, v199
	v_add_f32_e32 v136, 1.0, v136
	v_rcp_f32_e32 v136, v136
	s_nop 0
	v_mul_f32_e32 v160, v16, v136
	v_mul_f32_e32 v136, 0xbfb8aa3b, v139
	v_exp_f32_e32 v136, v136
	s_nop 0
	v_add_f32_e32 v136, 1.0, v136
	v_rcp_f32_e32 v136, v136
	s_nop 0
	v_mul_f32_e32 v139, v17, v136
	v_cvt_pk_bf16_f32 v136, v2, v5
	v_cvt_pk_bf16_f32 v137, v157, v137
	v_cvt_pk_bf16_f32 v138, v159, v138
	v_cvt_pk_bf16_f32 v139, v160, v139
	global_store_dwordx4 v[140:141], v[136:139], off offset:256
	s_nop 1
	v_add_u32_e32 v136, 0xb0, v4
	v_mad_i64_i32 v[134:135], s[26:27], v136, s25, v[134:135]
	v_lshl_add_u64 v[134:135], v[134:135], 0, v[154:155]
	v_ashrrev_i32_e32 v137, 31, v136
	v_lshlrev_b64 v[136:137], 12, v[136:137]
	v_lshl_add_u64 v[136:137], s[6:7], 0, v[136:137]
	v_lshl_add_u64 v[136:137], v[136:137], 0, v[154:155]
	s_waitcnt vmcnt(11)
; __device__ __forceinline__ unsigned cvt_pk_bf16(float lo, float hi) { unsigned r; asm volatile("v_cvt_pk_bf16_f32 %0, %1, %2" : "=v"(r) : "v"(lo), "v"(hi)); return r; }
; __device__ __forceinline__ float fast_sigmoid(float x) { return __builtin_amdgcn_rcpf(1.f + __expf(-x)); }
;     __device__ __forceinline__ void operator()(f32x4 (&acc)[2][2][4][2], const Unit& u, int wr, int wc, int fr, int fq) const {
;     ...
;             for (int st = 0; st < 16; ++st) { const int ai = st >> 3, m = (st >> 1) & 3, bj = st & 1;
;                 const size_t r = (size_t)(row0 + ai * HALF + m * 16); const int c = col0 + bj * HALF;
;                 const u32x4 ga = *(const u32x4*)(za + r * ldz + c);
;                 float o[8];
; #pragma unroll
;                 for (int j = 0; j < 4; ++j) { const unsigned wa = ga[j];
;                     const float a0 = fminf(fmaxf(__uint_as_float(wa << 16), -30.f), 30.f), a1 = fminf(fmaxf(__uint_as_float(wa & 0xffff0000u), -30.f), 30.f);
;                     o[2 * j] = acc[ai][bj][m][j >> 1][(j & 1) * 2] * fast_sigmoid(a0); o[2 * j + 1] = acc[ai][bj][m][j >> 1][(j & 1) * 2 + 1] * fast_sigmoid(a1); }
;                 u32x4 w; w.x = cvt_pk_bf16(o[0], o[1]); w.y = cvt_pk_bf16(o[2], o[3]); w.z = cvt_pk_bf16(o[4], o[5]); w.w = cvt_pk_bf16(o[6], o[7]);
;                 *(u32x4*)(MG + r * ldm + c) = w;
;                 if ((st & 3) == 3) asm volatile("" ::: "memory"); }
	v_mov_b64_e32 v[138:139], v[230:231]
	v_mov_b64_e32 v[140:141], v[232:233]
	v_lshlrev_b32_e32 v2, 16, v138
	v_and_b32_e32 v5, 0xffff0000, v138
	v_lshlrev_b32_e32 v138, 16, v139
	v_max_f32_e32 v138, v138, v138
	v_med3_f32 v138, v138, s20, v199
	v_mul_f32_e32 v138, 0xbfb8aa3b, v138
	v_exp_f32_e32 v138, v138
	v_and_b32_e32 v139, 0xffff0000, v139
	v_max_f32_e32 v139, v139, v139
	v_med3_f32 v139, v139, s20, v199
	v_add_f32_e32 v138, 1.0, v138
	v_rcp_f32_e32 v138, v138
	v_max_f32_e32 v2, v2, v2
	v_max_f32_e32 v5, v5, v5
	v_med3_f32 v2, v2, s20, v199
	v_mul_f32_e32 v157, v44, v138
	v_mul_f32_e32 v138, 0xbfb8aa3b, v139
	v_exp_f32_e32 v138, v138
	v_med3_f32 v5, v5, s20, v199
	v_mul_f32_e32 v2, 0xbfb8aa3b, v2
	v_mul_f32_e32 v5, 0xbfb8aa3b, v5
	v_add_f32_e32 v138, 1.0, v138
	v_rcp_f32_e32 v138, v138
	v_exp_f32_e32 v2, v2
	v_exp_f32_e32 v5, v5
	v_mul_f32_e32 v139, v45, v138
	v_lshlrev_b32_e32 v138, 16, v140
	v_max_f32_e32 v138, v138, v138
	v_med3_f32 v138, v138, s20, v199
	v_mul_f32_e32 v138, 0xbfb8aa3b, v138
	v_exp_f32_e32 v138, v138
	v_and_b32_e32 v140, 0xffff0000, v140
	v_max_f32_e32 v140, v140, v140
	v_med3_f32 v140, v140, s20, v199
	v_add_f32_e32 v138, 1.0, v138
	v_rcp_f32_e32 v138, v138
	v_add_f32_e32 v2, 1.0, v2
	v_add_f32_e32 v5, 1.0, v5
	v_rcp_f32_e32 v2, v2
	v_mul_f32_e32 v159, v38, v138
	v_mul_f32_e32 v138, 0xbfb8aa3b, v140
	v_exp_f32_e32 v138, v138
	v_rcp_f32_e32 v5, v5
	v_mul_f32_e32 v2, v42, v2
	v_add_f32_e32 v138, 1.0, v138
	v_rcp_f32_e32 v138, v138
	v_mul_f32_e32 v5, v43, v5
	v_mul_f32_e32 v140, v39, v138
	v_lshlrev_b32_e32 v138, 16, v141
	v_max_f32_e32 v138, v138, v138
	v_med3_f32 v138, v138, s20, v199
	v_mul_f32_e32 v138, 0xbfb8aa3b, v138
	v_exp_f32_e32 v138, v138
	v_and_b32_e32 v141, 0xffff0000, v141
	v_max_f32_e32 v141, v141, v141
	v_med3_f32 v141, v141, s20, v199
	v_add_f32_e32 v138, 1.0, v138
	v_rcp_f32_e32 v138, v138
	s_nop 0
	v_mul_f32_e32 v160, v40, v138
	v_mul_f32_e32 v138, 0xbfb8aa3b, v141
	v_exp_f32_e32 v138, v138
	s_nop 0
	v_add_f32_e32 v138, 1.0, v138
	v_rcp_f32_e32 v138, v138
	s_nop 0
	v_mul_f32_e32 v141, v41, v138
	v_cvt_pk_bf16_f32 v138, v2, v5
	v_cvt_pk_bf16_f32 v139, v157, v139
	v_cvt_pk_bf16_f32 v140, v159, v140
	v_cvt_pk_bf16_f32 v141, v160, v141
	global_store_dwordx4 v[136:137], v[138:141], off
	s_waitcnt vmcnt(10)
	v_mov_b64_e32 v[138:139], v[234:235]
	v_mov_b64_e32 v[140:141], v[236:237]
	v_lshlrev_b32_e32 v2, 16, v138
	v_and_b32_e32 v5, 0xffff0000, v138
	v_lshlrev_b32_e32 v138, 16, v140
	v_max_f32_e32 v138, v138, v138
	v_med3_f32 v138, v138, s20, v199
	v_mul_f32_e32 v138, 0xbfb8aa3b, v138
	v_exp_f32_e32 v138, v138
	v_lshlrev_b32_e32 v134, 16, v139
	v_and_b32_e32 v135, 0xffff0000, v139
	v_and_b32_e32 v139, 0xffff0000, v140
	v_add_f32_e32 v138, 1.0, v138
	v_rcp_f32_e32 v138, v138
	v_max_f32_e32 v139, v139, v139
	v_med3_f32 v139, v139, s20, v199
	v_max_f32_e32 v2, v2, v2
	v_mul_f32_e32 v140, v6, v138
	v_mul_f32_e32 v138, 0xbfb8aa3b, v139
	v_exp_f32_e32 v138, v138
	v_and_b32_e32 v139, 0xffff0000, v141
	v_max_f32_e32 v5, v5, v5
	v_max_f32_e32 v134, v134, v134
	v_add_f32_e32 v138, 1.0, v138
	v_rcp_f32_e32 v138, v138
	v_max_f32_e32 v135, v135, v135
	v_max_f32_e32 v139, v139, v139
	v_med3_f32 v2, v2, s20, v199
	v_mul_f32_e32 v157, v7, v138
	v_lshlrev_b32_e32 v138, 16, v141
	v_max_f32_e32 v138, v138, v138
	v_med3_f32 v138, v138, s20, v199
	v_mul_f32_e32 v138, 0xbfb8aa3b, v138
	v_exp_f32_e32 v138, v138
	v_med3_f32 v5, v5, s20, v199
	v_med3_f32 v134, v134, s20, v199
	v_med3_f32 v135, v135, s20, v199
	v_add_f32_e32 v138, 1.0, v138
	v_rcp_f32_e32 v138, v138
	v_med3_f32 v139, v139, s20, v199
	v_mul_f32_e32 v2, 0xbfb8aa3b, v2
	v_mul_f32_e32 v5, 0xbfb8aa3b, v5
	v_mul_f32_e32 v134, 0xbfb8aa3b, v134
	v_mul_f32_e32 v135, 0xbfb8aa3b, v135
	v_mul_f32_e32 v141, v8, v138
	v_mul_f32_e32 v138, 0xbfb8aa3b, v139
	v_exp_f32_e32 v2, v2
	v_exp_f32_e32 v5, v5
	v_exp_f32_e32 v134, v134
	v_exp_f32_e32 v135, v135
	v_exp_f32_e32 v138, v138
	v_add_f32_e32 v2, 1.0, v2
	v_add_f32_e32 v5, 1.0, v5
	v_add_f32_e32 v134, 1.0, v134
	v_add_f32_e32 v135, 1.0, v135
	v_add_f32_e32 v138, 1.0, v138
	v_rcp_f32_e32 v2, v2
	v_rcp_f32_e32 v5, v5
	v_rcp_f32_e32 v134, v134
	v_rcp_f32_e32 v135, v135
	v_rcp_f32_e32 v138, v138
	v_mul_f32_e32 v2, v10, v2
	v_mul_f32_e32 v5, v11, v5
	v_mul_f32_e32 v134, v12, v134
	v_mul_f32_e32 v135, v13, v135
	v_mul_f32_e32 v159, v9, v138
	v_cvt_pk_bf16_f32 v138, v2, v5
	v_cvt_pk_bf16_f32 v139, v134, v135
	v_cvt_pk_bf16_f32 v140, v140, v157
	v_cvt_pk_bf16_f32 v141, v141, v159
	global_store_dwordx4 v[136:137], v[138:141], off offset:256
	s_cbranch_execz .LBB0_2103

;     __device__ __forceinline__ void operator()(f32x4 (&acc)[2][2][4][2], const Unit& u, int wr, int wc, int fr, int fq) const {
;     ...
;             for (int st = 0; st < 16; ++st) { const int ai = st >> 3, m = (st >> 1) & 3, bj = st & 1;
;                 const size_t r = (size_t)(row0 + ai * HALF + m * 16); const int c = col0 + bj * HALF;
;                 const u32x4 ga = *(const u32x4*)(za + r * ldz + c), gb = *(const u32x4*)(zb + r * ldz + c);
; #pragma unroll
;                 for (int j = 0; j < 4; ++j) { const unsigned wa = ga[j], wb = gb[j];
;                     const float a0 = fminf(fmaxf(__uint_as_float(wa << 16), -30.f), 30.f), a1 = fminf(fmaxf(__uint_as_float(wa & 0xffff0000u), -30.f), 30.f);
;                     const float b0 = fminf(fmaxf(__uint_as_float(wb << 16), -30.f), 30.f), b1 = fminf(fmaxf(__uint_as_float(wb & 0xffff0000u), -30.f), 30.f);
;                     const float r0 = (1.f + __expf(-b0)) * __builtin_amdgcn_rcpf(1.f + __expf(-a0)), r1 = (1.f + __expf(-b1)) * __builtin_amdgcn_rcpf(1.f + __expf(-a1));
;                     acc[ai][bj][m][j >> 1][(j & 1) * 2] *= r0; acc[ai][bj][m][j >> 1][(j & 1) * 2 + 1] *= r1; }
;                 if ((st & 3) == 3) asm volatile("" ::: "memory"); }
.LBB0_2103:
	s_add_u32 s26, s36, 0x1000
	v_mov_b64_e32 v[162:163], s[36:37]
	s_addc_u32 s27, s37, 0
	v_mad_i64_i32 v[134:135], s[36:37], v4, s25, v[162:163]
	v_lshl_add_u64 v[134:135], v[134:135], 0, v[154:155]
	v_mov_b64_e32 v[160:161], s[26:27]
	v_mad_i64_i32 v[246:247], s[26:27], v4, s25, v[162:163]
	v_lshl_add_u64 v[246:247], v[246:247], 0, v[154:155]
	global_load_dwordx4 v[214:217], v[246:247], off
	v_mad_i64_i32 v[248:249], s[26:27], v4, s25, v[160:161]
	v_lshl_add_u64 v[248:249], v[248:249], 0, v[154:155]
	global_load_dwordx4 v[218:221], v[248:249], off
	v_mad_i64_i32 v[246:247], s[26:27], v4, s25, v[162:163]
	v_lshl_add_u64 v[246:247], v[246:247], 0, v[154:155]
	global_load_dwordx4 v[222:225], v[246:247], off offset:256
	v_mad_i64_i32 v[248:249], s[26:27], v4, s25, v[160:161]
	v_lshl_add_u64 v[248:249], v[248:249], 0, v[154:155]
	global_load_dwordx4 v[226:229], v[248:249], off offset:256
	v_add_u32_e32 v213, 0x10, v4
	v_mad_i64_i32 v[246:247], s[26:27], v213, s25, v[162:163]
	v_lshl_add_u64 v[246:247], v[246:247], 0, v[154:155]
	global_load_dwordx4 v[230:233], v[246:247], off
	v_add_u32_e32 v213, 0x10, v4
	v_mad_i64_i32 v[248:249], s[26:27], v213, s25, v[160:161]
	v_lshl_add_u64 v[248:249], v[248:249], 0, v[154:155]
	global_load_dwordx4 v[234:237], v[248:249], off
	v_add_u32_e32 v213, 0x10, v4
	v_mad_i64_i32 v[246:247], s[26:27], v213, s25, v[160:161]
	v_lshl_add_u64 v[246:247], v[246:247], 0, v[154:155]
	global_load_dwordx4 v[238:241], v[246:247], off offset:256
	v_add_u32_e32 v213, 0x10, v4
	v_mad_i64_i32 v[248:249], s[26:27], v213, s25, v[162:163]
	v_lshl_add_u64 v[248:249], v[248:249], 0, v[154:155]
	global_load_dwordx4 v[242:245], v[248:249], off offset:256
	v_add_u32_e32 v213, 0x20, v4
	v_mad_i64_i32 v[246:247], s[26:27], v213, s25, v[162:163]
	v_lshl_add_u64 v[246:247], v[246:247], 0, v[154:155]
	global_load_dwordx4 v[204:207], v[246:247], off
	v_add_u32_e32 v213, 0x20, v4
	v_mad_i64_i32 v[248:249], s[26:27], v213, s25, v[160:161]
	v_lshl_add_u64 v[248:249], v[248:249], 0, v[154:155]
	global_load_dwordx4 v[208:211], v[248:249], off
	v_mad_i64_i32 v[136:137], s[26:27], v4, s25, v[160:161]
	v_lshl_add_u64 v[136:137], v[136:137], 0, v[154:155]
	s_waitcnt vmcnt(9)
	v_mov_b64_e32 v[138:139], v[214:215]
	v_mov_b64_e32 v[140:141], v[216:217]
	v_add_u32_e32 v213, 0x20, v4
	v_mad_i64_i32 v[246:247], s[26:27], v213, s25, v[160:161]
	v_lshl_add_u64 v[246:247], v[246:247], 0, v[154:155]
	global_load_dwordx4 v[214:217], v[246:247], off offset:256
	s_waitcnt vmcnt(9)
	v_mov_b64_e32 v[178:179], v[218:219]
	v_mov_b64_e32 v[180:181], v[220:221]
	v_add_u32_e32 v213, 0x20, v4
	v_mad_i64_i32 v[248:249], s[26:27], v213, s25, v[162:163]
	v_lshl_add_u64 v[248:249], v[248:249], 0, v[154:155]
	global_load_dwordx4 v[218:221], v[248:249], off offset:256
	v_lshlrev_b32_e32 v2, 16, v138
	v_max_f32_e32 v2, v2, v2
	v_med3_f32 v2, v2, s20, v199
	v_mul_f32_e32 v2, 0xbfb8aa3b, v2
	v_exp_f32_e32 v2, v2
	v_and_b32_e32 v157, 0xffff0000, v178
	v_and_b32_e32 v5, 0xffff0000, v138
	v_max_f32_e32 v157, v157, v157
	v_max_f32_e32 v5, v5, v5
	v_med3_f32 v157, v157, s20, v199
	v_add_f32_e32 v2, 1.0, v2
	v_med3_f32 v5, v5, s20, v199
	v_rcp_f32_e32 v170, v2
	v_mul_f32_e32 v2, 0xbfb8aa3b, v157
	v_exp_f32_e32 v165, v2
	v_mul_f32_e32 v2, 0xbfb8aa3b, v5
	v_exp_f32_e32 v2, v2
	v_and_b32_e32 v5, 0xffff0000, v139
	v_lshlrev_b32_e32 v138, 16, v178
	v_max_f32_e32 v5, v5, v5
	v_add_f32_e32 v2, 1.0, v2
	v_rcp_f32_e32 v171, v2
	v_lshlrev_b32_e32 v2, 16, v139
	v_max_f32_e32 v2, v2, v2
	v_med3_f32 v2, v2, s20, v199
	v_mul_f32_e32 v2, 0xbfb8aa3b, v2
	v_exp_f32_e32 v2, v2
	v_and_b32_e32 v139, 0xffff0000, v179
	v_max_f32_e32 v139, v139, v139
	v_med3_f32 v139, v139, s20, v199
	v_add_f32_e32 v2, 1.0, v2
	v_max_f32_e32 v138, v138, v138
	v_med3_f32 v5, v5, s20, v199
	v_rcp_f32_e32 v178, v2
	v_mul_f32_e32 v2, 0xbfb8aa3b, v139
	v_med3_f32 v138, v138, s20, v199
	v_exp_f32_e32 v139, v2
	v_mul_f32_e32 v2, 0xbfb8aa3b, v5
	v_mul_f32_e32 v138, 0xbfb8aa3b, v138
	v_exp_f32_e32 v2, v2
	v_exp_f32_e32 v164, v138
	v_lshlrev_b32_e32 v138, 16, v179
	v_max_f32_e32 v138, v138, v138
	v_med3_f32 v138, v138, s20, v199
	v_mul_f32_e32 v138, 0xbfb8aa3b, v138
	v_add_f32_e32 v2, 1.0, v2
	v_exp_f32_e32 v138, v138
	v_rcp_f32_e32 v179, v2
	v_lshlrev_b32_e32 v2, 16, v140
	v_max_f32_e32 v2, v2, v2
	v_med3_f32 v2, v2, s20, v199
	v_mul_f32_e32 v2, 0xbfb8aa3b, v2
	v_pk_add_f32 v[138:139], v[138:139], 1.0 op_sel_hi:[1,0]
	v_exp_f32_e32 v2, v2
	v_pk_mul_f32 v[138:139], v[138:139], v[178:179]
	v_pk_add_f32 v[164:165], v[164:165], 1.0 op_sel_hi:[1,0]
	v_pk_mul_f32 v[132:133], v[132:133], v[138:139]
	v_and_b32_e32 v139, 0xffff0000, v180
	v_and_b32_e32 v5, 0xffff0000, v140
	v_max_f32_e32 v139, v139, v139
	v_pk_mul_f32 v[164:165], v[164:165], v[170:171]
	v_max_f32_e32 v5, v5, v5
	v_med3_f32 v139, v139, s20, v199
	v_add_f32_e32 v2, 1.0, v2
	v_pk_mul_f32 v[130:131], v[130:131], v[164:165]
	v_med3_f32 v5, v5, s20, v199
	v_rcp_f32_e32 v164, v2
	v_mul_f32_e32 v2, 0xbfb8aa3b, v139
	v_exp_f32_e32 v139, v2
	v_mul_f32_e32 v2, 0xbfb8aa3b, v5
	v_exp_f32_e32 v2, v2
	v_and_b32_e32 v5, 0xffff0000, v141
	v_max_f32_e32 v5, v5, v5
	v_med3_f32 v5, v5, s20, v199
	v_add_f32_e32 v2, 1.0, v2
	v_rcp_f32_e32 v165, v2
	v_lshlrev_b32_e32 v2, 16, v141
	v_max_f32_e32 v2, v2, v2
	v_med3_f32 v2, v2, s20, v199
	v_mul_f32_e32 v2, 0xbfb8aa3b, v2
	v_exp_f32_e32 v2, v2
	v_and_b32_e32 v141, 0xffff0000, v181
	v_max_f32_e32 v141, v141, v141
	v_med3_f32 v141, v141, s20, v199
	v_add_f32_e32 v2, 1.0, v2
	v_rcp_f32_e32 v170, v2
	v_mul_f32_e32 v2, 0xbfb8aa3b, v141
	v_exp_f32_e32 v141, v2
	v_mul_f32_e32 v2, 0xbfb8aa3b, v5
	v_lshlrev_b32_e32 v138, 16, v180
	v_lshlrev_b32_e32 v140, 16, v181
	v_exp_f32_e32 v2, v2
	v_max_f32_e32 v138, v138, v138
	v_max_f32_e32 v140, v140, v140
	v_med3_f32 v138, v138, s20, v199
	v_med3_f32 v140, v140, s20, v199
	v_mul_f32_e32 v138, 0xbfb8aa3b, v138
	v_mul_f32_e32 v140, 0xbfb8aa3b, v140
	v_exp_f32_e32 v138, v138
	v_exp_f32_e32 v140, v140
	v_add_f32_e32 v2, 1.0, v2
	v_rcp_f32_e32 v171, v2
	v_pk_add_f32 v[138:139], v[138:139], 1.0 op_sel_hi:[1,0]
	v_pk_add_f32 v[140:141], v[140:141], 1.0 op_sel_hi:[1,0]
	v_pk_mul_f32 v[138:139], v[138:139], v[164:165]
	v_pk_mul_f32 v[140:141], v[140:141], v[170:171]
	v_pk_mul_f32 v[126:127], v[126:127], v[138:139]
	v_pk_mul_f32 v[128:129], v[128:129], v[140:141]
	s_nop 0
	s_waitcnt vmcnt(9)
;     __device__ __forceinline__ void operator()(f32x4 (&acc)[2][2][4][2], const Unit& u, int wr, int wc, int fr, int fq) const {
;     ...
;             for (int st = 0; st < 16; ++st) { const int ai = st >> 3, m = (st >> 1) & 3, bj = st & 1;
;                 const size_t r = (size_t)(row0 + ai * HALF + m * 16); const int c = col0 + bj * HALF;
;                 const u32x4 ga = *(const u32x4*)(za + r * ldz + c), gb = *(const u32x4*)(zb + r * ldz + c);
; #pragma unroll
;                 for (int j = 0; j < 4; ++j) { const unsigned wa = ga[j], wb = gb[j];
;                     const float a0 = fminf(fmaxf(__uint_as_float(wa << 16), -30.f), 30.f), a1 = fminf(fmaxf(__uint_as_float(wa & 0xffff0000u), -30.f), 30.f);
;                     const float b0 = fminf(fmaxf(__uint_as_float(wb << 16), -30.f), 30.f), b1 = fminf(fmaxf(__uint_as_float(wb & 0xffff0000u), -30.f), 30.f);
;                     const float r0 = (1.f + __expf(-b0)) * __builtin_amdgcn_rcpf(1.f + __expf(-a0)), r1 = (1.f + __expf(-b1)) * __builtin_amdgcn_rcpf(1.f + __expf(-a1));
;                     acc[ai][bj][m][j >> 1][(j & 1) * 2] *= r0; acc[ai][bj][m][j >> 1][(j & 1) * 2 + 1] *= r1; }
;                 if ((st & 3) == 3) asm volatile("" ::: "memory"); }
	v_mov_b64_e32 v[138:139], v[222:223]
	v_mov_b64_e32 v[140:141], v[224:225]
	v_add_u32_e32 v213, 0x30, v4
	v_mad_i64_i32 v[246:247], s[26:27], v213, s25, v[162:163]
	v_lshl_add_u64 v[246:247], v[246:247], 0, v[154:155]
	global_load_dwordx4 v[222:225], v[246:247], off
	v_lshlrev_b32_e32 v2, 16, v138
	v_max_f32_e32 v2, v2, v2
	v_med3_f32 v2, v2, s20, v199
	v_mul_f32_e32 v2, 0xbfb8aa3b, v2
	v_exp_f32_e32 v2, v2
	v_and_b32_e32 v5, 0xffff0000, v138
	s_waitcnt vmcnt(9)
	v_mov_b64_e32 v[134:135], v[226:227]
	v_mov_b64_e32 v[136:137], v[228:229]
	v_add_u32_e32 v213, 0x30, v4
	v_mad_i64_i32 v[248:249], s[26:27], v213, s25, v[160:161]
	v_lshl_add_u64 v[248:249], v[248:249], 0, v[154:155]
	global_load_dwordx4 v[226:229], v[248:249], off
	v_lshlrev_b32_e32 v138, 16, v134
	v_and_b32_e32 v134, 0xffff0000, v134
	v_max_f32_e32 v134, v134, v134
	v_max_f32_e32 v5, v5, v5
	v_med3_f32 v134, v134, s20, v199
	v_add_f32_e32 v2, 1.0, v2
	v_med3_f32 v5, v5, s20, v199
	v_rcp_f32_e32 v170, v2
	v_mul_f32_e32 v2, 0xbfb8aa3b, v134
	v_exp_f32_e32 v165, v2
	v_mul_f32_e32 v2, 0xbfb8aa3b, v5
	v_exp_f32_e32 v2, v2
	v_max_f32_e32 v138, v138, v138
	v_lshlrev_b32_e32 v134, 16, v135
	v_and_b32_e32 v135, 0xffff0000, v135
	v_add_f32_e32 v2, 1.0, v2
	v_rcp_f32_e32 v171, v2
	v_lshlrev_b32_e32 v2, 16, v139
	v_max_f32_e32 v2, v2, v2
	v_med3_f32 v2, v2, s20, v199
	v_mul_f32_e32 v2, 0xbfb8aa3b, v2
	v_exp_f32_e32 v2, v2
	v_med3_f32 v138, v138, s20, v199
	v_and_b32_e32 v5, 0xffff0000, v139
	v_max_f32_e32 v135, v135, v135
	v_mul_f32_e32 v138, 0xbfb8aa3b, v138
	v_max_f32_e32 v5, v5, v5
	v_med3_f32 v135, v135, s20, v199
	v_add_f32_e32 v2, 1.0, v2
	v_exp_f32_e32 v164, v138
	v_med3_f32 v5, v5, s20, v199
	v_rcp_f32_e32 v138, v2
	v_mul_f32_e32 v2, 0xbfb8aa3b, v135
	v_exp_f32_e32 v135, v2
	v_mul_f32_e32 v2, 0xbfb8aa3b, v5
	v_exp_f32_e32 v2, v2
	v_max_f32_e32 v134, v134, v134
	v_med3_f32 v134, v134, s20, v199
	v_mul_f32_e32 v134, 0xbfb8aa3b, v134
	v_add_f32_e32 v2, 1.0, v2
	v_exp_f32_e32 v134, v134
	v_rcp_f32_e32 v139, v2
	v_lshlrev_b32_e32 v2, 16, v140
	v_max_f32_e32 v2, v2, v2
	v_med3_f32 v2, v2, s20, v199
	v_mul_f32_e32 v2, 0xbfb8aa3b, v2
	v_pk_add_f32 v[134:135], v[134:135], 1.0 op_sel_hi:[1,0]
	v_exp_f32_e32 v2, v2
	v_pk_mul_f32 v[134:135], v[134:135], v[138:139]
	v_and_b32_e32 v5, 0xffff0000, v140
	v_pk_mul_f32 v[100:101], v[100:101], v[134:135]
	v_and_b32_e32 v135, 0xffff0000, v136
	v_max_f32_e32 v135, v135, v135
	v_max_f32_e32 v5, v5, v5
	v_med3_f32 v135, v135, s20, v199
	v_add_f32_e32 v2, 1.0, v2
	v_med3_f32 v5, v5, s20, v199
	v_rcp_f32_e32 v138, v2
	v_mul_f32_e32 v2, 0xbfb8aa3b, v135
	v_exp_f32_e32 v135, v2
	v_mul_f32_e32 v2, 0xbfb8aa3b, v5
	v_exp_f32_e32 v2, v2
	v_lshlrev_b32_e32 v134, 16, v136
	v_lshlrev_b32_e32 v136, 16, v137
	v_and_b32_e32 v137, 0xffff0000, v137
	v_add_f32_e32 v2, 1.0, v2
	v_rcp_f32_e32 v139, v2
	v_lshlrev_b32_e32 v2, 16, v141
	v_max_f32_e32 v2, v2, v2
	v_med3_f32 v2, v2, s20, v199
	v_mul_f32_e32 v2, 0xbfb8aa3b, v2
	v_exp_f32_e32 v2, v2
	v_and_b32_e32 v5, 0xffff0000, v141
	v_max_f32_e32 v137, v137, v137
	v_max_f32_e32 v5, v5, v5
	v_med3_f32 v137, v137, s20, v199
	v_add_f32_e32 v2, 1.0, v2
	v_med3_f32 v5, v5, s20, v199
	v_rcp_f32_e32 v140, v2
	v_mul_f32_e32 v2, 0xbfb8aa3b, v137
	v_max_f32_e32 v134, v134, v134
	v_exp_f32_e32 v137, v2
	v_mul_f32_e32 v2, 0xbfb8aa3b, v5
	v_med3_f32 v134, v134, s20, v199
	v_exp_f32_e32 v2, v2
	v_mul_f32_e32 v134, 0xbfb8aa3b, v134
	v_max_f32_e32 v136, v136, v136
	v_exp_f32_e32 v134, v134
	v_med3_f32 v136, v136, s20, v199
	v_mul_f32_e32 v136, 0xbfb8aa3b, v136
	v_exp_f32_e32 v136, v136
	v_add_f32_e32 v2, 1.0, v2
	v_rcp_f32_e32 v141, v2
	v_pk_add_f32 v[134:135], v[134:135], 1.0 op_sel_hi:[1,0]
	v_pk_add_f32 v[136:137], v[136:137], 1.0 op_sel_hi:[1,0]
	v_pk_mul_f32 v[134:135], v[134:135], v[138:139]
	v_pk_mul_f32 v[136:137], v[136:137], v[140:141]
	v_pk_mul_f32 v[94:95], v[94:95], v[134:135]
	v_mad_i64_i32 v[134:135], s[26:27], v174, s25, v[162:163]
	v_lshl_add_u64 v[138:139], v[134:135], 0, v[154:155]
	v_pk_mul_f32 v[96:97], v[96:97], v[136:137]
	v_mad_i64_i32 v[140:141], s[26:27], v174, s25, v[160:161]
	v_lshl_add_u64 v[140:141], v[140:141], 0, v[154:155]
	v_pk_add_f32 v[164:165], v[164:165], 1.0 op_sel_hi:[1,0]
	s_waitcnt vmcnt(9)
	v_mov_b64_e32 v[134:135], v[230:231]
	v_mov_b64_e32 v[136:137], v[232:233]
	v_add_u32_e32 v213, 0x30, v4
	v_mad_i64_i32 v[246:247], s[26:27], v213, s25, v[160:161]
	v_lshl_add_u64 v[246:247], v[246:247], 0, v[154:155]
	global_load_dwordx4 v[230:233], v[246:247], off offset:256
	v_lshlrev_b32_e32 v2, 16, v134
	v_max_f32_e32 v2, v2, v2
	v_med3_f32 v2, v2, s20, v199
	v_mul_f32_e32 v2, 0xbfb8aa3b, v2
	v_exp_f32_e32 v2, v2
	s_waitcnt vmcnt(9)
;     __device__ __forceinline__ void operator()(f32x4 (&acc)[2][2][4][2], const Unit& u, int wr, int wc, int fr, int fq) const {
;     ...
;             for (int st = 0; st < 16; ++st) { const int ai = st >> 3, m = (st >> 1) & 3, bj = st & 1;
;                 const size_t r = (size_t)(row0 + ai * HALF + m * 16); const int c = col0 + bj * HALF;
;                 const u32x4 ga = *(const u32x4*)(za + r * ldz + c), gb = *(const u32x4*)(zb + r * ldz + c);
; #pragma unroll
;                 for (int j = 0; j < 4; ++j) { const unsigned wa = ga[j], wb = gb[j];
;                     const float a0 = fminf(fmaxf(__uint_as_float(wa << 16), -30.f), 30.f), a1 = fminf(fmaxf(__uint_as_float(wa & 0xffff0000u), -30.f), 30.f);
;                     const float b0 = fminf(fmaxf(__uint_as_float(wb << 16), -30.f), 30.f), b1 = fminf(fmaxf(__uint_as_float(wb & 0xffff0000u), -30.f), 30.f);
;                     const float r0 = (1.f + __expf(-b0)) * __builtin_amdgcn_rcpf(1.f + __expf(-a0)), r1 = (1.f + __expf(-b1)) * __builtin_amdgcn_rcpf(1.f + __expf(-a1));
;                     acc[ai][bj][m][j >> 1][(j & 1) * 2] *= r0; acc[ai][bj][m][j >> 1][(j & 1) * 2 + 1] *= r1; }
;                 if ((st & 3) == 3) asm volatile("" ::: "memory"); }
	v_mov_b64_e32 v[178:179], v[234:235]
	v_mov_b64_e32 v[180:181], v[236:237]
	v_add_u32_e32 v213, 0x30, v4
	v_mad_i64_i32 v[248:249], s[26:27], v213, s25, v[162:163]
	v_lshl_add_u64 v[248:249], v[248:249], 0, v[154:155]
	global_load_dwordx4 v[234:237], v[248:249], off offset:256
	v_and_b32_e32 v157, 0xffff0000, v178
	v_and_b32_e32 v5, 0xffff0000, v134
	v_max_f32_e32 v157, v157, v157
	v_max_f32_e32 v5, v5, v5
	v_med3_f32 v157, v157, s20, v199
	v_add_f32_e32 v2, 1.0, v2
	v_pk_mul_f32 v[164:165], v[164:165], v[170:171]
	v_med3_f32 v5, v5, s20, v199
	v_rcp_f32_e32 v170, v2
	v_mul_f32_e32 v2, 0xbfb8aa3b, v157
	v_pk_mul_f32 v[98:99], v[98:99], v[164:165]
	v_exp_f32_e32 v165, v2
	v_mul_f32_e32 v2, 0xbfb8aa3b, v5
	v_exp_f32_e32 v2, v2
	v_and_b32_e32 v5, 0xffff0000, v135
	v_lshlrev_b32_e32 v134, 16, v178
	v_max_f32_e32 v5, v5, v5
	v_add_f32_e32 v2, 1.0, v2
	v_rcp_f32_e32 v171, v2
	v_lshlrev_b32_e32 v2, 16, v135
	v_max_f32_e32 v2, v2, v2
	v_med3_f32 v2, v2, s20, v199
	v_mul_f32_e32 v2, 0xbfb8aa3b, v2
	v_exp_f32_e32 v2, v2
	v_and_b32_e32 v135, 0xffff0000, v179
	v_max_f32_e32 v135, v135, v135
	v_med3_f32 v135, v135, s20, v199
	v_add_f32_e32 v2, 1.0, v2
	v_max_f32_e32 v134, v134, v134
	v_med3_f32 v5, v5, s20, v199
	v_rcp_f32_e32 v174, v2
	v_mul_f32_e32 v2, 0xbfb8aa3b, v135
	v_med3_f32 v134, v134, s20, v199
	v_exp_f32_e32 v135, v2
	v_mul_f32_e32 v2, 0xbfb8aa3b, v5
	v_mul_f32_e32 v134, 0xbfb8aa3b, v134
	v_exp_f32_e32 v2, v2
	v_exp_f32_e32 v164, v134
	v_lshlrev_b32_e32 v134, 16, v179
	v_max_f32_e32 v134, v134, v134
	v_med3_f32 v134, v134, s20, v199
	v_mul_f32_e32 v134, 0xbfb8aa3b, v134
	v_add_f32_e32 v2, 1.0, v2
	v_exp_f32_e32 v134, v134
	v_rcp_f32_e32 v175, v2
	v_lshlrev_b32_e32 v2, 16, v136
	v_max_f32_e32 v2, v2, v2
	v_med3_f32 v2, v2, s20, v199
	v_mul_f32_e32 v2, 0xbfb8aa3b, v2
	v_pk_add_f32 v[134:135], v[134:135], 1.0 op_sel_hi:[1,0]
	v_exp_f32_e32 v2, v2
	v_pk_mul_f32 v[134:135], v[134:135], v[174:175]
	v_pk_add_f32 v[164:165], v[164:165], 1.0 op_sel_hi:[1,0]
	v_pk_mul_f32 v[124:125], v[124:125], v[134:135]
	v_and_b32_e32 v135, 0xffff0000, v180
	v_and_b32_e32 v5, 0xffff0000, v136
	v_max_f32_e32 v135, v135, v135
	v_pk_mul_f32 v[164:165], v[164:165], v[170:171]
	v_max_f32_e32 v5, v5, v5
	v_med3_f32 v135, v135, s20, v199
	v_add_f32_e32 v2, 1.0, v2
	v_pk_mul_f32 v[122:123], v[122:123], v[164:165]
	v_med3_f32 v5, v5, s20, v199
	v_rcp_f32_e32 v164, v2
	v_mul_f32_e32 v2, 0xbfb8aa3b, v135
	v_exp_f32_e32 v135, v2
	v_mul_f32_e32 v2, 0xbfb8aa3b, v5
	v_exp_f32_e32 v2, v2
	v_and_b32_e32 v5, 0xffff0000, v137
	v_max_f32_e32 v5, v5, v5
	v_med3_f32 v5, v5, s20, v199
	v_add_f32_e32 v2, 1.0, v2
	v_rcp_f32_e32 v165, v2
	v_lshlrev_b32_e32 v2, 16, v137
	v_max_f32_e32 v2, v2, v2
	v_med3_f32 v2, v2, s20, v199
	v_mul_f32_e32 v2, 0xbfb8aa3b, v2
	v_exp_f32_e32 v2, v2
	v_and_b32_e32 v137, 0xffff0000, v181
	v_max_f32_e32 v137, v137, v137
	v_med3_f32 v137, v137, s20, v199
	v_add_f32_e32 v2, 1.0, v2
	v_rcp_f32_e32 v170, v2
	v_mul_f32_e32 v2, 0xbfb8aa3b, v137
	v_exp_f32_e32 v137, v2
	v_mul_f32_e32 v2, 0xbfb8aa3b, v5
	v_lshlrev_b32_e32 v134, 16, v180
	v_lshlrev_b32_e32 v136, 16, v181
	v_exp_f32_e32 v2, v2
	v_max_f32_e32 v134, v134, v134
	v_max_f32_e32 v136, v136, v136
	v_med3_f32 v134, v134, s20, v199
	v_med3_f32 v136, v136, s20, v199
	v_mul_f32_e32 v134, 0xbfb8aa3b, v134
	v_mul_f32_e32 v136, 0xbfb8aa3b, v136
	v_exp_f32_e32 v134, v134
	v_exp_f32_e32 v136, v136
	v_add_f32_e32 v2, 1.0, v2
	v_rcp_f32_e32 v171, v2
	v_pk_add_f32 v[134:135], v[134:135], 1.0 op_sel_hi:[1,0]
	v_pk_add_f32 v[136:137], v[136:137], 1.0 op_sel_hi:[1,0]
	v_pk_mul_f32 v[134:135], v[134:135], v[164:165]
	v_pk_mul_f32 v[136:137], v[136:137], v[170:171]
	v_pk_mul_f32 v[118:119], v[118:119], v[134:135]
	v_pk_mul_f32 v[120:121], v[120:121], v[136:137]
	s_nop 0
	s_waitcnt vmcnt(9)
	v_mov_b64_e32 v[134:135], v[238:239]
	v_mov_b64_e32 v[136:137], v[240:241]
	v_add_u32_e32 v213, 0x80, v4
	v_mad_i64_i32 v[246:247], s[26:27], v213, s25, v[162:163]
	v_lshl_add_u64 v[246:247], v[246:247], 0, v[154:155]
	global_load_dwordx4 v[238:241], v[246:247], off
	s_waitcnt vmcnt(9)
	v_mov_b64_e32 v[138:139], v[242:243]
	v_mov_b64_e32 v[140:141], v[244:245]
	v_add_u32_e32 v213, 0x80, v4
	v_mad_i64_i32 v[248:249], s[26:27], v213, s25, v[160:161]
	v_lshl_add_u64 v[248:249], v[248:249], 0, v[154:155]
	global_load_dwordx4 v[242:245], v[248:249], off
	v_lshlrev_b32_e32 v2, 16, v138
	v_max_f32_e32 v2, v2, v2
	v_med3_f32 v2, v2, s20, v199
	v_mul_f32_e32 v2, 0xbfb8aa3b, v2
	v_exp_f32_e32 v2, v2
	v_and_b32_e32 v5, 0xffff0000, v138
	v_lshlrev_b32_e32 v138, 16, v134
	v_and_b32_e32 v134, 0xffff0000, v134
	v_max_f32_e32 v134, v134, v134
	v_max_f32_e32 v5, v5, v5
	v_med3_f32 v134, v134, s20, v199
	v_add_f32_e32 v2, 1.0, v2
	v_med3_f32 v5, v5, s20, v199
	v_rcp_f32_e32 v170, v2
	v_mul_f32_e32 v2, 0xbfb8aa3b, v134
	v_exp_f32_e32 v165, v2
	v_mul_f32_e32 v2, 0xbfb8aa3b, v5
	v_exp_f32_e32 v2, v2
	v_max_f32_e32 v138, v138, v138
	v_lshlrev_b32_e32 v134, 16, v135
	v_and_b32_e32 v135, 0xffff0000, v135
	v_add_f32_e32 v2, 1.0, v2
	v_rcp_f32_e32 v171, v2
	v_lshlrev_b32_e32 v2, 16, v139
	v_max_f32_e32 v2, v2, v2
	v_med3_f32 v2, v2, s20, v199
	v_mul_f32_e32 v2, 0xbfb8aa3b, v2
	v_exp_f32_e32 v2, v2
	v_med3_f32 v138, v138, s20, v199
	v_and_b32_e32 v5, 0xffff0000, v139
	v_max_f32_e32 v135, v135, v135
	v_mul_f32_e32 v138, 0xbfb8aa3b, v138
	v_max_f32_e32 v5, v5, v5
	v_med3_f32 v135, v135, s20, v199
	v_add_f32_e32 v2, 1.0, v2
	v_exp_f32_e32 v164, v138
	v_med3_f32 v5, v5, s20, v199
	v_rcp_f32_e32 v138, v2
	v_mul_f32_e32 v2, 0xbfb8aa3b, v135
	v_exp_f32_e32 v135, v2
	v_mul_f32_e32 v2, 0xbfb8aa3b, v5
	v_exp_f32_e32 v2, v2
	v_max_f32_e32 v134, v134, v134
	v_med3_f32 v134, v134, s20, v199
;     __device__ __forceinline__ void operator()(f32x4 (&acc)[2][2][4][2], const Unit& u, int wr, int wc, int fr, int fq) const {
;     ...
;             for (int st = 0; st < 16; ++st) { const int ai = st >> 3, m = (st >> 1) & 3, bj = st & 1;
;                 const size_t r = (size_t)(row0 + ai * HALF + m * 16); const int c = col0 + bj * HALF;
;                 const u32x4 ga = *(const u32x4*)(za + r * ldz + c), gb = *(const u32x4*)(zb + r * ldz + c);
; #pragma unroll
;                 for (int j = 0; j < 4; ++j) { const unsigned wa = ga[j], wb = gb[j];
;                     const float a0 = fminf(fmaxf(__uint_as_float(wa << 16), -30.f), 30.f), a1 = fminf(fmaxf(__uint_as_float(wa & 0xffff0000u), -30.f), 30.f);
;                     const float b0 = fminf(fmaxf(__uint_as_float(wb << 16), -30.f), 30.f), b1 = fminf(fmaxf(__uint_as_float(wb & 0xffff0000u), -30.f), 30.f);
;                     const float r0 = (1.f + __expf(-b0)) * __builtin_amdgcn_rcpf(1.f + __expf(-a0)), r1 = (1.f + __expf(-b1)) * __builtin_amdgcn_rcpf(1.f + __expf(-a1));
;                     acc[ai][bj][m][j >> 1][(j & 1) * 2] *= r0; acc[ai][bj][m][j >> 1][(j & 1) * 2 + 1] *= r1; }
;                 if ((st & 3) == 3) asm volatile("" ::: "memory"); }
	v_mul_f32_e32 v134, 0xbfb8aa3b, v134
	v_add_f32_e32 v2, 1.0, v2
	v_exp_f32_e32 v134, v134
	v_rcp_f32_e32 v139, v2
	v_lshlrev_b32_e32 v2, 16, v140
	v_max_f32_e32 v2, v2, v2
	v_med3_f32 v2, v2, s20, v199
	v_mul_f32_e32 v2, 0xbfb8aa3b, v2
	v_pk_add_f32 v[134:135], v[134:135], 1.0 op_sel_hi:[1,0]
	v_exp_f32_e32 v2, v2
	v_pk_mul_f32 v[134:135], v[134:135], v[138:139]
	v_and_b32_e32 v5, 0xffff0000, v140
	v_pk_mul_f32 v[92:93], v[92:93], v[134:135]
	v_and_b32_e32 v135, 0xffff0000, v136
	v_max_f32_e32 v135, v135, v135
	v_max_f32_e32 v5, v5, v5
	v_med3_f32 v135, v135, s20, v199
	v_add_f32_e32 v2, 1.0, v2
	v_med3_f32 v5, v5, s20, v199
	v_rcp_f32_e32 v138, v2
	v_mul_f32_e32 v2, 0xbfb8aa3b, v135
	v_exp_f32_e32 v135, v2
	v_mul_f32_e32 v2, 0xbfb8aa3b, v5
	v_exp_f32_e32 v2, v2
	v_lshlrev_b32_e32 v134, 16, v136
	v_lshlrev_b32_e32 v136, 16, v137
	v_and_b32_e32 v137, 0xffff0000, v137
	v_add_f32_e32 v2, 1.0, v2
	v_rcp_f32_e32 v139, v2
	v_lshlrev_b32_e32 v2, 16, v141
	v_max_f32_e32 v2, v2, v2
	v_med3_f32 v2, v2, s20, v199
	v_mul_f32_e32 v2, 0xbfb8aa3b, v2
	v_exp_f32_e32 v2, v2
	v_and_b32_e32 v5, 0xffff0000, v141
	v_max_f32_e32 v137, v137, v137
	v_max_f32_e32 v5, v5, v5
	v_med3_f32 v137, v137, s20, v199
	v_add_f32_e32 v2, 1.0, v2
	v_med3_f32 v5, v5, s20, v199
	v_rcp_f32_e32 v140, v2
	v_mul_f32_e32 v2, 0xbfb8aa3b, v137
	v_max_f32_e32 v134, v134, v134
	v_exp_f32_e32 v137, v2
	v_mul_f32_e32 v2, 0xbfb8aa3b, v5
	v_med3_f32 v134, v134, s20, v199
	v_exp_f32_e32 v2, v2
	v_mul_f32_e32 v134, 0xbfb8aa3b, v134
	v_max_f32_e32 v136, v136, v136
	v_exp_f32_e32 v134, v134
	v_med3_f32 v136, v136, s20, v199
	v_mul_f32_e32 v136, 0xbfb8aa3b, v136
	v_exp_f32_e32 v136, v136
	v_add_f32_e32 v2, 1.0, v2
	v_rcp_f32_e32 v141, v2
	v_pk_add_f32 v[134:135], v[134:135], 1.0 op_sel_hi:[1,0]
	v_pk_add_f32 v[136:137], v[136:137], 1.0 op_sel_hi:[1,0]
	v_pk_mul_f32 v[134:135], v[134:135], v[138:139]
	v_pk_mul_f32 v[136:137], v[136:137], v[140:141]
	v_pk_mul_f32 v[86:87], v[86:87], v[134:135]
	v_mad_i64_i32 v[134:135], s[26:27], v158, s25, v[162:163]
	v_lshl_add_u64 v[138:139], v[134:135], 0, v[154:155]
	v_pk_mul_f32 v[88:89], v[88:89], v[136:137]
	v_mad_i64_i32 v[140:141], s[26:27], v158, s25, v[160:161]
	v_lshl_add_u64 v[140:141], v[140:141], 0, v[154:155]
	v_pk_add_f32 v[164:165], v[164:165], 1.0 op_sel_hi:[1,0]
	s_waitcnt vmcnt(9)
	v_mov_b64_e32 v[134:135], v[204:205]
	v_mov_b64_e32 v[136:137], v[206:207]
	v_add_u32_e32 v213, 0x80, v4
	v_mad_i64_i32 v[246:247], s[26:27], v213, s25, v[160:161]
	v_lshl_add_u64 v[246:247], v[246:247], 0, v[154:155]
	global_load_dwordx4 v[204:207], v[246:247], off offset:256
	v_lshlrev_b32_e32 v2, 16, v134
	v_max_f32_e32 v2, v2, v2
	v_med3_f32 v2, v2, s20, v199
	v_mul_f32_e32 v2, 0xbfb8aa3b, v2
	v_exp_f32_e32 v2, v2
	s_waitcnt vmcnt(9)
	v_mov_b64_e32 v[178:179], v[208:209]
	v_mov_b64_e32 v[180:181], v[210:211]
	v_add_u32_e32 v213, 0x80, v4
	v_mad_i64_i32 v[248:249], s[26:27], v213, s25, v[162:163]
	v_lshl_add_u64 v[248:249], v[248:249], 0, v[154:155]
	global_load_dwordx4 v[208:211], v[248:249], off offset:256
	v_and_b32_e32 v157, 0xffff0000, v178
	v_and_b32_e32 v5, 0xffff0000, v134
	v_max_f32_e32 v157, v157, v157
	v_pk_mul_f32 v[164:165], v[164:165], v[170:171]
	v_max_f32_e32 v5, v5, v5
	v_med3_f32 v157, v157, s20, v199
	v_add_f32_e32 v2, 1.0, v2
	v_pk_mul_f32 v[90:91], v[90:91], v[164:165]
	v_med3_f32 v5, v5, s20, v199
	v_rcp_f32_e32 v164, v2
	v_mul_f32_e32 v2, 0xbfb8aa3b, v157
	v_exp_f32_e32 v159, v2
	v_mul_f32_e32 v2, 0xbfb8aa3b, v5
	v_exp_f32_e32 v2, v2
	v_and_b32_e32 v5, 0xffff0000, v135
	v_lshlrev_b32_e32 v134, 16, v178
	v_max_f32_e32 v5, v5, v5
	v_add_f32_e32 v2, 1.0, v2
	v_rcp_f32_e32 v165, v2
	v_lshlrev_b32_e32 v2, 16, v135
	v_max_f32_e32 v2, v2, v2
	v_med3_f32 v2, v2, s20, v199
	v_mul_f32_e32 v2, 0xbfb8aa3b, v2
	v_exp_f32_e32 v2, v2
	v_and_b32_e32 v135, 0xffff0000, v179
	v_max_f32_e32 v135, v135, v135
	v_med3_f32 v135, v135, s20, v199
	v_add_f32_e32 v2, 1.0, v2
	v_max_f32_e32 v134, v134, v134
	v_med3_f32 v5, v5, s20, v199
	v_rcp_f32_e32 v170, v2
	v_mul_f32_e32 v2, 0xbfb8aa3b, v135
	v_med3_f32 v134, v134, s20, v199
	v_exp_f32_e32 v135, v2
	v_mul_f32_e32 v2, 0xbfb8aa3b, v5
	v_mul_f32_e32 v134, 0xbfb8aa3b, v134
	v_exp_f32_e32 v2, v2
	v_exp_f32_e32 v158, v134
	v_lshlrev_b32_e32 v134, 16, v179
	v_max_f32_e32 v134, v134, v134
	v_med3_f32 v134, v134, s20, v199
	v_mul_f32_e32 v134, 0xbfb8aa3b, v134
	v_add_f32_e32 v2, 1.0, v2
	v_exp_f32_e32 v134, v134
	v_rcp_f32_e32 v171, v2
	v_lshlrev_b32_e32 v2, 16, v136
	v_max_f32_e32 v2, v2, v2
	v_med3_f32 v2, v2, s20, v199
	v_mul_f32_e32 v2, 0xbfb8aa3b, v2
	v_pk_add_f32 v[134:135], v[134:135], 1.0 op_sel_hi:[1,0]
	v_exp_f32_e32 v2, v2
	v_pk_mul_f32 v[134:135], v[134:135], v[170:171]
	v_pk_add_f32 v[158:159], v[158:159], 1.0 op_sel_hi:[1,0]
	v_pk_mul_f32 v[116:117], v[116:117], v[134:135]
	v_and_b32_e32 v135, 0xffff0000, v180
	v_and_b32_e32 v5, 0xffff0000, v136
	v_max_f32_e32 v135, v135, v135
	v_pk_mul_f32 v[158:159], v[158:159], v[164:165]
	v_max_f32_e32 v5, v5, v5
	v_med3_f32 v135, v135, s20, v199
	v_add_f32_e32 v2, 1.0, v2
	v_pk_mul_f32 v[114:115], v[114:115], v[158:159]
	v_med3_f32 v5, v5, s20, v199
	v_rcp_f32_e32 v158, v2
	v_mul_f32_e32 v2, 0xbfb8aa3b, v135
	v_exp_f32_e32 v135, v2
	v_mul_f32_e32 v2, 0xbfb8aa3b, v5
	v_exp_f32_e32 v2, v2
	v_and_b32_e32 v5, 0xffff0000, v137
	v_max_f32_e32 v5, v5, v5
	v_med3_f32 v5, v5, s20, v199
	v_add_f32_e32 v2, 1.0, v2
	v_rcp_f32_e32 v159, v2
	v_lshlrev_b32_e32 v2, 16, v137
	v_max_f32_e32 v2, v2, v2
	v_med3_f32 v2, v2, s20, v199
	v_mul_f32_e32 v2, 0xbfb8aa3b, v2
	v_exp_f32_e32 v2, v2
	v_and_b32_e32 v137, 0xffff0000, v181
	v_max_f32_e32 v137, v137, v137
	v_med3_f32 v137, v137, s20, v199
	v_add_f32_e32 v2, 1.0, v2
	v_rcp_f32_e32 v164, v2
	v_mul_f32_e32 v2, 0xbfb8aa3b, v137
	v_exp_f32_e32 v137, v2
	v_mul_f32_e32 v2, 0xbfb8aa3b, v5
	v_lshlrev_b32_e32 v134, 16, v180
	v_lshlrev_b32_e32 v136, 16, v181
	v_exp_f32_e32 v2, v2
	v_max_f32_e32 v134, v134, v134
	v_max_f32_e32 v136, v136, v136
	v_med3_f32 v134, v134, s20, v199
	v_med3_f32 v136, v136, s20, v199
	v_mul_f32_e32 v134, 0xbfb8aa3b, v134
	v_mul_f32_e32 v136, 0xbfb8aa3b, v136
	v_exp_f32_e32 v134, v134
	v_exp_f32_e32 v136, v136
	v_add_f32_e32 v2, 1.0, v2
	v_rcp_f32_e32 v165, v2
	v_pk_add_f32 v[134:135], v[134:135], 1.0 op_sel_hi:[1,0]
	v_pk_add_f32 v[136:137], v[136:137], 1.0 op_sel_hi:[1,0]
	v_pk_mul_f32 v[134:135], v[134:135], v[158:159]
	v_pk_mul_f32 v[136:137], v[136:137], v[164:165]
	v_pk_mul_f32 v[110:111], v[110:111], v[134:135]
	v_pk_mul_f32 v[112:113], v[112:113], v[136:137]
	s_nop 0
	s_waitcnt vmcnt(9)
;     __device__ __forceinline__ void operator()(f32x4 (&acc)[2][2][4][2], const Unit& u, int wr, int wc, int fr, int fq) const {
;     ...
;             for (int st = 0; st < 16; ++st) { const int ai = st >> 3, m = (st >> 1) & 3, bj = st & 1;
;                 const size_t r = (size_t)(row0 + ai * HALF + m * 16); const int c = col0 + bj * HALF;
;                 const u32x4 ga = *(const u32x4*)(za + r * ldz + c), gb = *(const u32x4*)(zb + r * ldz + c);
; #pragma unroll
;                 for (int j = 0; j < 4; ++j) { const unsigned wa = ga[j], wb = gb[j];
;                     const float a0 = fminf(fmaxf(__uint_as_float(wa << 16), -30.f), 30.f), a1 = fminf(fmaxf(__uint_as_float(wa & 0xffff0000u), -30.f), 30.f);
;                     const float b0 = fminf(fmaxf(__uint_as_float(wb << 16), -30.f), 30.f), b1 = fminf(fmaxf(__uint_as_float(wb & 0xffff0000u), -30.f), 30.f);
;                     const float r0 = (1.f + __expf(-b0)) * __builtin_amdgcn_rcpf(1.f + __expf(-a0)), r1 = (1.f + __expf(-b1)) * __builtin_amdgcn_rcpf(1.f + __expf(-a1));
;                     acc[ai][bj][m][j >> 1][(j & 1) * 2] *= r0; acc[ai][bj][m][j >> 1][(j & 1) * 2 + 1] *= r1; }
;                 if ((st & 3) == 3) asm volatile("" ::: "memory"); }
	v_mov_b64_e32 v[134:135], v[214:215]
	v_mov_b64_e32 v[136:137], v[216:217]
	v_add_u32_e32 v213, 0x90, v4
	v_mad_i64_i32 v[246:247], s[26:27], v213, s25, v[162:163]
	v_lshl_add_u64 v[246:247], v[246:247], 0, v[154:155]
	global_load_dwordx4 v[214:217], v[246:247], off
	s_waitcnt vmcnt(9)
	v_mov_b64_e32 v[138:139], v[218:219]
	v_mov_b64_e32 v[140:141], v[220:221]
	v_add_u32_e32 v213, 0x90, v4
	v_mad_i64_i32 v[248:249], s[26:27], v213, s25, v[160:161]
	v_lshl_add_u64 v[248:249], v[248:249], 0, v[154:155]
	global_load_dwordx4 v[218:221], v[248:249], off
	v_lshlrev_b32_e32 v2, 16, v138
	v_max_f32_e32 v2, v2, v2
	v_med3_f32 v2, v2, s20, v199
	v_mul_f32_e32 v2, 0xbfb8aa3b, v2
	v_exp_f32_e32 v2, v2
	v_and_b32_e32 v5, 0xffff0000, v138
	v_lshlrev_b32_e32 v138, 16, v134
	v_and_b32_e32 v134, 0xffff0000, v134
	v_max_f32_e32 v134, v134, v134
	v_max_f32_e32 v5, v5, v5
	v_med3_f32 v134, v134, s20, v199
	v_add_f32_e32 v2, 1.0, v2
	v_med3_f32 v5, v5, s20, v199
	v_rcp_f32_e32 v164, v2
	v_mul_f32_e32 v2, 0xbfb8aa3b, v134
	v_exp_f32_e32 v159, v2
	v_mul_f32_e32 v2, 0xbfb8aa3b, v5
	v_exp_f32_e32 v2, v2
	v_max_f32_e32 v138, v138, v138
	v_lshlrev_b32_e32 v134, 16, v135
	v_and_b32_e32 v135, 0xffff0000, v135
	v_add_f32_e32 v2, 1.0, v2
	v_rcp_f32_e32 v165, v2
	v_lshlrev_b32_e32 v2, 16, v139
	v_max_f32_e32 v2, v2, v2
	v_med3_f32 v2, v2, s20, v199
	v_mul_f32_e32 v2, 0xbfb8aa3b, v2
	v_exp_f32_e32 v2, v2
	v_med3_f32 v138, v138, s20, v199
	v_and_b32_e32 v5, 0xffff0000, v139
	v_max_f32_e32 v135, v135, v135
	v_mul_f32_e32 v138, 0xbfb8aa3b, v138
	v_max_f32_e32 v5, v5, v5
	v_med3_f32 v135, v135, s20, v199
	v_add_f32_e32 v2, 1.0, v2
	v_exp_f32_e32 v158, v138
	v_med3_f32 v5, v5, s20, v199
	v_rcp_f32_e32 v138, v2
	v_mul_f32_e32 v2, 0xbfb8aa3b, v135
	v_exp_f32_e32 v135, v2
	v_mul_f32_e32 v2, 0xbfb8aa3b, v5
	v_exp_f32_e32 v2, v2
	v_max_f32_e32 v134, v134, v134
	v_med3_f32 v134, v134, s20, v199
	v_mul_f32_e32 v134, 0xbfb8aa3b, v134
	v_add_f32_e32 v2, 1.0, v2
	v_exp_f32_e32 v134, v134
	v_rcp_f32_e32 v139, v2
	v_lshlrev_b32_e32 v2, 16, v140
	v_max_f32_e32 v2, v2, v2
	v_med3_f32 v2, v2, s20, v199
	v_mul_f32_e32 v2, 0xbfb8aa3b, v2
	v_pk_add_f32 v[134:135], v[134:135], 1.0 op_sel_hi:[1,0]
	v_exp_f32_e32 v2, v2
	v_pk_mul_f32 v[134:135], v[134:135], v[138:139]
	v_and_b32_e32 v5, 0xffff0000, v140
	v_pk_mul_f32 v[84:85], v[84:85], v[134:135]
	v_and_b32_e32 v135, 0xffff0000, v136
	v_max_f32_e32 v135, v135, v135
	v_max_f32_e32 v5, v5, v5
	v_med3_f32 v135, v135, s20, v199
	v_add_f32_e32 v2, 1.0, v2
	v_med3_f32 v5, v5, s20, v199
	v_rcp_f32_e32 v138, v2
	v_mul_f32_e32 v2, 0xbfb8aa3b, v135
	v_exp_f32_e32 v135, v2
	v_mul_f32_e32 v2, 0xbfb8aa3b, v5
	v_exp_f32_e32 v2, v2
	v_lshlrev_b32_e32 v134, 16, v136
	v_lshlrev_b32_e32 v136, 16, v137
	v_and_b32_e32 v137, 0xffff0000, v137
	v_add_f32_e32 v2, 1.0, v2
	v_rcp_f32_e32 v139, v2
	v_lshlrev_b32_e32 v2, 16, v141
	v_max_f32_e32 v2, v2, v2
	v_med3_f32 v2, v2, s20, v199
	v_mul_f32_e32 v2, 0xbfb8aa3b, v2
	v_exp_f32_e32 v2, v2
	v_and_b32_e32 v5, 0xffff0000, v141
	v_max_f32_e32 v137, v137, v137
	v_max_f32_e32 v5, v5, v5
	v_med3_f32 v137, v137, s20, v199
	v_add_f32_e32 v2, 1.0, v2
	v_med3_f32 v5, v5, s20, v199
	v_rcp_f32_e32 v140, v2
	v_mul_f32_e32 v2, 0xbfb8aa3b, v137
	v_max_f32_e32 v134, v134, v134
	v_exp_f32_e32 v137, v2
	v_mul_f32_e32 v2, 0xbfb8aa3b, v5
	v_med3_f32 v134, v134, s20, v199
	v_exp_f32_e32 v2, v2
	v_mul_f32_e32 v134, 0xbfb8aa3b, v134
	v_max_f32_e32 v136, v136, v136
	v_exp_f32_e32 v134, v134
	v_med3_f32 v136, v136, s20, v199
	v_mul_f32_e32 v136, 0xbfb8aa3b, v136
	v_exp_f32_e32 v136, v136
	v_add_f32_e32 v2, 1.0, v2
	v_rcp_f32_e32 v141, v2
	v_pk_add_f32 v[134:135], v[134:135], 1.0 op_sel_hi:[1,0]
	v_pk_add_f32 v[136:137], v[136:137], 1.0 op_sel_hi:[1,0]
	v_pk_mul_f32 v[134:135], v[134:135], v[138:139]
	v_pk_mul_f32 v[136:137], v[136:137], v[140:141]
	v_pk_mul_f32 v[78:79], v[78:79], v[134:135]
	v_mad_i64_i32 v[134:135], s[26:27], v156, s25, v[162:163]
	v_lshl_add_u64 v[138:139], v[134:135], 0, v[154:155]
	v_pk_mul_f32 v[80:81], v[80:81], v[136:137]
	v_pk_add_f32 v[158:159], v[158:159], 1.0 op_sel_hi:[1,0]
	v_mad_i64_i32 v[140:141], s[26:27], v156, s25, v[160:161]
	v_pk_mul_f32 v[158:159], v[158:159], v[164:165]
	v_lshl_add_u64 v[140:141], v[140:141], 0, v[154:155]
	v_pk_mul_f32 v[82:83], v[82:83], v[158:159]
	s_waitcnt vmcnt(9)
	v_mov_b64_e32 v[134:135], v[222:223]
	v_mov_b64_e32 v[136:137], v[224:225]
	v_add_u32_e32 v213, 0x90, v4
	v_mad_i64_i32 v[246:247], s[26:27], v213, s25, v[160:161]
	v_lshl_add_u64 v[246:247], v[246:247], 0, v[154:155]
	global_load_dwordx4 v[222:225], v[246:247], off offset:256
	v_lshlrev_b32_e32 v2, 16, v134
	v_max_f32_e32 v2, v2, v2
	v_med3_f32 v2, v2, s20, v199
	v_mul_f32_e32 v2, 0xbfb8aa3b, v2
	v_exp_f32_e32 v2, v2
	v_and_b32_e32 v5, 0xffff0000, v134
	v_max_f32_e32 v5, v5, v5
	s_waitcnt vmcnt(9)
;     __device__ __forceinline__ void operator()(f32x4 (&acc)[2][2][4][2], const Unit& u, int wr, int wc, int fr, int fq) const {
;     ...
;             for (int st = 0; st < 16; ++st) { const int ai = st >> 3, m = (st >> 1) & 3, bj = st & 1;
;                 const size_t r = (size_t)(row0 + ai * HALF + m * 16); const int c = col0 + bj * HALF;
;                 const u32x4 ga = *(const u32x4*)(za + r * ldz + c), gb = *(const u32x4*)(zb + r * ldz + c);
; #pragma unroll
;                 for (int j = 0; j < 4; ++j) { const unsigned wa = ga[j], wb = gb[j];
;                     const float a0 = fminf(fmaxf(__uint_as_float(wa << 16), -30.f), 30.f), a1 = fminf(fmaxf(__uint_as_float(wa & 0xffff0000u), -30.f), 30.f);
;                     const float b0 = fminf(fmaxf(__uint_as_float(wb << 16), -30.f), 30.f), b1 = fminf(fmaxf(__uint_as_float(wb & 0xffff0000u), -30.f), 30.f);
;                     const float r0 = (1.f + __expf(-b0)) * __builtin_amdgcn_rcpf(1.f + __expf(-a0)), r1 = (1.f + __expf(-b1)) * __builtin_amdgcn_rcpf(1.f + __expf(-a1));
;                     acc[ai][bj][m][j >> 1][(j & 1) * 2] *= r0; acc[ai][bj][m][j >> 1][(j & 1) * 2 + 1] *= r1; }
;                 if ((st & 3) == 3) asm volatile("" ::: "memory"); }
	v_mov_b64_e32 v[156:157], v[226:227]
	v_mov_b64_e32 v[158:159], v[228:229]
	v_add_u32_e32 v213, 0x90, v4
	v_mad_i64_i32 v[248:249], s[26:27], v213, s25, v[162:163]
	v_lshl_add_u64 v[248:249], v[248:249], 0, v[154:155]
	global_load_dwordx4 v[226:229], v[248:249], off offset:256
	v_lshlrev_b32_e32 v134, 16, v156
	v_and_b32_e32 v156, 0xffff0000, v156
	v_max_f32_e32 v156, v156, v156
	v_med3_f32 v156, v156, s20, v199
	v_add_f32_e32 v2, 1.0, v2
	v_med3_f32 v5, v5, s20, v199
	v_rcp_f32_e32 v170, v2
	v_mul_f32_e32 v2, 0xbfb8aa3b, v156
	v_exp_f32_e32 v165, v2
	v_mul_f32_e32 v2, 0xbfb8aa3b, v5
	v_exp_f32_e32 v2, v2
	v_and_b32_e32 v5, 0xffff0000, v135
	v_max_f32_e32 v5, v5, v5
	v_max_f32_e32 v134, v134, v134
	v_add_f32_e32 v2, 1.0, v2
	v_rcp_f32_e32 v171, v2
	v_lshlrev_b32_e32 v2, 16, v135
	v_max_f32_e32 v2, v2, v2
	v_med3_f32 v2, v2, s20, v199
	v_mul_f32_e32 v2, 0xbfb8aa3b, v2
	v_exp_f32_e32 v2, v2
	v_and_b32_e32 v135, 0xffff0000, v157
	v_max_f32_e32 v135, v135, v135
	v_med3_f32 v135, v135, s20, v199
	v_add_f32_e32 v2, 1.0, v2
	v_med3_f32 v5, v5, s20, v199
	v_rcp_f32_e32 v156, v2
	v_mul_f32_e32 v2, 0xbfb8aa3b, v135
	v_med3_f32 v134, v134, s20, v199
	v_exp_f32_e32 v135, v2
	v_mul_f32_e32 v2, 0xbfb8aa3b, v5
	v_mul_f32_e32 v134, 0xbfb8aa3b, v134
	v_exp_f32_e32 v2, v2
	v_exp_f32_e32 v164, v134
	v_lshlrev_b32_e32 v134, 16, v157
	v_max_f32_e32 v134, v134, v134
	v_med3_f32 v134, v134, s20, v199
	v_mul_f32_e32 v134, 0xbfb8aa3b, v134
	v_add_f32_e32 v2, 1.0, v2
	v_exp_f32_e32 v134, v134
	v_rcp_f32_e32 v157, v2
	v_lshlrev_b32_e32 v2, 16, v136
	v_max_f32_e32 v2, v2, v2
	v_med3_f32 v2, v2, s20, v199
	v_mul_f32_e32 v2, 0xbfb8aa3b, v2
	v_pk_add_f32 v[134:135], v[134:135], 1.0 op_sel_hi:[1,0]
	v_exp_f32_e32 v2, v2
	v_pk_mul_f32 v[134:135], v[134:135], v[156:157]
	v_and_b32_e32 v5, 0xffff0000, v136
	v_pk_mul_f32 v[108:109], v[108:109], v[134:135]
	v_and_b32_e32 v135, 0xffff0000, v158
	v_max_f32_e32 v135, v135, v135
	v_max_f32_e32 v5, v5, v5
	v_med3_f32 v135, v135, s20, v199
	v_add_f32_e32 v2, 1.0, v2
	v_med3_f32 v5, v5, s20, v199
	v_rcp_f32_e32 v156, v2
	v_mul_f32_e32 v2, 0xbfb8aa3b, v135
	v_exp_f32_e32 v135, v2
	v_mul_f32_e32 v2, 0xbfb8aa3b, v5
	v_exp_f32_e32 v2, v2
	v_and_b32_e32 v5, 0xffff0000, v137
	v_max_f32_e32 v5, v5, v5
	v_lshlrev_b32_e32 v134, 16, v158
	v_add_f32_e32 v2, 1.0, v2
	v_rcp_f32_e32 v157, v2
	v_lshlrev_b32_e32 v2, 16, v137
	v_max_f32_e32 v2, v2, v2
	v_med3_f32 v2, v2, s20, v199
	v_mul_f32_e32 v2, 0xbfb8aa3b, v2
	v_exp_f32_e32 v2, v2
	v_and_b32_e32 v137, 0xffff0000, v159
	v_max_f32_e32 v137, v137, v137
	v_med3_f32 v137, v137, s20, v199
	v_add_f32_e32 v2, 1.0, v2
	v_med3_f32 v5, v5, s20, v199
	v_rcp_f32_e32 v158, v2
	v_mul_f32_e32 v2, 0xbfb8aa3b, v137
	v_exp_f32_e32 v137, v2
	v_mul_f32_e32 v2, 0xbfb8aa3b, v5
	v_lshlrev_b32_e32 v136, 16, v159
	v_exp_f32_e32 v2, v2
	v_max_f32_e32 v134, v134, v134
	v_max_f32_e32 v136, v136, v136
	v_med3_f32 v134, v134, s20, v199
	v_med3_f32 v136, v136, s20, v199
	v_mul_f32_e32 v134, 0xbfb8aa3b, v134
	v_mul_f32_e32 v136, 0xbfb8aa3b, v136
	v_exp_f32_e32 v134, v134
	v_exp_f32_e32 v136, v136
	v_add_f32_e32 v2, 1.0, v2
	v_rcp_f32_e32 v159, v2
	v_pk_add_f32 v[134:135], v[134:135], 1.0 op_sel_hi:[1,0]
	v_pk_add_f32 v[136:137], v[136:137], 1.0 op_sel_hi:[1,0]
	v_pk_mul_f32 v[134:135], v[134:135], v[156:157]
	v_pk_mul_f32 v[136:137], v[136:137], v[158:159]
	v_pk_mul_f32 v[102:103], v[102:103], v[134:135]
	v_pk_mul_f32 v[104:105], v[104:105], v[136:137]
	s_nop 0
	v_pk_add_f32 v[164:165], v[164:165], 1.0 op_sel_hi:[1,0]
	s_waitcnt vmcnt(9)
	v_mov_b64_e32 v[134:135], v[230:231]
	v_mov_b64_e32 v[136:137], v[232:233]
	v_add_u32_e32 v213, 0xa0, v4
	v_mad_i64_i32 v[246:247], s[26:27], v213, s25, v[162:163]
	v_lshl_add_u64 v[246:247], v[246:247], 0, v[154:155]
	global_load_dwordx4 v[230:233], v[246:247], off
	s_waitcnt vmcnt(9)
	v_mov_b64_e32 v[138:139], v[234:235]
	v_mov_b64_e32 v[140:141], v[236:237]
	v_add_u32_e32 v213, 0xa0, v4
	v_mad_i64_i32 v[248:249], s[26:27], v213, s25, v[160:161]
	v_lshl_add_u64 v[248:249], v[248:249], 0, v[154:155]
	global_load_dwordx4 v[234:237], v[248:249], off
	v_lshlrev_b32_e32 v2, 16, v138
	v_max_f32_e32 v2, v2, v2
	v_med3_f32 v2, v2, s20, v199
	v_mul_f32_e32 v2, 0xbfb8aa3b, v2
	v_exp_f32_e32 v2, v2
	v_and_b32_e32 v5, 0xffff0000, v138
	v_lshlrev_b32_e32 v138, 16, v134
	v_and_b32_e32 v134, 0xffff0000, v134
	v_max_f32_e32 v134, v134, v134
	v_max_f32_e32 v5, v5, v5
	v_med3_f32 v134, v134, s20, v199
	v_add_f32_e32 v2, 1.0, v2
	v_med3_f32 v5, v5, s20, v199
	v_rcp_f32_e32 v158, v2
	v_mul_f32_e32 v2, 0xbfb8aa3b, v134
	v_exp_f32_e32 v157, v2
	v_mul_f32_e32 v2, 0xbfb8aa3b, v5
	v_exp_f32_e32 v2, v2
	v_max_f32_e32 v138, v138, v138
	v_lshlrev_b32_e32 v134, 16, v135
	v_and_b32_e32 v135, 0xffff0000, v135
	v_add_f32_e32 v2, 1.0, v2
	v_rcp_f32_e32 v159, v2
	v_lshlrev_b32_e32 v2, 16, v139
	v_max_f32_e32 v2, v2, v2
	v_med3_f32 v2, v2, s20, v199
	v_mul_f32_e32 v2, 0xbfb8aa3b, v2
	v_exp_f32_e32 v2, v2
	v_med3_f32 v138, v138, s20, v199
	v_and_b32_e32 v5, 0xffff0000, v139
	v_max_f32_e32 v135, v135, v135
	v_mul_f32_e32 v138, 0xbfb8aa3b, v138
	v_max_f32_e32 v5, v5, v5
	v_med3_f32 v135, v135, s20, v199
	v_add_f32_e32 v2, 1.0, v2
	v_exp_f32_e32 v156, v138
	v_med3_f32 v5, v5, s20, v199
	v_rcp_f32_e32 v138, v2
	v_mul_f32_e32 v2, 0xbfb8aa3b, v135
	v_exp_f32_e32 v135, v2
	v_mul_f32_e32 v2, 0xbfb8aa3b, v5
	v_exp_f32_e32 v2, v2
	v_max_f32_e32 v134, v134, v134
	v_med3_f32 v134, v134, s20, v199
	v_mul_f32_e32 v134, 0xbfb8aa3b, v134
	v_add_f32_e32 v2, 1.0, v2
	v_exp_f32_e32 v134, v134
	v_rcp_f32_e32 v139, v2
	v_lshlrev_b32_e32 v2, 16, v140
	v_max_f32_e32 v2, v2, v2
	v_med3_f32 v2, v2, s20, v199
	v_mul_f32_e32 v2, 0xbfb8aa3b, v2
;     __device__ __forceinline__ void operator()(f32x4 (&acc)[2][2][4][2], const Unit& u, int wr, int wc, int fr, int fq) const {
;     ...
;             for (int st = 0; st < 16; ++st) { const int ai = st >> 3, m = (st >> 1) & 3, bj = st & 1;
;                 const size_t r = (size_t)(row0 + ai * HALF + m * 16); const int c = col0 + bj * HALF;
;                 const u32x4 ga = *(const u32x4*)(za + r * ldz + c), gb = *(const u32x4*)(zb + r * ldz + c);
; #pragma unroll
;                 for (int j = 0; j < 4; ++j) { const unsigned wa = ga[j], wb = gb[j];
;                     const float a0 = fminf(fmaxf(__uint_as_float(wa << 16), -30.f), 30.f), a1 = fminf(fmaxf(__uint_as_float(wa & 0xffff0000u), -30.f), 30.f);
;                     const float b0 = fminf(fmaxf(__uint_as_float(wb << 16), -30.f), 30.f), b1 = fminf(fmaxf(__uint_as_float(wb & 0xffff0000u), -30.f), 30.f);
;                     const float r0 = (1.f + __expf(-b0)) * __builtin_amdgcn_rcpf(1.f + __expf(-a0)), r1 = (1.f + __expf(-b1)) * __builtin_amdgcn_rcpf(1.f + __expf(-a1));
;                     acc[ai][bj][m][j >> 1][(j & 1) * 2] *= r0; acc[ai][bj][m][j >> 1][(j & 1) * 2 + 1] *= r1; }
;                 if ((st & 3) == 3) asm volatile("" ::: "memory"); }
	v_pk_add_f32 v[134:135], v[134:135], 1.0 op_sel_hi:[1,0]
	v_exp_f32_e32 v2, v2
	v_pk_mul_f32 v[134:135], v[134:135], v[138:139]
	v_and_b32_e32 v5, 0xffff0000, v140
	v_pk_mul_f32 v[76:77], v[76:77], v[134:135]
	v_and_b32_e32 v135, 0xffff0000, v136
	v_max_f32_e32 v135, v135, v135
	v_max_f32_e32 v5, v5, v5
	v_med3_f32 v135, v135, s20, v199
	v_add_f32_e32 v2, 1.0, v2
	v_med3_f32 v5, v5, s20, v199
	v_rcp_f32_e32 v138, v2
	v_mul_f32_e32 v2, 0xbfb8aa3b, v135
	v_exp_f32_e32 v135, v2
	v_mul_f32_e32 v2, 0xbfb8aa3b, v5
	v_exp_f32_e32 v2, v2
	v_lshlrev_b32_e32 v134, 16, v136
	v_lshlrev_b32_e32 v136, 16, v137
	v_and_b32_e32 v137, 0xffff0000, v137
	v_add_f32_e32 v2, 1.0, v2
	v_rcp_f32_e32 v139, v2
	v_lshlrev_b32_e32 v2, 16, v141
	v_max_f32_e32 v2, v2, v2
	v_med3_f32 v2, v2, s20, v199
	v_mul_f32_e32 v2, 0xbfb8aa3b, v2
	v_exp_f32_e32 v2, v2
	v_and_b32_e32 v5, 0xffff0000, v141
	v_max_f32_e32 v137, v137, v137
	v_max_f32_e32 v5, v5, v5
	v_med3_f32 v137, v137, s20, v199
	v_add_f32_e32 v2, 1.0, v2
	v_med3_f32 v5, v5, s20, v199
	v_rcp_f32_e32 v140, v2
	v_mul_f32_e32 v2, 0xbfb8aa3b, v137
	v_max_f32_e32 v134, v134, v134
	v_exp_f32_e32 v137, v2
	v_mul_f32_e32 v2, 0xbfb8aa3b, v5
	v_med3_f32 v134, v134, s20, v199
	v_exp_f32_e32 v2, v2
	v_mul_f32_e32 v134, 0xbfb8aa3b, v134
	v_max_f32_e32 v136, v136, v136
	v_exp_f32_e32 v134, v134
	v_med3_f32 v136, v136, s20, v199
	v_mul_f32_e32 v136, 0xbfb8aa3b, v136
	v_exp_f32_e32 v136, v136
	v_add_f32_e32 v2, 1.0, v2
	v_rcp_f32_e32 v141, v2
	v_pk_add_f32 v[134:135], v[134:135], 1.0 op_sel_hi:[1,0]
	v_add_u32_e32 v2, 0x80, v4
	v_pk_mul_f32 v[134:135], v[134:135], v[138:139]
	v_pk_add_f32 v[136:137], v[136:137], 1.0 op_sel_hi:[1,0]
	v_pk_mul_f32 v[70:71], v[70:71], v[134:135]
	v_mad_i64_i32 v[134:135], s[26:27], v2, s25, v[162:163]
	v_pk_mul_f32 v[136:137], v[136:137], v[140:141]
	v_lshl_add_u64 v[138:139], v[134:135], 0, v[154:155]
	v_pk_mul_f32 v[72:73], v[72:73], v[136:137]
	v_pk_add_f32 v[156:157], v[156:157], 1.0 op_sel_hi:[1,0]
	v_mad_i64_i32 v[140:141], s[26:27], v2, s25, v[160:161]
	v_pk_mul_f32 v[156:157], v[156:157], v[158:159]
	v_lshl_add_u64 v[140:141], v[140:141], 0, v[154:155]
	v_pk_mul_f32 v[74:75], v[74:75], v[156:157]
	v_pk_mul_f32 v[164:165], v[164:165], v[170:171]
	s_waitcnt vmcnt(9)
	v_mov_b64_e32 v[134:135], v[238:239]
	v_mov_b64_e32 v[136:137], v[240:241]
	v_add_u32_e32 v213, 0xa0, v4
	v_mad_i64_i32 v[246:247], s[26:27], v213, s25, v[160:161]
	v_lshl_add_u64 v[246:247], v[246:247], 0, v[154:155]
	global_load_dwordx4 v[238:241], v[246:247], off offset:256
	v_lshlrev_b32_e32 v2, 16, v134
	v_max_f32_e32 v2, v2, v2
	v_med3_f32 v2, v2, s20, v199
	v_mul_f32_e32 v2, 0xbfb8aa3b, v2
	v_exp_f32_e32 v2, v2
	v_and_b32_e32 v5, 0xffff0000, v134
	v_max_f32_e32 v5, v5, v5
	s_waitcnt vmcnt(9)
	v_mov_b64_e32 v[156:157], v[242:243]
	v_mov_b64_e32 v[158:159], v[244:245]
	v_add_u32_e32 v213, 0xa0, v4
	v_mad_i64_i32 v[248:249], s[26:27], v213, s25, v[162:163]
	v_lshl_add_u64 v[248:249], v[248:249], 0, v[154:155]
	global_load_dwordx4 v[242:245], v[248:249], off offset:256
	v_lshlrev_b32_e32 v134, 16, v156
	v_and_b32_e32 v156, 0xffff0000, v156
	v_max_f32_e32 v156, v156, v156
	v_med3_f32 v156, v156, s20, v199
	v_add_f32_e32 v2, 1.0, v2
	v_med3_f32 v5, v5, s20, v199
	v_rcp_f32_e32 v170, v2
	v_mul_f32_e32 v2, 0xbfb8aa3b, v156
	v_pk_mul_f32 v[106:107], v[106:107], v[164:165]
	v_exp_f32_e32 v165, v2
	v_mul_f32_e32 v2, 0xbfb8aa3b, v5
	v_exp_f32_e32 v2, v2
	v_and_b32_e32 v5, 0xffff0000, v135
	v_max_f32_e32 v5, v5, v5
	v_max_f32_e32 v134, v134, v134
	v_add_f32_e32 v2, 1.0, v2
	v_rcp_f32_e32 v171, v2
	v_lshlrev_b32_e32 v2, 16, v135
	v_max_f32_e32 v2, v2, v2
	v_med3_f32 v2, v2, s20, v199
	v_mul_f32_e32 v2, 0xbfb8aa3b, v2
	v_exp_f32_e32 v2, v2
	v_and_b32_e32 v135, 0xffff0000, v157
	v_max_f32_e32 v135, v135, v135
	v_med3_f32 v135, v135, s20, v199
	v_add_f32_e32 v2, 1.0, v2
	v_med3_f32 v5, v5, s20, v199
	v_rcp_f32_e32 v156, v2
	v_mul_f32_e32 v2, 0xbfb8aa3b, v135
	v_med3_f32 v134, v134, s20, v199
	v_exp_f32_e32 v135, v2
	v_mul_f32_e32 v2, 0xbfb8aa3b, v5
	v_mul_f32_e32 v134, 0xbfb8aa3b, v134
	v_exp_f32_e32 v2, v2
	v_exp_f32_e32 v164, v134
	v_lshlrev_b32_e32 v134, 16, v157
	v_max_f32_e32 v134, v134, v134
	v_med3_f32 v134, v134, s20, v199
	v_mul_f32_e32 v134, 0xbfb8aa3b, v134
	v_add_f32_e32 v2, 1.0, v2
	v_exp_f32_e32 v134, v134
	v_rcp_f32_e32 v157, v2
	v_lshlrev_b32_e32 v2, 16, v136
	v_max_f32_e32 v2, v2, v2
	v_med3_f32 v2, v2, s20, v199
	v_mul_f32_e32 v2, 0xbfb8aa3b, v2
	v_pk_add_f32 v[134:135], v[134:135], 1.0 op_sel_hi:[1,0]
	v_exp_f32_e32 v2, v2
	v_pk_mul_f32 v[134:135], v[134:135], v[156:157]
	v_and_b32_e32 v5, 0xffff0000, v136
	v_pk_mul_f32 v[68:69], v[68:69], v[134:135]
	v_and_b32_e32 v135, 0xffff0000, v158
	v_max_f32_e32 v135, v135, v135
	v_max_f32_e32 v5, v5, v5
	v_med3_f32 v135, v135, s20, v199
	v_add_f32_e32 v2, 1.0, v2
	v_med3_f32 v5, v5, s20, v199
	v_rcp_f32_e32 v156, v2
	v_mul_f32_e32 v2, 0xbfb8aa3b, v135
	v_exp_f32_e32 v135, v2
	v_mul_f32_e32 v2, 0xbfb8aa3b, v5
	v_exp_f32_e32 v2, v2
	v_and_b32_e32 v5, 0xffff0000, v137
	v_max_f32_e32 v5, v5, v5
	v_lshlrev_b32_e32 v134, 16, v158
	v_add_f32_e32 v2, 1.0, v2
	v_rcp_f32_e32 v157, v2
	v_lshlrev_b32_e32 v2, 16, v137
	v_max_f32_e32 v2, v2, v2
	v_med3_f32 v2, v2, s20, v199
	v_mul_f32_e32 v2, 0xbfb8aa3b, v2
	v_exp_f32_e32 v2, v2
	v_and_b32_e32 v137, 0xffff0000, v159
	v_max_f32_e32 v137, v137, v137
	v_med3_f32 v137, v137, s20, v199
	v_add_f32_e32 v2, 1.0, v2
	v_med3_f32 v5, v5, s20, v199
	v_rcp_f32_e32 v158, v2
	v_mul_f32_e32 v2, 0xbfb8aa3b, v137
	v_exp_f32_e32 v137, v2
	v_mul_f32_e32 v2, 0xbfb8aa3b, v5
	v_lshlrev_b32_e32 v136, 16, v159
	v_exp_f32_e32 v2, v2
	v_max_f32_e32 v134, v134, v134
	v_max_f32_e32 v136, v136, v136
	v_med3_f32 v134, v134, s20, v199
	v_med3_f32 v136, v136, s20, v199
	v_mul_f32_e32 v134, 0xbfb8aa3b, v134
	v_mul_f32_e32 v136, 0xbfb8aa3b, v136
	v_exp_f32_e32 v134, v134
	v_exp_f32_e32 v136, v136
	v_add_f32_e32 v2, 1.0, v2
	v_rcp_f32_e32 v159, v2
	v_pk_add_f32 v[134:135], v[134:135], 1.0 op_sel_hi:[1,0]
	v_pk_add_f32 v[136:137], v[136:137], 1.0 op_sel_hi:[1,0]
	v_pk_mul_f32 v[134:135], v[134:135], v[156:157]
	v_pk_mul_f32 v[136:137], v[136:137], v[158:159]
	v_pk_mul_f32 v[62:63], v[62:63], v[134:135]
	v_pk_mul_f32 v[64:65], v[64:65], v[136:137]
	s_nop 0
	v_pk_add_f32 v[164:165], v[164:165], 1.0 op_sel_hi:[1,0]
	s_waitcnt vmcnt(9)
;     __device__ __forceinline__ void operator()(f32x4 (&acc)[2][2][4][2], const Unit& u, int wr, int wc, int fr, int fq) const {
;     ...
;             for (int st = 0; st < 16; ++st) { const int ai = st >> 3, m = (st >> 1) & 3, bj = st & 1;
;                 const size_t r = (size_t)(row0 + ai * HALF + m * 16); const int c = col0 + bj * HALF;
;                 const u32x4 ga = *(const u32x4*)(za + r * ldz + c), gb = *(const u32x4*)(zb + r * ldz + c);
; #pragma unroll
;                 for (int j = 0; j < 4; ++j) { const unsigned wa = ga[j], wb = gb[j];
;                     const float a0 = fminf(fmaxf(__uint_as_float(wa << 16), -30.f), 30.f), a1 = fminf(fmaxf(__uint_as_float(wa & 0xffff0000u), -30.f), 30.f);
;                     const float b0 = fminf(fmaxf(__uint_as_float(wb << 16), -30.f), 30.f), b1 = fminf(fmaxf(__uint_as_float(wb & 0xffff0000u), -30.f), 30.f);
;                     const float r0 = (1.f + __expf(-b0)) * __builtin_amdgcn_rcpf(1.f + __expf(-a0)), r1 = (1.f + __expf(-b1)) * __builtin_amdgcn_rcpf(1.f + __expf(-a1));
;                     acc[ai][bj][m][j >> 1][(j & 1) * 2] *= r0; acc[ai][bj][m][j >> 1][(j & 1) * 2 + 1] *= r1; }
;                 if ((st & 3) == 3) asm volatile("" ::: "memory"); }
	v_mov_b64_e32 v[134:135], v[204:205]
	v_mov_b64_e32 v[136:137], v[206:207]
	v_add_u32_e32 v213, 0xb0, v4
	v_mad_i64_i32 v[246:247], s[26:27], v213, s25, v[162:163]
	v_lshl_add_u64 v[246:247], v[246:247], 0, v[154:155]
	global_load_dwordx4 v[204:207], v[246:247], off
	s_waitcnt vmcnt(9)
	v_mov_b64_e32 v[138:139], v[208:209]
	v_mov_b64_e32 v[140:141], v[210:211]
	v_add_u32_e32 v213, 0xb0, v4
	v_mad_i64_i32 v[248:249], s[26:27], v213, s25, v[160:161]
	v_lshl_add_u64 v[248:249], v[248:249], 0, v[154:155]
	global_load_dwordx4 v[208:211], v[248:249], off
	v_lshlrev_b32_e32 v2, 16, v138
	v_max_f32_e32 v2, v2, v2
	v_med3_f32 v2, v2, s20, v199
	v_mul_f32_e32 v2, 0xbfb8aa3b, v2
	v_exp_f32_e32 v2, v2
	v_and_b32_e32 v5, 0xffff0000, v138
	v_lshlrev_b32_e32 v138, 16, v134
	v_and_b32_e32 v134, 0xffff0000, v134
	v_max_f32_e32 v134, v134, v134
	v_max_f32_e32 v5, v5, v5
	v_med3_f32 v134, v134, s20, v199
	v_add_f32_e32 v2, 1.0, v2
	v_med3_f32 v5, v5, s20, v199
	v_rcp_f32_e32 v158, v2
	v_mul_f32_e32 v2, 0xbfb8aa3b, v134
	v_exp_f32_e32 v157, v2
	v_mul_f32_e32 v2, 0xbfb8aa3b, v5
	v_exp_f32_e32 v2, v2
	v_max_f32_e32 v138, v138, v138
	v_lshlrev_b32_e32 v134, 16, v135
	v_and_b32_e32 v135, 0xffff0000, v135
	v_add_f32_e32 v2, 1.0, v2
	v_rcp_f32_e32 v159, v2
	v_lshlrev_b32_e32 v2, 16, v139
	v_max_f32_e32 v2, v2, v2
	v_med3_f32 v2, v2, s20, v199
	v_mul_f32_e32 v2, 0xbfb8aa3b, v2
	v_exp_f32_e32 v2, v2
	v_med3_f32 v138, v138, s20, v199
	v_and_b32_e32 v5, 0xffff0000, v139
	v_max_f32_e32 v135, v135, v135
	v_mul_f32_e32 v138, 0xbfb8aa3b, v138
	v_max_f32_e32 v5, v5, v5
	v_med3_f32 v135, v135, s20, v199
	v_add_f32_e32 v2, 1.0, v2
	v_exp_f32_e32 v156, v138
	v_med3_f32 v5, v5, s20, v199
	v_rcp_f32_e32 v138, v2
	v_mul_f32_e32 v2, 0xbfb8aa3b, v135
	v_exp_f32_e32 v135, v2
	v_mul_f32_e32 v2, 0xbfb8aa3b, v5
	v_exp_f32_e32 v2, v2
	v_max_f32_e32 v134, v134, v134
	v_med3_f32 v134, v134, s20, v199
	v_mul_f32_e32 v134, 0xbfb8aa3b, v134
	v_add_f32_e32 v2, 1.0, v2
	v_exp_f32_e32 v134, v134
	v_rcp_f32_e32 v139, v2
	v_lshlrev_b32_e32 v2, 16, v140
	v_max_f32_e32 v2, v2, v2
	v_med3_f32 v2, v2, s20, v199
	v_mul_f32_e32 v2, 0xbfb8aa3b, v2
	v_pk_add_f32 v[134:135], v[134:135], 1.0 op_sel_hi:[1,0]
	v_exp_f32_e32 v2, v2
	v_pk_mul_f32 v[134:135], v[134:135], v[138:139]
	v_and_b32_e32 v5, 0xffff0000, v140
	v_pk_mul_f32 v[36:37], v[36:37], v[134:135]
	v_and_b32_e32 v135, 0xffff0000, v136
	v_max_f32_e32 v135, v135, v135
	v_max_f32_e32 v5, v5, v5
	v_med3_f32 v135, v135, s20, v199
	v_add_f32_e32 v2, 1.0, v2
	v_med3_f32 v5, v5, s20, v199
	v_rcp_f32_e32 v138, v2
	v_mul_f32_e32 v2, 0xbfb8aa3b, v135
	v_exp_f32_e32 v135, v2
	v_mul_f32_e32 v2, 0xbfb8aa3b, v5
	v_exp_f32_e32 v2, v2
	v_lshlrev_b32_e32 v134, 16, v136
	v_lshlrev_b32_e32 v136, 16, v137
	v_and_b32_e32 v137, 0xffff0000, v137
	v_add_f32_e32 v2, 1.0, v2
	v_rcp_f32_e32 v139, v2
	v_lshlrev_b32_e32 v2, 16, v141
	v_max_f32_e32 v2, v2, v2
	v_med3_f32 v2, v2, s20, v199
	v_mul_f32_e32 v2, 0xbfb8aa3b, v2
	v_exp_f32_e32 v2, v2
	v_and_b32_e32 v5, 0xffff0000, v141
	v_max_f32_e32 v137, v137, v137
	v_max_f32_e32 v5, v5, v5
	v_med3_f32 v137, v137, s20, v199
	v_add_f32_e32 v2, 1.0, v2
	v_med3_f32 v5, v5, s20, v199
	v_rcp_f32_e32 v140, v2
	v_mul_f32_e32 v2, 0xbfb8aa3b, v137
	v_max_f32_e32 v134, v134, v134
	v_exp_f32_e32 v137, v2
	v_mul_f32_e32 v2, 0xbfb8aa3b, v5
	v_med3_f32 v134, v134, s20, v199
	v_exp_f32_e32 v2, v2
	v_mul_f32_e32 v134, 0xbfb8aa3b, v134
	v_max_f32_e32 v136, v136, v136
	v_exp_f32_e32 v134, v134
	v_med3_f32 v136, v136, s20, v199
	v_mul_f32_e32 v136, 0xbfb8aa3b, v136
	v_exp_f32_e32 v136, v136
	v_add_f32_e32 v2, 1.0, v2
	v_rcp_f32_e32 v141, v2
	v_pk_add_f32 v[134:135], v[134:135], 1.0 op_sel_hi:[1,0]
	v_add_u32_e32 v2, 0x90, v4
	v_pk_mul_f32 v[134:135], v[134:135], v[138:139]
	v_pk_add_f32 v[136:137], v[136:137], 1.0 op_sel_hi:[1,0]
	v_pk_mul_f32 v[30:31], v[30:31], v[134:135]
	v_mad_i64_i32 v[134:135], s[26:27], v2, s25, v[162:163]
	v_pk_mul_f32 v[136:137], v[136:137], v[140:141]
	v_lshl_add_u64 v[138:139], v[134:135], 0, v[154:155]
	v_pk_mul_f32 v[32:33], v[32:33], v[136:137]
	v_pk_add_f32 v[156:157], v[156:157], 1.0 op_sel_hi:[1,0]
	v_mad_i64_i32 v[140:141], s[26:27], v2, s25, v[160:161]
	v_pk_mul_f32 v[156:157], v[156:157], v[158:159]
	v_lshl_add_u64 v[140:141], v[140:141], 0, v[154:155]
	v_pk_mul_f32 v[34:35], v[34:35], v[156:157]
	v_pk_mul_f32 v[164:165], v[164:165], v[170:171]
	s_waitcnt vmcnt(9)
	v_mov_b64_e32 v[134:135], v[214:215]
	v_mov_b64_e32 v[136:137], v[216:217]
	v_add_u32_e32 v213, 0xb0, v4
	v_mad_i64_i32 v[246:247], s[26:27], v213, s25, v[160:161]
	v_lshl_add_u64 v[246:247], v[246:247], 0, v[154:155]
	global_load_dwordx4 v[214:217], v[246:247], off offset:256
	v_lshlrev_b32_e32 v2, 16, v134
	v_max_f32_e32 v2, v2, v2
	v_med3_f32 v2, v2, s20, v199
	v_mul_f32_e32 v2, 0xbfb8aa3b, v2
	v_exp_f32_e32 v2, v2
	v_and_b32_e32 v5, 0xffff0000, v134
	v_max_f32_e32 v5, v5, v5
	s_waitcnt vmcnt(9)
;     __device__ __forceinline__ void operator()(f32x4 (&acc)[2][2][4][2], const Unit& u, int wr, int wc, int fr, int fq) const {
;     ...
;             for (int st = 0; st < 16; ++st) { const int ai = st >> 3, m = (st >> 1) & 3, bj = st & 1;
;                 const size_t r = (size_t)(row0 + ai * HALF + m * 16); const int c = col0 + bj * HALF;
;                 const u32x4 ga = *(const u32x4*)(za + r * ldz + c), gb = *(const u32x4*)(zb + r * ldz + c);
; #pragma unroll
;                 for (int j = 0; j < 4; ++j) { const unsigned wa = ga[j], wb = gb[j];
;                     const float a0 = fminf(fmaxf(__uint_as_float(wa << 16), -30.f), 30.f), a1 = fminf(fmaxf(__uint_as_float(wa & 0xffff0000u), -30.f), 30.f);
;                     const float b0 = fminf(fmaxf(__uint_as_float(wb << 16), -30.f), 30.f), b1 = fminf(fmaxf(__uint_as_float(wb & 0xffff0000u), -30.f), 30.f);
;                     const float r0 = (1.f + __expf(-b0)) * __builtin_amdgcn_rcpf(1.f + __expf(-a0)), r1 = (1.f + __expf(-b1)) * __builtin_amdgcn_rcpf(1.f + __expf(-a1));
;                     acc[ai][bj][m][j >> 1][(j & 1) * 2] *= r0; acc[ai][bj][m][j >> 1][(j & 1) * 2 + 1] *= r1; }
;                 if ((st & 3) == 3) asm volatile("" ::: "memory"); }
	v_mov_b64_e32 v[156:157], v[218:219]
	v_mov_b64_e32 v[158:159], v[220:221]
	v_add_u32_e32 v213, 0xb0, v4
	v_mad_i64_i32 v[248:249], s[26:27], v213, s25, v[162:163]
	v_lshl_add_u64 v[248:249], v[248:249], 0, v[154:155]
	global_load_dwordx4 v[218:221], v[248:249], off offset:256
	v_lshlrev_b32_e32 v134, 16, v156
	v_and_b32_e32 v156, 0xffff0000, v156
	v_max_f32_e32 v156, v156, v156
	v_med3_f32 v156, v156, s20, v199
	v_add_f32_e32 v2, 1.0, v2
	v_med3_f32 v5, v5, s20, v199
	v_rcp_f32_e32 v170, v2
	v_mul_f32_e32 v2, 0xbfb8aa3b, v156
	v_pk_mul_f32 v[66:67], v[66:67], v[164:165]
	v_exp_f32_e32 v165, v2
	v_mul_f32_e32 v2, 0xbfb8aa3b, v5
	v_exp_f32_e32 v2, v2
	v_and_b32_e32 v5, 0xffff0000, v135
	v_max_f32_e32 v5, v5, v5
	v_max_f32_e32 v134, v134, v134
	v_add_f32_e32 v2, 1.0, v2
	v_rcp_f32_e32 v171, v2
	v_lshlrev_b32_e32 v2, 16, v135
	v_max_f32_e32 v2, v2, v2
	v_med3_f32 v2, v2, s20, v199
	v_mul_f32_e32 v2, 0xbfb8aa3b, v2
	v_exp_f32_e32 v2, v2
	v_and_b32_e32 v135, 0xffff0000, v157
	v_max_f32_e32 v135, v135, v135
	v_med3_f32 v135, v135, s20, v199
	v_add_f32_e32 v2, 1.0, v2
	v_med3_f32 v5, v5, s20, v199
	v_rcp_f32_e32 v156, v2
	v_mul_f32_e32 v2, 0xbfb8aa3b, v135
	v_med3_f32 v134, v134, s20, v199
	v_exp_f32_e32 v135, v2
	v_mul_f32_e32 v2, 0xbfb8aa3b, v5
	v_mul_f32_e32 v134, 0xbfb8aa3b, v134
	v_exp_f32_e32 v2, v2
	v_exp_f32_e32 v164, v134
	v_lshlrev_b32_e32 v134, 16, v157
	v_max_f32_e32 v134, v134, v134
	v_med3_f32 v134, v134, s20, v199
	v_mul_f32_e32 v134, 0xbfb8aa3b, v134
	v_add_f32_e32 v2, 1.0, v2
	v_exp_f32_e32 v134, v134
	v_rcp_f32_e32 v157, v2
	v_lshlrev_b32_e32 v2, 16, v136
	v_max_f32_e32 v2, v2, v2
	v_med3_f32 v2, v2, s20, v199
	v_mul_f32_e32 v2, 0xbfb8aa3b, v2
	v_pk_add_f32 v[134:135], v[134:135], 1.0 op_sel_hi:[1,0]
	v_exp_f32_e32 v2, v2
	v_pk_mul_f32 v[134:135], v[134:135], v[156:157]
	v_and_b32_e32 v5, 0xffff0000, v136
	v_pk_mul_f32 v[60:61], v[60:61], v[134:135]
	v_and_b32_e32 v135, 0xffff0000, v158
	v_max_f32_e32 v135, v135, v135
	v_max_f32_e32 v5, v5, v5
	v_med3_f32 v135, v135, s20, v199
	v_add_f32_e32 v2, 1.0, v2
	v_med3_f32 v5, v5, s20, v199
	v_rcp_f32_e32 v156, v2
	v_mul_f32_e32 v2, 0xbfb8aa3b, v135
	v_exp_f32_e32 v135, v2
	v_mul_f32_e32 v2, 0xbfb8aa3b, v5
	v_exp_f32_e32 v2, v2
	v_and_b32_e32 v5, 0xffff0000, v137
	v_max_f32_e32 v5, v5, v5
	v_lshlrev_b32_e32 v134, 16, v158
	v_add_f32_e32 v2, 1.0, v2
	v_rcp_f32_e32 v157, v2
	v_lshlrev_b32_e32 v2, 16, v137
	v_max_f32_e32 v2, v2, v2
	v_med3_f32 v2, v2, s20, v199
	v_mul_f32_e32 v2, 0xbfb8aa3b, v2
	v_exp_f32_e32 v2, v2
	v_and_b32_e32 v137, 0xffff0000, v159
	v_max_f32_e32 v137, v137, v137
	v_med3_f32 v137, v137, s20, v199
	v_add_f32_e32 v2, 1.0, v2
	v_med3_f32 v5, v5, s20, v199
	v_rcp_f32_e32 v158, v2
	v_mul_f32_e32 v2, 0xbfb8aa3b, v137
	v_exp_f32_e32 v137, v2
	v_mul_f32_e32 v2, 0xbfb8aa3b, v5
	v_lshlrev_b32_e32 v136, 16, v159
	v_exp_f32_e32 v2, v2
	v_max_f32_e32 v134, v134, v134
	v_max_f32_e32 v136, v136, v136
	v_med3_f32 v134, v134, s20, v199
	v_med3_f32 v136, v136, s20, v199
	v_mul_f32_e32 v134, 0xbfb8aa3b, v134
	v_mul_f32_e32 v136, 0xbfb8aa3b, v136
	v_exp_f32_e32 v134, v134
	v_exp_f32_e32 v136, v136
	v_add_f32_e32 v2, 1.0, v2
	v_rcp_f32_e32 v159, v2
	v_pk_add_f32 v[134:135], v[134:135], 1.0 op_sel_hi:[1,0]
	v_pk_add_f32 v[136:137], v[136:137], 1.0 op_sel_hi:[1,0]
	v_pk_mul_f32 v[134:135], v[134:135], v[156:157]
	v_pk_mul_f32 v[136:137], v[136:137], v[158:159]
	v_pk_mul_f32 v[54:55], v[54:55], v[134:135]
	v_pk_mul_f32 v[56:57], v[56:57], v[136:137]
	s_nop 0
	v_pk_add_f32 v[164:165], v[164:165], 1.0 op_sel_hi:[1,0]
	s_waitcnt vmcnt(9)
	v_mov_b64_e32 v[134:135], v[222:223]
	v_mov_b64_e32 v[136:137], v[224:225]
	s_waitcnt vmcnt(8)
	v_mov_b64_e32 v[138:139], v[226:227]
	v_mov_b64_e32 v[140:141], v[228:229]
	v_lshlrev_b32_e32 v2, 16, v138
	v_max_f32_e32 v2, v2, v2
	v_med3_f32 v2, v2, s20, v199
	v_mul_f32_e32 v2, 0xbfb8aa3b, v2
	v_exp_f32_e32 v2, v2
	v_and_b32_e32 v5, 0xffff0000, v138
	v_lshlrev_b32_e32 v138, 16, v134
	v_and_b32_e32 v134, 0xffff0000, v134
	v_max_f32_e32 v134, v134, v134
	v_max_f32_e32 v5, v5, v5
	v_med3_f32 v134, v134, s20, v199
	v_add_f32_e32 v2, 1.0, v2
	v_med3_f32 v5, v5, s20, v199
	v_rcp_f32_e32 v158, v2
	v_mul_f32_e32 v2, 0xbfb8aa3b, v134
	v_exp_f32_e32 v157, v2
	v_mul_f32_e32 v2, 0xbfb8aa3b, v5
	v_exp_f32_e32 v2, v2
	v_max_f32_e32 v138, v138, v138
	v_lshlrev_b32_e32 v134, 16, v135
	v_and_b32_e32 v135, 0xffff0000, v135
	v_add_f32_e32 v2, 1.0, v2
	v_rcp_f32_e32 v159, v2
	v_lshlrev_b32_e32 v2, 16, v139
	v_max_f32_e32 v2, v2, v2
	v_med3_f32 v2, v2, s20, v199
	v_mul_f32_e32 v2, 0xbfb8aa3b, v2
	v_exp_f32_e32 v2, v2
	v_med3_f32 v138, v138, s20, v199
	v_and_b32_e32 v5, 0xffff0000, v139
	v_max_f32_e32 v135, v135, v135
	v_mul_f32_e32 v138, 0xbfb8aa3b, v138
	v_max_f32_e32 v5, v5, v5
	v_med3_f32 v135, v135, s20, v199
	v_add_f32_e32 v2, 1.0, v2
	v_exp_f32_e32 v156, v138
	v_med3_f32 v5, v5, s20, v199
	v_rcp_f32_e32 v138, v2
	v_mul_f32_e32 v2, 0xbfb8aa3b, v135
	v_exp_f32_e32 v135, v2
	v_mul_f32_e32 v2, 0xbfb8aa3b, v5
	v_exp_f32_e32 v2, v2
	v_max_f32_e32 v134, v134, v134
	v_med3_f32 v134, v134, s20, v199
	v_mul_f32_e32 v134, 0xbfb8aa3b, v134
	v_add_f32_e32 v2, 1.0, v2
	v_exp_f32_e32 v134, v134
	v_rcp_f32_e32 v139, v2
	v_lshlrev_b32_e32 v2, 16, v140
	v_max_f32_e32 v2, v2, v2
	v_med3_f32 v2, v2, s20, v199
	v_mul_f32_e32 v2, 0xbfb8aa3b, v2
	v_pk_add_f32 v[134:135], v[134:135], 1.0 op_sel_hi:[1,0]
	v_exp_f32_e32 v2, v2
	v_pk_mul_f32 v[134:135], v[134:135], v[138:139]
	v_and_b32_e32 v5, 0xffff0000, v140
	v_pk_mul_f32 v[28:29], v[28:29], v[134:135]
	v_and_b32_e32 v135, 0xffff0000, v136
	v_max_f32_e32 v135, v135, v135
	v_max_f32_e32 v5, v5, v5
	v_med3_f32 v135, v135, s20, v199
;     __device__ __forceinline__ void operator()(f32x4 (&acc)[2][2][4][2], const Unit& u, int wr, int wc, int fr, int fq) const {
;     ...
;             for (int st = 0; st < 16; ++st) { const int ai = st >> 3, m = (st >> 1) & 3, bj = st & 1;
;                 const size_t r = (size_t)(row0 + ai * HALF + m * 16); const int c = col0 + bj * HALF;
;                 const u32x4 ga = *(const u32x4*)(za + r * ldz + c), gb = *(const u32x4*)(zb + r * ldz + c);
; #pragma unroll
;                 for (int j = 0; j < 4; ++j) { const unsigned wa = ga[j], wb = gb[j];
;                     const float a0 = fminf(fmaxf(__uint_as_float(wa << 16), -30.f), 30.f), a1 = fminf(fmaxf(__uint_as_float(wa & 0xffff0000u), -30.f), 30.f);
;                     const float b0 = fminf(fmaxf(__uint_as_float(wb << 16), -30.f), 30.f), b1 = fminf(fmaxf(__uint_as_float(wb & 0xffff0000u), -30.f), 30.f);
;                     const float r0 = (1.f + __expf(-b0)) * __builtin_amdgcn_rcpf(1.f + __expf(-a0)), r1 = (1.f + __expf(-b1)) * __builtin_amdgcn_rcpf(1.f + __expf(-a1));
;                     acc[ai][bj][m][j >> 1][(j & 1) * 2] *= r0; acc[ai][bj][m][j >> 1][(j & 1) * 2 + 1] *= r1; }
;                 if ((st & 3) == 3) asm volatile("" ::: "memory"); }
	v_add_f32_e32 v2, 1.0, v2
	v_med3_f32 v5, v5, s20, v199
	v_rcp_f32_e32 v138, v2
	v_mul_f32_e32 v2, 0xbfb8aa3b, v135
	v_exp_f32_e32 v135, v2
	v_mul_f32_e32 v2, 0xbfb8aa3b, v5
	v_exp_f32_e32 v2, v2
	v_lshlrev_b32_e32 v134, 16, v136
	v_lshlrev_b32_e32 v136, 16, v137
	v_and_b32_e32 v137, 0xffff0000, v137
	v_add_f32_e32 v2, 1.0, v2
	v_rcp_f32_e32 v139, v2
	v_lshlrev_b32_e32 v2, 16, v141
	v_max_f32_e32 v2, v2, v2
	v_med3_f32 v2, v2, s20, v199
	v_mul_f32_e32 v2, 0xbfb8aa3b, v2
	v_exp_f32_e32 v2, v2
	v_and_b32_e32 v5, 0xffff0000, v141
	v_max_f32_e32 v137, v137, v137
	v_max_f32_e32 v5, v5, v5
	v_med3_f32 v137, v137, s20, v199
	v_add_f32_e32 v2, 1.0, v2
	v_med3_f32 v5, v5, s20, v199
	v_rcp_f32_e32 v140, v2
	v_mul_f32_e32 v2, 0xbfb8aa3b, v137
	v_max_f32_e32 v134, v134, v134
	v_exp_f32_e32 v137, v2
	v_mul_f32_e32 v2, 0xbfb8aa3b, v5
	v_med3_f32 v134, v134, s20, v199
	v_exp_f32_e32 v2, v2
	v_mul_f32_e32 v134, 0xbfb8aa3b, v134
	v_max_f32_e32 v136, v136, v136
	v_exp_f32_e32 v134, v134
	v_med3_f32 v136, v136, s20, v199
	v_mul_f32_e32 v136, 0xbfb8aa3b, v136
	v_exp_f32_e32 v136, v136
	v_add_f32_e32 v2, 1.0, v2
	v_rcp_f32_e32 v141, v2
	v_pk_add_f32 v[134:135], v[134:135], 1.0 op_sel_hi:[1,0]
	v_add_u32_e32 v2, 0xa0, v4
	v_pk_mul_f32 v[134:135], v[134:135], v[138:139]
	v_pk_add_f32 v[136:137], v[136:137], 1.0 op_sel_hi:[1,0]
	v_pk_mul_f32 v[22:23], v[22:23], v[134:135]
	v_mad_i64_i32 v[134:135], s[26:27], v2, s25, v[162:163]
	v_pk_mul_f32 v[136:137], v[136:137], v[140:141]
	v_lshl_add_u64 v[138:139], v[134:135], 0, v[154:155]
	v_pk_mul_f32 v[24:25], v[24:25], v[136:137]
	v_pk_add_f32 v[156:157], v[156:157], 1.0 op_sel_hi:[1,0]
	v_mad_i64_i32 v[140:141], s[26:27], v2, s25, v[160:161]
	v_pk_mul_f32 v[156:157], v[156:157], v[158:159]
	v_lshl_add_u64 v[140:141], v[140:141], 0, v[154:155]
	v_pk_mul_f32 v[26:27], v[26:27], v[156:157]
	v_pk_mul_f32 v[164:165], v[164:165], v[170:171]
	s_waitcnt vmcnt(7)
	v_mov_b64_e32 v[134:135], v[230:231]
	v_mov_b64_e32 v[136:137], v[232:233]
	v_lshlrev_b32_e32 v2, 16, v134
	v_max_f32_e32 v2, v2, v2
	v_med3_f32 v2, v2, s20, v199
	v_mul_f32_e32 v2, 0xbfb8aa3b, v2
	v_exp_f32_e32 v2, v2
	v_and_b32_e32 v5, 0xffff0000, v134
	v_max_f32_e32 v5, v5, v5
	s_waitcnt vmcnt(6)
	v_mov_b64_e32 v[156:157], v[234:235]
	v_mov_b64_e32 v[158:159], v[236:237]
	v_lshlrev_b32_e32 v134, 16, v156
	v_and_b32_e32 v156, 0xffff0000, v156
	v_max_f32_e32 v156, v156, v156
	v_med3_f32 v156, v156, s20, v199
	v_add_f32_e32 v2, 1.0, v2
	v_med3_f32 v5, v5, s20, v199
	v_rcp_f32_e32 v170, v2
	v_mul_f32_e32 v2, 0xbfb8aa3b, v156
	v_pk_mul_f32 v[58:59], v[58:59], v[164:165]
	v_exp_f32_e32 v165, v2
	v_mul_f32_e32 v2, 0xbfb8aa3b, v5
	v_exp_f32_e32 v2, v2
	v_and_b32_e32 v5, 0xffff0000, v135
	v_max_f32_e32 v5, v5, v5
	v_max_f32_e32 v134, v134, v134
	v_add_f32_e32 v2, 1.0, v2
	v_rcp_f32_e32 v171, v2
	v_lshlrev_b32_e32 v2, 16, v135
	v_max_f32_e32 v2, v2, v2
	v_med3_f32 v2, v2, s20, v199
	v_mul_f32_e32 v2, 0xbfb8aa3b, v2
	v_exp_f32_e32 v2, v2
	v_and_b32_e32 v135, 0xffff0000, v157
	v_max_f32_e32 v135, v135, v135
	v_med3_f32 v135, v135, s20, v199
	v_add_f32_e32 v2, 1.0, v2
	v_med3_f32 v5, v5, s20, v199
	v_rcp_f32_e32 v156, v2
	v_mul_f32_e32 v2, 0xbfb8aa3b, v135
	v_med3_f32 v134, v134, s20, v199
	v_exp_f32_e32 v135, v2
	v_mul_f32_e32 v2, 0xbfb8aa3b, v5
	v_mul_f32_e32 v134, 0xbfb8aa3b, v134
	v_exp_f32_e32 v2, v2
	v_exp_f32_e32 v164, v134
	v_lshlrev_b32_e32 v134, 16, v157
	v_max_f32_e32 v134, v134, v134
	v_med3_f32 v134, v134, s20, v199
	v_mul_f32_e32 v134, 0xbfb8aa3b, v134
	v_add_f32_e32 v2, 1.0, v2
	v_exp_f32_e32 v134, v134
	v_rcp_f32_e32 v157, v2
	v_lshlrev_b32_e32 v2, 16, v136
	v_max_f32_e32 v2, v2, v2
	v_med3_f32 v2, v2, s20, v199
	v_mul_f32_e32 v2, 0xbfb8aa3b, v2
	v_pk_add_f32 v[134:135], v[134:135], 1.0 op_sel_hi:[1,0]
	v_exp_f32_e32 v2, v2
	v_pk_mul_f32 v[134:135], v[134:135], v[156:157]
	v_and_b32_e32 v5, 0xffff0000, v136
	v_pk_mul_f32 v[52:53], v[52:53], v[134:135]
	v_and_b32_e32 v135, 0xffff0000, v158
	v_max_f32_e32 v135, v135, v135
	v_max_f32_e32 v5, v5, v5
	v_med3_f32 v135, v135, s20, v199
	v_add_f32_e32 v2, 1.0, v2
	v_med3_f32 v5, v5, s20, v199
	v_rcp_f32_e32 v156, v2
	v_mul_f32_e32 v2, 0xbfb8aa3b, v135
	v_exp_f32_e32 v135, v2
	v_mul_f32_e32 v2, 0xbfb8aa3b, v5
	v_exp_f32_e32 v2, v2
	v_and_b32_e32 v5, 0xffff0000, v137
	v_max_f32_e32 v5, v5, v5
	v_lshlrev_b32_e32 v134, 16, v158
	v_add_f32_e32 v2, 1.0, v2
	v_rcp_f32_e32 v157, v2
	v_lshlrev_b32_e32 v2, 16, v137
	v_max_f32_e32 v2, v2, v2
	v_med3_f32 v2, v2, s20, v199
	v_mul_f32_e32 v2, 0xbfb8aa3b, v2
	v_exp_f32_e32 v2, v2
	v_and_b32_e32 v137, 0xffff0000, v159
	v_max_f32_e32 v137, v137, v137
	v_med3_f32 v137, v137, s20, v199
	v_add_f32_e32 v2, 1.0, v2
	v_med3_f32 v5, v5, s20, v199
	v_rcp_f32_e32 v158, v2
	v_mul_f32_e32 v2, 0xbfb8aa3b, v137
	v_exp_f32_e32 v137, v2
	v_mul_f32_e32 v2, 0xbfb8aa3b, v5
	v_lshlrev_b32_e32 v136, 16, v159
	v_exp_f32_e32 v2, v2
	v_max_f32_e32 v134, v134, v134
	v_max_f32_e32 v136, v136, v136
	v_med3_f32 v134, v134, s20, v199
	v_med3_f32 v136, v136, s20, v199
	v_mul_f32_e32 v134, 0xbfb8aa3b, v134
	v_mul_f32_e32 v136, 0xbfb8aa3b, v136
	v_exp_f32_e32 v134, v134
	v_exp_f32_e32 v136, v136
	v_add_f32_e32 v2, 1.0, v2
	v_rcp_f32_e32 v159, v2
	v_pk_add_f32 v[134:135], v[134:135], 1.0 op_sel_hi:[1,0]
	v_pk_add_f32 v[136:137], v[136:137], 1.0 op_sel_hi:[1,0]
	v_pk_mul_f32 v[134:135], v[134:135], v[156:157]
	v_pk_mul_f32 v[136:137], v[136:137], v[158:159]
	v_pk_mul_f32 v[46:47], v[46:47], v[134:135]
	v_pk_mul_f32 v[48:49], v[48:49], v[136:137]
	s_nop 0
	v_pk_add_f32 v[164:165], v[164:165], 1.0 op_sel_hi:[1,0]
	s_waitcnt vmcnt(5)
	v_mov_b64_e32 v[134:135], v[238:239]
	v_mov_b64_e32 v[136:137], v[240:241]
	s_waitcnt vmcnt(4)
;     __device__ __forceinline__ void operator()(f32x4 (&acc)[2][2][4][2], const Unit& u, int wr, int wc, int fr, int fq) const {
;     ...
;             for (int st = 0; st < 16; ++st) { const int ai = st >> 3, m = (st >> 1) & 3, bj = st & 1;
;                 const size_t r = (size_t)(row0 + ai * HALF + m * 16); const int c = col0 + bj * HALF;
;                 const u32x4 ga = *(const u32x4*)(za + r * ldz + c), gb = *(const u32x4*)(zb + r * ldz + c);
; #pragma unroll
;                 for (int j = 0; j < 4; ++j) { const unsigned wa = ga[j], wb = gb[j];
;                     const float a0 = fminf(fmaxf(__uint_as_float(wa << 16), -30.f), 30.f), a1 = fminf(fmaxf(__uint_as_float(wa & 0xffff0000u), -30.f), 30.f);
;                     const float b0 = fminf(fmaxf(__uint_as_float(wb << 16), -30.f), 30.f), b1 = fminf(fmaxf(__uint_as_float(wb & 0xffff0000u), -30.f), 30.f);
;                     const float r0 = (1.f + __expf(-b0)) * __builtin_amdgcn_rcpf(1.f + __expf(-a0)), r1 = (1.f + __expf(-b1)) * __builtin_amdgcn_rcpf(1.f + __expf(-a1));
;                     acc[ai][bj][m][j >> 1][(j & 1) * 2] *= r0; acc[ai][bj][m][j >> 1][(j & 1) * 2 + 1] *= r1; }
;                 if ((st & 3) == 3) asm volatile("" ::: "memory"); }
	v_mov_b64_e32 v[138:139], v[242:243]
	v_mov_b64_e32 v[140:141], v[244:245]
	v_lshlrev_b32_e32 v2, 16, v138
	v_max_f32_e32 v2, v2, v2
	v_med3_f32 v2, v2, s20, v199
	v_mul_f32_e32 v2, 0xbfb8aa3b, v2
	v_exp_f32_e32 v2, v2
	v_and_b32_e32 v5, 0xffff0000, v138
	v_lshlrev_b32_e32 v138, 16, v134
	v_and_b32_e32 v134, 0xffff0000, v134
	v_max_f32_e32 v134, v134, v134
	v_max_f32_e32 v5, v5, v5
	v_med3_f32 v134, v134, s20, v199
	v_add_f32_e32 v2, 1.0, v2
	v_med3_f32 v5, v5, s20, v199
	v_rcp_f32_e32 v158, v2
	v_mul_f32_e32 v2, 0xbfb8aa3b, v134
	v_exp_f32_e32 v157, v2
	v_mul_f32_e32 v2, 0xbfb8aa3b, v5
	v_exp_f32_e32 v2, v2
	v_max_f32_e32 v138, v138, v138
	v_lshlrev_b32_e32 v134, 16, v135
	v_and_b32_e32 v135, 0xffff0000, v135
	v_add_f32_e32 v2, 1.0, v2
	v_rcp_f32_e32 v159, v2
	v_lshlrev_b32_e32 v2, 16, v139
	v_max_f32_e32 v2, v2, v2
	v_med3_f32 v2, v2, s20, v199
	v_mul_f32_e32 v2, 0xbfb8aa3b, v2
	v_exp_f32_e32 v2, v2
	v_med3_f32 v138, v138, s20, v199
	v_and_b32_e32 v5, 0xffff0000, v139
	v_max_f32_e32 v135, v135, v135
	v_mul_f32_e32 v138, 0xbfb8aa3b, v138
	v_max_f32_e32 v5, v5, v5
	v_med3_f32 v135, v135, s20, v199
	v_add_f32_e32 v2, 1.0, v2
	v_exp_f32_e32 v156, v138
	v_med3_f32 v5, v5, s20, v199
	v_rcp_f32_e32 v138, v2
	v_mul_f32_e32 v2, 0xbfb8aa3b, v135
	v_exp_f32_e32 v135, v2
	v_mul_f32_e32 v2, 0xbfb8aa3b, v5
	v_exp_f32_e32 v2, v2
	v_max_f32_e32 v134, v134, v134
	v_med3_f32 v134, v134, s20, v199
	v_mul_f32_e32 v134, 0xbfb8aa3b, v134
	v_add_f32_e32 v2, 1.0, v2
	v_exp_f32_e32 v134, v134
	v_rcp_f32_e32 v139, v2
	v_lshlrev_b32_e32 v2, 16, v140
	v_max_f32_e32 v2, v2, v2
	v_med3_f32 v2, v2, s20, v199
	v_mul_f32_e32 v2, 0xbfb8aa3b, v2
	v_pk_add_f32 v[134:135], v[134:135], 1.0 op_sel_hi:[1,0]
	v_exp_f32_e32 v2, v2
	v_pk_mul_f32 v[134:135], v[134:135], v[138:139]
	v_and_b32_e32 v5, 0xffff0000, v140
	v_pk_mul_f32 v[20:21], v[20:21], v[134:135]
	v_and_b32_e32 v135, 0xffff0000, v136
	v_max_f32_e32 v135, v135, v135
	v_max_f32_e32 v5, v5, v5
	v_med3_f32 v135, v135, s20, v199
	v_add_f32_e32 v2, 1.0, v2
	v_med3_f32 v5, v5, s20, v199
	v_rcp_f32_e32 v138, v2
	v_mul_f32_e32 v2, 0xbfb8aa3b, v135
	v_exp_f32_e32 v135, v2
	v_mul_f32_e32 v2, 0xbfb8aa3b, v5
	v_exp_f32_e32 v2, v2
	v_lshlrev_b32_e32 v134, 16, v136
	v_lshlrev_b32_e32 v136, 16, v137
	v_and_b32_e32 v137, 0xffff0000, v137
	v_add_f32_e32 v2, 1.0, v2
	v_rcp_f32_e32 v139, v2
	v_lshlrev_b32_e32 v2, 16, v141
	v_max_f32_e32 v2, v2, v2
	v_med3_f32 v2, v2, s20, v199
	v_mul_f32_e32 v2, 0xbfb8aa3b, v2
	v_exp_f32_e32 v2, v2
	v_and_b32_e32 v5, 0xffff0000, v141
	v_max_f32_e32 v137, v137, v137
	v_max_f32_e32 v5, v5, v5
	v_med3_f32 v137, v137, s20, v199
	v_add_f32_e32 v2, 1.0, v2
	v_med3_f32 v5, v5, s20, v199
	v_rcp_f32_e32 v140, v2
	v_mul_f32_e32 v2, 0xbfb8aa3b, v137
	v_exp_f32_e32 v137, v2
	v_mul_f32_e32 v2, 0xbfb8aa3b, v5
	v_exp_f32_e32 v2, v2
	v_max_f32_e32 v134, v134, v134
	v_max_f32_e32 v136, v136, v136
	v_med3_f32 v134, v134, s20, v199
	v_med3_f32 v136, v136, s20, v199
	v_mul_f32_e32 v134, 0xbfb8aa3b, v134
	v_mul_f32_e32 v136, 0xbfb8aa3b, v136
	v_exp_f32_e32 v134, v134
	v_exp_f32_e32 v136, v136
	v_add_f32_e32 v2, 1.0, v2
	v_rcp_f32_e32 v141, v2
	v_add_u32_e32 v2, 0xb0, v4
	v_pk_add_f32 v[136:137], v[136:137], 1.0 op_sel_hi:[1,0]
	v_pk_add_f32 v[134:135], v[134:135], 1.0 op_sel_hi:[1,0]
	v_mad_i64_i32 v[4:5], s[26:27], v2, s25, v[162:163]
	v_pk_mul_f32 v[134:135], v[134:135], v[138:139]
	v_pk_mul_f32 v[136:137], v[136:137], v[140:141]
	v_lshl_add_u64 v[4:5], v[4:5], 0, v[154:155]
	v_pk_mul_f32 v[16:17], v[16:17], v[136:137]
	v_pk_mul_f32 v[14:15], v[14:15], v[134:135]
	v_mad_i64_i32 v[138:139], s[26:27], v2, s25, v[160:161]
	v_lshl_add_u64 v[154:155], v[138:139], 0, v[154:155]
	v_pk_add_f32 v[156:157], v[156:157], 1.0 op_sel_hi:[1,0]
	v_pk_mul_f32 v[164:165], v[164:165], v[170:171]
	v_pk_mul_f32 v[156:157], v[156:157], v[158:159]
	v_pk_mul_f32 v[50:51], v[50:51], v[164:165]
	v_pk_mul_f32 v[18:19], v[18:19], v[156:157]
	s_waitcnt vmcnt(3)
	v_mov_b64_e32 v[134:135], v[204:205]
	v_mov_b64_e32 v[136:137], v[206:207]
	v_lshlrev_b32_e32 v2, 16, v134
	v_max_f32_e32 v2, v2, v2
	v_med3_f32 v2, v2, s20, v199
	v_mul_f32_e32 v2, 0xbfb8aa3b, v2
	v_exp_f32_e32 v2, v2
	s_waitcnt vmcnt(2)
	v_mov_b64_e32 v[138:139], v[208:209]
	v_mov_b64_e32 v[140:141], v[210:211]
	v_lshlrev_b32_e32 v156, 16, v138
	v_and_b32_e32 v138, 0xffff0000, v138
	v_and_b32_e32 v134, 0xffff0000, v134
	v_max_f32_e32 v138, v138, v138
	v_max_f32_e32 v134, v134, v134
	v_med3_f32 v138, v138, s20, v199
	v_add_f32_e32 v2, 1.0, v2
	v_med3_f32 v134, v134, s20, v199
	v_rcp_f32_e32 v158, v2
	v_mul_f32_e32 v2, 0xbfb8aa3b, v138
	v_exp_f32_e32 v157, v2
	v_mul_f32_e32 v2, 0xbfb8aa3b, v134
	v_exp_f32_e32 v2, v2
	v_and_b32_e32 v134, 0xffff0000, v135
	v_max_f32_e32 v134, v134, v134
	v_med3_f32 v160, v134, s20, v199
	v_add_f32_e32 v2, 1.0, v2
	v_rcp_f32_e32 v159, v2
	v_lshlrev_b32_e32 v2, 16, v135
	v_max_f32_e32 v2, v2, v2
	v_med3_f32 v2, v2, s20, v199
	v_mul_f32_e32 v2, 0xbfb8aa3b, v2
	v_exp_f32_e32 v2, v2
	v_and_b32_e32 v135, 0xffff0000, v139
	v_max_f32_e32 v135, v135, v135
	v_med3_f32 v135, v135, s20, v199
	v_add_f32_e32 v2, 1.0, v2
	v_rcp_f32_e32 v138, v2
	v_mul_f32_e32 v2, 0xbfb8aa3b, v135
	v_exp_f32_e32 v135, v2
	v_mul_f32_e32 v2, 0xbfb8aa3b, v160
	v_exp_f32_e32 v2, v2
	v_lshlrev_b32_e32 v134, 16, v139
	v_max_f32_e32 v134, v134, v134
	v_med3_f32 v134, v134, s20, v199
	v_mul_f32_e32 v134, 0xbfb8aa3b, v134
	v_add_f32_e32 v2, 1.0, v2
	v_exp_f32_e32 v134, v134
	v_rcp_f32_e32 v139, v2
	v_lshlrev_b32_e32 v2, 16, v136
	v_max_f32_e32 v2, v2, v2
	v_med3_f32 v2, v2, s20, v199
	v_mul_f32_e32 v2, 0xbfb8aa3b, v2
	v_pk_add_f32 v[134:135], v[134:135], 1.0 op_sel_hi:[1,0]
	v_exp_f32_e32 v2, v2
;     __device__ __forceinline__ void operator()(f32x4 (&acc)[2][2][4][2], const Unit& u, int wr, int wc, int fr, int fq) const {
;     ...
;             for (int st = 0; st < 16; ++st) { const int ai = st >> 3, m = (st >> 1) & 3, bj = st & 1;
;                 const size_t r = (size_t)(row0 + ai * HALF + m * 16); const int c = col0 + bj * HALF;
;                 const u32x4 ga = *(const u32x4*)(za + r * ldz + c), gb = *(const u32x4*)(zb + r * ldz + c);
; #pragma unroll
;                 for (int j = 0; j < 4; ++j) { const unsigned wa = ga[j], wb = gb[j];
;                     const float a0 = fminf(fmaxf(__uint_as_float(wa << 16), -30.f), 30.f), a1 = fminf(fmaxf(__uint_as_float(wa & 0xffff0000u), -30.f), 30.f);
;                     const float b0 = fminf(fmaxf(__uint_as_float(wb << 16), -30.f), 30.f), b1 = fminf(fmaxf(__uint_as_float(wb & 0xffff0000u), -30.f), 30.f);
;                     const float r0 = (1.f + __expf(-b0)) * __builtin_amdgcn_rcpf(1.f + __expf(-a0)), r1 = (1.f + __expf(-b1)) * __builtin_amdgcn_rcpf(1.f + __expf(-a1));
;                     acc[ai][bj][m][j >> 1][(j & 1) * 2] *= r0; acc[ai][bj][m][j >> 1][(j & 1) * 2 + 1] *= r1; }
;                 if ((st & 3) == 3) asm volatile("" ::: "memory"); }
	v_pk_mul_f32 v[134:135], v[134:135], v[138:139]
	v_max_f32_e32 v156, v156, v156
	v_pk_mul_f32 v[44:45], v[44:45], v[134:135]
	v_and_b32_e32 v135, 0xffff0000, v140
	v_and_b32_e32 v134, 0xffff0000, v136
	v_max_f32_e32 v135, v135, v135
	v_max_f32_e32 v134, v134, v134
	v_med3_f32 v135, v135, s20, v199
	v_add_f32_e32 v2, 1.0, v2
	v_med3_f32 v136, v134, s20, v199
	v_rcp_f32_e32 v138, v2
	v_mul_f32_e32 v2, 0xbfb8aa3b, v135
	v_exp_f32_e32 v135, v2
	v_mul_f32_e32 v2, 0xbfb8aa3b, v136
	v_exp_f32_e32 v2, v2
	v_med3_f32 v156, v156, s20, v199
	v_mul_f32_e32 v156, 0xbfb8aa3b, v156
	v_exp_f32_e32 v156, v156
	v_add_f32_e32 v2, 1.0, v2
	v_rcp_f32_e32 v139, v2
	v_lshlrev_b32_e32 v2, 16, v137
	v_max_f32_e32 v2, v2, v2
	v_med3_f32 v2, v2, s20, v199
	v_mul_f32_e32 v2, 0xbfb8aa3b, v2
	v_exp_f32_e32 v2, v2
	v_and_b32_e32 v136, 0xffff0000, v137
	v_and_b32_e32 v137, 0xffff0000, v141
	v_pk_add_f32 v[156:157], v[156:157], 1.0 op_sel_hi:[1,0]
	v_max_f32_e32 v137, v137, v137
	v_pk_mul_f32 v[156:157], v[156:157], v[158:159]
	v_max_f32_e32 v136, v136, v136
	v_med3_f32 v137, v137, s20, v199
	v_add_f32_e32 v2, 1.0, v2
	v_pk_mul_f32 v[42:43], v[42:43], v[156:157]
	v_lshlrev_b32_e32 v134, 16, v140
	v_med3_f32 v156, v136, s20, v199
	v_rcp_f32_e32 v140, v2
	v_mul_f32_e32 v2, 0xbfb8aa3b, v137
	v_exp_f32_e32 v137, v2
	v_mul_f32_e32 v2, 0xbfb8aa3b, v156
	v_lshlrev_b32_e32 v136, 16, v141
	v_exp_f32_e32 v2, v2
	v_max_f32_e32 v134, v134, v134
	v_max_f32_e32 v136, v136, v136
	v_med3_f32 v134, v134, s20, v199
	v_med3_f32 v136, v136, s20, v199
	v_mul_f32_e32 v134, 0xbfb8aa3b, v134
	v_mul_f32_e32 v136, 0xbfb8aa3b, v136
	v_exp_f32_e32 v134, v134
	v_exp_f32_e32 v136, v136
	v_add_f32_e32 v2, 1.0, v2
	v_rcp_f32_e32 v141, v2
	v_pk_add_f32 v[134:135], v[134:135], 1.0 op_sel_hi:[1,0]
	v_pk_add_f32 v[136:137], v[136:137], 1.0 op_sel_hi:[1,0]
	v_pk_mul_f32 v[134:135], v[134:135], v[138:139]
	v_pk_mul_f32 v[136:137], v[136:137], v[140:141]
	v_pk_mul_f32 v[38:39], v[38:39], v[134:135]
	v_pk_mul_f32 v[40:41], v[40:41], v[136:137]
	s_waitcnt vmcnt(1)
	v_mov_b64_e32 v[134:135], v[214:215]
	v_mov_b64_e32 v[136:137], v[216:217]
	v_and_b32_e32 v5, 0xffff0000, v134
	s_waitcnt vmcnt(0)
	v_mov_b64_e32 v[138:139], v[218:219]
	v_mov_b64_e32 v[140:141], v[220:221]
	v_lshlrev_b32_e32 v2, 16, v138
	v_max_f32_e32 v2, v2, v2
	v_med3_f32 v2, v2, s20, v199
	v_mul_f32_e32 v2, 0xbfb8aa3b, v2
	v_exp_f32_e32 v2, v2
	v_and_b32_e32 v4, 0xffff0000, v138
	v_max_f32_e32 v5, v5, v5
	v_max_f32_e32 v4, v4, v4
	v_med3_f32 v5, v5, s20, v199
	v_add_f32_e32 v2, 1.0, v2
	v_med3_f32 v138, v4, s20, v199
	v_rcp_f32_e32 v154, v2
	v_mul_f32_e32 v2, 0xbfb8aa3b, v5
	v_exp_f32_e32 v5, v2
	v_mul_f32_e32 v2, 0xbfb8aa3b, v138
	v_exp_f32_e32 v2, v2
	v_lshlrev_b32_e32 v4, 16, v134
	v_and_b32_e32 v134, 0xffff0000, v139
	v_max_f32_e32 v134, v134, v134
	v_add_f32_e32 v2, 1.0, v2
	v_rcp_f32_e32 v155, v2
	v_lshlrev_b32_e32 v2, 16, v139
	v_max_f32_e32 v2, v2, v2
	v_med3_f32 v2, v2, s20, v199
	v_mul_f32_e32 v2, 0xbfb8aa3b, v2
	v_exp_f32_e32 v2, v2
	v_med3_f32 v139, v134, s20, v199
	v_lshlrev_b32_e32 v134, 16, v135
	v_and_b32_e32 v135, 0xffff0000, v135
	v_max_f32_e32 v135, v135, v135
	v_med3_f32 v135, v135, s20, v199
	v_add_f32_e32 v2, 1.0, v2
	v_rcp_f32_e32 v138, v2
	v_mul_f32_e32 v2, 0xbfb8aa3b, v135
	v_exp_f32_e32 v135, v2
	v_mul_f32_e32 v2, 0xbfb8aa3b, v139
	v_exp_f32_e32 v2, v2
	v_max_f32_e32 v4, v4, v4
	v_med3_f32 v4, v4, s20, v199
	v_mul_f32_e32 v4, 0xbfb8aa3b, v4
	v_add_f32_e32 v2, 1.0, v2
	v_exp_f32_e32 v4, v4
	v_max_f32_e32 v134, v134, v134
	v_rcp_f32_e32 v139, v2
	v_lshlrev_b32_e32 v2, 16, v140
	v_med3_f32 v134, v134, s20, v199
	v_max_f32_e32 v2, v2, v2
	v_mul_f32_e32 v134, 0xbfb8aa3b, v134
	v_med3_f32 v2, v2, s20, v199
	v_exp_f32_e32 v134, v134
	v_mul_f32_e32 v2, 0xbfb8aa3b, v2
	v_pk_add_f32 v[4:5], v[4:5], 1.0 op_sel_hi:[1,0]
	v_exp_f32_e32 v2, v2
	v_pk_mul_f32 v[4:5], v[4:5], v[154:155]
	v_pk_add_f32 v[134:135], v[134:135], 1.0 op_sel_hi:[1,0]
	v_pk_mul_f32 v[10:11], v[10:11], v[4:5]
	v_and_b32_e32 v5, 0xffff0000, v136
	v_and_b32_e32 v4, 0xffff0000, v140
	v_max_f32_e32 v5, v5, v5
	v_pk_mul_f32 v[134:135], v[134:135], v[138:139]
	v_max_f32_e32 v4, v4, v4
	v_med3_f32 v5, v5, s20, v199
	v_add_f32_e32 v2, 1.0, v2
	v_pk_mul_f32 v[12:13], v[12:13], v[134:135]
	v_med3_f32 v135, v4, s20, v199
	v_rcp_f32_e32 v134, v2
	v_mul_f32_e32 v2, 0xbfb8aa3b, v5
	v_exp_f32_e32 v5, v2
	v_mul_f32_e32 v2, 0xbfb8aa3b, v135
	v_exp_f32_e32 v2, v2
	v_lshlrev_b32_e32 v4, 16, v136
	v_and_b32_e32 v136, 0xffff0000, v141
	v_max_f32_e32 v136, v136, v136
	v_add_f32_e32 v2, 1.0, v2
	v_rcp_f32_e32 v135, v2
	v_lshlrev_b32_e32 v2, 16, v141
	v_max_f32_e32 v2, v2, v2
	v_med3_f32 v2, v2, s20, v199
	v_mul_f32_e32 v2, 0xbfb8aa3b, v2
	v_exp_f32_e32 v2, v2
	v_med3_f32 v139, v136, s20, v199
	v_lshlrev_b32_e32 v136, 16, v137
	v_and_b32_e32 v137, 0xffff0000, v137
	v_max_f32_e32 v137, v137, v137
	v_med3_f32 v137, v137, s20, v199
	v_add_f32_e32 v2, 1.0, v2
	v_rcp_f32_e32 v138, v2
	v_mul_f32_e32 v2, 0xbfb8aa3b, v137
	v_exp_f32_e32 v137, v2
	v_mul_f32_e32 v2, 0xbfb8aa3b, v139
	v_exp_f32_e32 v2, v2
	v_max_f32_e32 v4, v4, v4
	v_max_f32_e32 v136, v136, v136
	v_med3_f32 v4, v4, s20, v199
	v_med3_f32 v136, v136, s20, v199
	v_mul_f32_e32 v4, 0xbfb8aa3b, v4
	v_mul_f32_e32 v136, 0xbfb8aa3b, v136
	v_exp_f32_e32 v4, v4
	v_exp_f32_e32 v136, v136
	v_add_f32_e32 v2, 1.0, v2
	v_rcp_f32_e32 v139, v2
	v_pk_add_f32 v[4:5], v[4:5], 1.0 op_sel_hi:[1,0]
	v_pk_add_f32 v[136:137], v[136:137], 1.0 op_sel_hi:[1,0]
	v_pk_mul_f32 v[4:5], v[4:5], v[134:135]
	v_pk_mul_f32 v[134:135], v[136:137], v[138:139]
	v_pk_mul_f32 v[6:7], v[6:7], v[4:5]
	v_pk_mul_f32 v[8:9], v[8:9], v[134:135]
	s_and_b64 vcc, exec, s[38:39]
	s_mov_b64 s[36:37], -1
	s_cbranch_vccnz .LBB0_2086
